# speedup vs baseline: 1.0151x; 1.0151x over previous
.LBB0_184:
	s_bfe_u32 s0, s13, 0x100005
	s_mulk_i32 s0, 0x2493
	s_lshr_b32 s0, s0, 16
	s_and_b32 s0, s0, 0xffff
	s_mul_i32 s2, s0, 0xff20
	s_add_i32 s3, s2, s13
	s_sext_i32_i16 s2, s3
	s_mulk_i32 s2, 0x4925
	s_lshr_b32 s4, s2, 31
	s_ashr_i32 s2, s2, 17
	s_add_i32 s2, s2, s4
	s_mul_i32 s4, s2, 7
	s_lshl_b32 s2, s2, 10
	s_or_b32 s2, s2, s14
	v_or_b32_e32 v2, s2, v1
	v_ashrrev_i32_e32 v3, 31, v2
	v_lshlrev_b64 v[2:3], 11, v[2:3]
	s_sub_i32 s3, s3, s4
	s_mul_i32 s0, s0, 7
	v_lshl_add_u64 v[104:105], v[100:101], 0, v[2:3]
	s_sext_i32_i16 s3, s3
	s_add_i32 s0, s0, s3
	s_lshl_b32 s3, s0, 7
	v_or_b32_e32 v18, s3, v1
	v_ashrrev_i32_e32 v19, 31, v18
	v_lshlrev_b64 v[18:19], 11, v[18:19]
	v_lshl_add_u64 v[108:109], v[102:103], 0, v[18:19]
	s_mov_b32 s4, -2
	s_mov_b32 s5, s1
	v_mov_b32_e32 v26, 0
	v_mov_b32_e32 v27, v99
	v_mov_b32_e32 v28, v99
	v_mov_b32_e32 v29, v99
	v_mov_b32_e32 v46, 0
	v_mov_b32_e32 v47, v99
	v_mov_b32_e32 v48, v99
	v_mov_b32_e32 v49, v99
	v_mov_b32_e32 v62, 0
	v_mov_b32_e32 v63, v99
	v_mov_b32_e32 v64, v99
	v_mov_b32_e32 v65, v99
	v_mov_b32_e32 v78, 0
	v_mov_b32_e32 v79, v99
	v_mov_b32_e32 v80, v99
	v_mov_b32_e32 v81, v99
	v_mov_b32_e32 v82, 0
	v_mov_b32_e32 v83, v99
	v_mov_b32_e32 v84, v99
	v_mov_b32_e32 v85, v99
	v_mov_b32_e32 v86, 0
	v_mov_b32_e32 v87, v99
	v_mov_b32_e32 v88, v99
	v_mov_b32_e32 v89, v99
	v_mov_b32_e32 v90, 0
	v_mov_b32_e32 v91, v99
	v_mov_b32_e32 v92, v99
	v_mov_b32_e32 v93, v99
	v_mov_b32_e32 v94, 0
	v_mov_b32_e32 v95, v99
	v_mov_b32_e32 v96, v99
	v_mov_b32_e32 v97, v99
	v_mov_b32_e32 v38, 0
	v_mov_b32_e32 v39, v99
	v_mov_b32_e32 v40, v99
	v_mov_b32_e32 v41, v99
	v_mov_b32_e32 v30, 0
	v_mov_b32_e32 v31, v99
	v_mov_b32_e32 v32, v99
	v_mov_b32_e32 v33, v99
	v_mov_b32_e32 v22, 0
	v_mov_b32_e32 v23, v99
	v_mov_b32_e32 v24, v99
	v_mov_b32_e32 v25, v99
	v_mov_b32_e32 v18, 0
	v_mov_b32_e32 v19, v99
	v_mov_b32_e32 v20, v99
	v_mov_b32_e32 v21, v99
	v_mov_b32_e32 v14, 0
	v_mov_b32_e32 v15, v99
	v_mov_b32_e32 v16, v99
	v_mov_b32_e32 v17, v99
	v_mov_b32_e32 v10, 0
	v_mov_b32_e32 v11, v99
	v_mov_b32_e32 v12, v99
	v_mov_b32_e32 v13, v99
	v_mov_b32_e32 v6, 0
	v_mov_b32_e32 v7, v99
	v_mov_b32_e32 v8, v99
	v_mov_b32_e32 v9, v99
	v_mov_b32_e32 v2, 0
	v_mov_b32_e32 v3, v99
	v_mov_b32_e32 v4, v99
	v_mov_b32_e32 v5, v99
	v_and_b32_e32 v181, 7, v106
	v_bfe_u32 v180, v106, 3, 3
	v_xor_b32_e32 v180, v181, v180
	v_sub_u32_e32 v180, v180, v181
	v_lshlrev_b32_e32 v180, 4, v180
	v_ashrrev_i32_e32 v181, 31, v180
	v_lshrrev_b32_e32 v186, 6, v106
	v_mov_b32_e32 v187, 0x110
	v_lshl_add_u32 v186, v186, 10, v187
	v_lshl_add_u64 v[188:189], v[104:105], 0, v[180:181]
	v_lshl_add_u64 v[196:197], v[108:109], 0, v[180:181]
	v_readfirstlane_b32 s6, v186
	v_add_co_u32_e32 v190, vcc, s15, v188
	v_addc_co_u32_e32 v191, vcc, 0, v189, vcc
	v_add_co_u32_e32 v192, vcc, s16, v188
	v_addc_co_u32_e32 v193, vcc, 0, v189, vcc
	v_add_co_u32_e32 v194, vcc, s17, v188
	v_addc_co_u32_e32 v195, vcc, 0, v189, vcc
	v_add_co_u32_e32 v198, vcc, s15, v196
	v_addc_co_u32_e32 v199, vcc, 0, v197, vcc
	v_add_co_u32_e32 v200, vcc, s16, v196
	v_addc_co_u32_e32 v201, vcc, 0, v197, vcc
	v_add_co_u32_e32 v202, vcc, s17, v196
	v_addc_co_u32_e32 v203, vcc, 0, v197, vcc
	s_add_u32 m0, s6, 0x0
	s_nop 0
	global_load_lds_dwordx4 v[188:189], off
	s_add_u32 m0, s6, 0x1000
	s_nop 0
	global_load_lds_dwordx4 v[190:191], off
	s_add_u32 m0, s6, 0x2000
	s_nop 0
	global_load_lds_dwordx4 v[192:193], off
	s_add_u32 m0, s6, 0x3000
	s_nop 0
	global_load_lds_dwordx4 v[194:195], off
	s_add_u32 m0, s6, 0x4000
	s_nop 0
	global_load_lds_dwordx4 v[196:197], off
	s_add_u32 m0, s6, 0x5000
	s_nop 0
	global_load_lds_dwordx4 v[198:199], off
	s_add_u32 m0, s6, 0x6000
	s_nop 0
	global_load_lds_dwordx4 v[200:201], off
	s_add_u32 m0, s6, 0x7000
	s_nop 0
	global_load_lds_dwordx4 v[202:203], off
	s_mov_b32 s0, 0x80
	s_add_u32 m0, s6, 0x8000
	v_lshl_add_u64 v[204:205], v[188:189], 0, s[0:1]
	global_load_lds_dwordx4 v[204:205], off
	s_add_u32 m0, s6, 0x9000
	v_lshl_add_u64 v[206:207], v[190:191], 0, s[0:1]
	global_load_lds_dwordx4 v[206:207], off
	s_add_u32 m0, s6, 0xa000
	v_lshl_add_u64 v[204:205], v[192:193], 0, s[0:1]
	global_load_lds_dwordx4 v[204:205], off
	s_add_u32 m0, s6, 0xb000
	v_lshl_add_u64 v[206:207], v[194:195], 0, s[0:1]
	global_load_lds_dwordx4 v[206:207], off
	s_add_u32 m0, s6, 0xc000
	v_lshl_add_u64 v[204:205], v[196:197], 0, s[0:1]
	global_load_lds_dwordx4 v[204:205], off
	s_add_u32 m0, s6, 0xd000
	v_lshl_add_u64 v[206:207], v[198:199], 0, s[0:1]
	global_load_lds_dwordx4 v[206:207], off
	s_add_u32 m0, s6, 0xe000
	v_lshl_add_u64 v[204:205], v[200:201], 0, s[0:1]
	global_load_lds_dwordx4 v[204:205], off
	s_add_u32 m0, s6, 0xf000
	v_lshl_add_u64 v[206:207], v[202:203], 0, s[0:1]
	global_load_lds_dwordx4 v[206:207], off
	s_mov_b32 s5, 0
	s_mov_b32 s4, 0
	s_waitcnt vmcnt(8)
	s_barrier
.Lglds2_2829:
	ds_read_b128 v[152:155], v112 offset:16384
	ds_read_b128 v[156:159], v112 offset:18432
	ds_read_b128 v[160:163], v110
	ds_read_b128 v[164:167], v110 offset:2048
	ds_read_b128 v[168:171], v112 offset:20480
	ds_read_b128 v[172:175], v113 offset:16384
	ds_read_b128 v[208:211], v110 offset:4096
	ds_read_b128 v[212:215], v111
	ds_read_b128 v[216:219], v116 offset:16384
	ds_read_b128 v[220:223], v116 offset:18432
	ds_read_b128 v[224:227], v114
	ds_read_b128 v[228:231], v114 offset:2048
	ds_read_b128 v[232:235], v116 offset:20480
	ds_read_b128 v[236:239], v117 offset:16384
	ds_read_b128 v[240:243], v114 offset:4096
	ds_read_b128 v[244:247], v115
	s_setprio 1
	s_waitcnt lgkmcnt(13)
	v_mfma_f32_16x16x32_bf16 v[94:97], v[152:155], v[160:163], v[94:97]
	v_mfma_f32_16x16x32_bf16 v[90:93], v[156:159], v[160:163], v[90:93]
	s_waitcnt lgkmcnt(11)
	v_mfma_f32_16x16x32_bf16 v[86:89], v[168:171], v[160:163], v[86:89]
	s_waitcnt lgkmcnt(10)
	v_mfma_f32_16x16x32_bf16 v[82:85], v[172:175], v[160:163], v[82:85]
	v_mfma_f32_16x16x32_bf16 v[78:81], v[152:155], v[164:167], v[78:81]
	v_mfma_f32_16x16x32_bf16 v[62:65], v[156:159], v[164:167], v[62:65]
	v_mfma_f32_16x16x32_bf16 v[46:49], v[168:171], v[164:167], v[46:49]
	v_mfma_f32_16x16x32_bf16 v[26:29], v[172:175], v[164:167], v[26:29]
	s_waitcnt lgkmcnt(9)
	v_mfma_f32_16x16x32_bf16 v[38:41], v[152:155], v[208:211], v[38:41]
	v_mfma_f32_16x16x32_bf16 v[30:33], v[156:159], v[208:211], v[30:33]
	v_mfma_f32_16x16x32_bf16 v[22:25], v[168:171], v[208:211], v[22:25]
	v_mfma_f32_16x16x32_bf16 v[18:21], v[172:175], v[208:211], v[18:21]
	s_waitcnt lgkmcnt(8)
	v_mfma_f32_16x16x32_bf16 v[14:17], v[152:155], v[212:215], v[14:17]
	v_mfma_f32_16x16x32_bf16 v[10:13], v[156:159], v[212:215], v[10:13]
	v_mfma_f32_16x16x32_bf16 v[6:9], v[168:171], v[212:215], v[6:9]
	v_mfma_f32_16x16x32_bf16 v[2:5], v[172:175], v[212:215], v[2:5]
	s_setprio 0
	s_waitcnt lgkmcnt(0)
	s_barrier
	s_add_i32 s0, s5, 0x80
	s_min_u32 s0, s0, 0x3c0
	s_lshl_b32 s0, s0, 1
	s_setprio 1
	v_mfma_f32_16x16x32_bf16 v[94:97], v[216:219], v[224:227], v[94:97]
	s_add_u32 m0, s6, 0x0
	v_lshl_add_u64 v[204:205], v[188:189], 0, s[0:1]
	global_load_lds_dwordx4 v[204:205], off
	v_mfma_f32_16x16x32_bf16 v[90:93], v[220:223], v[224:227], v[90:93]
	v_mfma_f32_16x16x32_bf16 v[86:89], v[232:235], v[224:227], v[86:89]
	s_add_u32 m0, s6, 0x1000
	v_lshl_add_u64 v[206:207], v[190:191], 0, s[0:1]
	global_load_lds_dwordx4 v[206:207], off
	v_mfma_f32_16x16x32_bf16 v[82:85], v[236:239], v[224:227], v[82:85]
	v_mfma_f32_16x16x32_bf16 v[78:81], v[216:219], v[228:231], v[78:81]
	s_add_u32 m0, s6, 0x2000
	v_lshl_add_u64 v[204:205], v[192:193], 0, s[0:1]
	global_load_lds_dwordx4 v[204:205], off
	v_mfma_f32_16x16x32_bf16 v[62:65], v[220:223], v[228:231], v[62:65]
	v_mfma_f32_16x16x32_bf16 v[46:49], v[232:235], v[228:231], v[46:49]
	s_add_u32 m0, s6, 0x3000
	v_lshl_add_u64 v[206:207], v[194:195], 0, s[0:1]
	global_load_lds_dwordx4 v[206:207], off
	v_mfma_f32_16x16x32_bf16 v[26:29], v[236:239], v[228:231], v[26:29]
	v_mfma_f32_16x16x32_bf16 v[38:41], v[216:219], v[240:243], v[38:41]
	s_add_u32 m0, s6, 0x4000
	v_lshl_add_u64 v[204:205], v[196:197], 0, s[0:1]
	global_load_lds_dwordx4 v[204:205], off
	v_mfma_f32_16x16x32_bf16 v[30:33], v[220:223], v[240:243], v[30:33]
	v_mfma_f32_16x16x32_bf16 v[22:25], v[232:235], v[240:243], v[22:25]
	s_add_u32 m0, s6, 0x5000
	v_lshl_add_u64 v[206:207], v[198:199], 0, s[0:1]
	global_load_lds_dwordx4 v[206:207], off
	v_mfma_f32_16x16x32_bf16 v[18:21], v[236:239], v[240:243], v[18:21]
	v_mfma_f32_16x16x32_bf16 v[14:17], v[216:219], v[244:247], v[14:17]
	s_add_u32 m0, s6, 0x6000
	v_lshl_add_u64 v[204:205], v[200:201], 0, s[0:1]
	global_load_lds_dwordx4 v[204:205], off
	v_mfma_f32_16x16x32_bf16 v[10:13], v[220:223], v[244:247], v[10:13]
	v_mfma_f32_16x16x32_bf16 v[6:9], v[232:235], v[244:247], v[6:9]
	s_add_u32 m0, s6, 0x7000
	v_lshl_add_u64 v[206:207], v[202:203], 0, s[0:1]
	global_load_lds_dwordx4 v[206:207], off
	v_mfma_f32_16x16x32_bf16 v[2:5], v[236:239], v[244:247], v[2:5]
	s_setprio 0
	s_waitcnt vmcnt(8)
	s_barrier
	ds_read_b128 v[152:155], v112 offset:49152
	ds_read_b128 v[156:159], v112 offset:51200
	ds_read_b128 v[160:163], v110 offset:32768
	ds_read_b128 v[164:167], v110 offset:34816
	ds_read_b128 v[168:171], v112 offset:53248
	ds_read_b128 v[172:175], v113 offset:49152
	ds_read_b128 v[208:211], v110 offset:36864
	ds_read_b128 v[212:215], v111 offset:32768
	ds_read_b128 v[216:219], v116 offset:49152
	ds_read_b128 v[220:223], v116 offset:51200
	ds_read_b128 v[224:227], v114 offset:32768
	ds_read_b128 v[228:231], v114 offset:34816
	ds_read_b128 v[232:235], v116 offset:53248
	ds_read_b128 v[236:239], v117 offset:49152
	ds_read_b128 v[240:243], v114 offset:36864
	ds_read_b128 v[244:247], v115 offset:32768
	s_setprio 1
	s_waitcnt lgkmcnt(13)
	v_mfma_f32_16x16x32_bf16 v[94:97], v[152:155], v[160:163], v[94:97]
	v_mfma_f32_16x16x32_bf16 v[90:93], v[156:159], v[160:163], v[90:93]
	s_waitcnt lgkmcnt(11)
	v_mfma_f32_16x16x32_bf16 v[86:89], v[168:171], v[160:163], v[86:89]
	s_waitcnt lgkmcnt(10)
	v_mfma_f32_16x16x32_bf16 v[82:85], v[172:175], v[160:163], v[82:85]
	v_mfma_f32_16x16x32_bf16 v[78:81], v[152:155], v[164:167], v[78:81]
	v_mfma_f32_16x16x32_bf16 v[62:65], v[156:159], v[164:167], v[62:65]
	v_mfma_f32_16x16x32_bf16 v[46:49], v[168:171], v[164:167], v[46:49]
	v_mfma_f32_16x16x32_bf16 v[26:29], v[172:175], v[164:167], v[26:29]
	s_waitcnt lgkmcnt(9)
	v_mfma_f32_16x16x32_bf16 v[38:41], v[152:155], v[208:211], v[38:41]
	v_mfma_f32_16x16x32_bf16 v[30:33], v[156:159], v[208:211], v[30:33]
	v_mfma_f32_16x16x32_bf16 v[22:25], v[168:171], v[208:211], v[22:25]
	v_mfma_f32_16x16x32_bf16 v[18:21], v[172:175], v[208:211], v[18:21]
	s_waitcnt lgkmcnt(8)
	v_mfma_f32_16x16x32_bf16 v[14:17], v[152:155], v[212:215], v[14:17]
	v_mfma_f32_16x16x32_bf16 v[10:13], v[156:159], v[212:215], v[10:13]
	v_mfma_f32_16x16x32_bf16 v[6:9], v[168:171], v[212:215], v[6:9]
	v_mfma_f32_16x16x32_bf16 v[2:5], v[172:175], v[212:215], v[2:5]
	s_setprio 0
	s_waitcnt lgkmcnt(0)
	s_barrier
	s_add_i32 s0, s5, 0xc0
	s_min_u32 s0, s0, 0x3c0
	s_lshl_b32 s0, s0, 1
	s_setprio 1
	v_mfma_f32_16x16x32_bf16 v[94:97], v[216:219], v[224:227], v[94:97]
	s_add_u32 m0, s6, 0x8000
	v_lshl_add_u64 v[204:205], v[188:189], 0, s[0:1]
	global_load_lds_dwordx4 v[204:205], off
	v_mfma_f32_16x16x32_bf16 v[90:93], v[220:223], v[224:227], v[90:93]
	v_mfma_f32_16x16x32_bf16 v[86:89], v[232:235], v[224:227], v[86:89]
	s_add_u32 m0, s6, 0x9000
	v_lshl_add_u64 v[206:207], v[190:191], 0, s[0:1]
	global_load_lds_dwordx4 v[206:207], off
	v_mfma_f32_16x16x32_bf16 v[82:85], v[236:239], v[224:227], v[82:85]
	v_mfma_f32_16x16x32_bf16 v[78:81], v[216:219], v[228:231], v[78:81]
	s_add_u32 m0, s6, 0xa000
	v_lshl_add_u64 v[204:205], v[192:193], 0, s[0:1]
	global_load_lds_dwordx4 v[204:205], off
	v_mfma_f32_16x16x32_bf16 v[62:65], v[220:223], v[228:231], v[62:65]
	v_mfma_f32_16x16x32_bf16 v[46:49], v[232:235], v[228:231], v[46:49]
	s_add_u32 m0, s6, 0xb000
	v_lshl_add_u64 v[206:207], v[194:195], 0, s[0:1]
	global_load_lds_dwordx4 v[206:207], off
	v_mfma_f32_16x16x32_bf16 v[26:29], v[236:239], v[228:231], v[26:29]
	v_mfma_f32_16x16x32_bf16 v[38:41], v[216:219], v[240:243], v[38:41]
	s_add_u32 m0, s6, 0xc000
	v_lshl_add_u64 v[204:205], v[196:197], 0, s[0:1]
	global_load_lds_dwordx4 v[204:205], off
	v_mfma_f32_16x16x32_bf16 v[30:33], v[220:223], v[240:243], v[30:33]
	v_mfma_f32_16x16x32_bf16 v[22:25], v[232:235], v[240:243], v[22:25]
	s_add_u32 m0, s6, 0xd000
	v_lshl_add_u64 v[206:207], v[198:199], 0, s[0:1]
	global_load_lds_dwordx4 v[206:207], off
	v_mfma_f32_16x16x32_bf16 v[18:21], v[236:239], v[240:243], v[18:21]
	v_mfma_f32_16x16x32_bf16 v[14:17], v[216:219], v[244:247], v[14:17]
	s_add_u32 m0, s6, 0xe000
	v_lshl_add_u64 v[204:205], v[200:201], 0, s[0:1]
	global_load_lds_dwordx4 v[204:205], off
	v_mfma_f32_16x16x32_bf16 v[10:13], v[220:223], v[244:247], v[10:13]
	v_mfma_f32_16x16x32_bf16 v[6:9], v[232:235], v[244:247], v[6:9]
	s_add_u32 m0, s6, 0xf000
	v_lshl_add_u64 v[206:207], v[202:203], 0, s[0:1]
	global_load_lds_dwordx4 v[206:207], off
	v_mfma_f32_16x16x32_bf16 v[2:5], v[236:239], v[244:247], v[2:5]
	s_setprio 0
	s_waitcnt vmcnt(8)
	s_barrier
	s_add_i32 s5, s5, 0x80
	s_add_i32 s4, s4, 2
	s_cmp_gt_u32 s4, 13
	s_cbranch_scc0 .Lglds2_2829
	ds_read_b128 v[152:155], v112 offset:16384
	ds_read_b128 v[156:159], v112 offset:18432
	ds_read_b128 v[160:163], v110
	ds_read_b128 v[164:167], v110 offset:2048
	ds_read_b128 v[168:171], v112 offset:20480
	ds_read_b128 v[172:175], v113 offset:16384
	ds_read_b128 v[208:211], v110 offset:4096
	ds_read_b128 v[212:215], v111
	ds_read_b128 v[216:219], v116 offset:16384
	ds_read_b128 v[220:223], v116 offset:18432
	ds_read_b128 v[224:227], v114
	ds_read_b128 v[228:231], v114 offset:2048
	ds_read_b128 v[232:235], v116 offset:20480
	ds_read_b128 v[236:239], v117 offset:16384
	ds_read_b128 v[240:243], v114 offset:4096
	ds_read_b128 v[244:247], v115
	s_setprio 1
	s_waitcnt lgkmcnt(13)
	v_mfma_f32_16x16x32_bf16 v[94:97], v[152:155], v[160:163], v[94:97]
	v_mfma_f32_16x16x32_bf16 v[90:93], v[156:159], v[160:163], v[90:93]
	s_waitcnt lgkmcnt(11)
	v_mfma_f32_16x16x32_bf16 v[86:89], v[168:171], v[160:163], v[86:89]
	s_waitcnt lgkmcnt(10)
	v_mfma_f32_16x16x32_bf16 v[82:85], v[172:175], v[160:163], v[82:85]
	v_mfma_f32_16x16x32_bf16 v[78:81], v[152:155], v[164:167], v[78:81]
	v_mfma_f32_16x16x32_bf16 v[62:65], v[156:159], v[164:167], v[62:65]
	v_mfma_f32_16x16x32_bf16 v[46:49], v[168:171], v[164:167], v[46:49]
	v_mfma_f32_16x16x32_bf16 v[26:29], v[172:175], v[164:167], v[26:29]
	s_waitcnt lgkmcnt(9)
	v_mfma_f32_16x16x32_bf16 v[38:41], v[152:155], v[208:211], v[38:41]
	v_mfma_f32_16x16x32_bf16 v[30:33], v[156:159], v[208:211], v[30:33]
	v_mfma_f32_16x16x32_bf16 v[22:25], v[168:171], v[208:211], v[22:25]
	v_mfma_f32_16x16x32_bf16 v[18:21], v[172:175], v[208:211], v[18:21]
	s_waitcnt lgkmcnt(8)
	v_mfma_f32_16x16x32_bf16 v[14:17], v[152:155], v[212:215], v[14:17]
	v_mfma_f32_16x16x32_bf16 v[10:13], v[156:159], v[212:215], v[10:13]
	v_mfma_f32_16x16x32_bf16 v[6:9], v[168:171], v[212:215], v[6:9]
	v_mfma_f32_16x16x32_bf16 v[2:5], v[172:175], v[212:215], v[2:5]
	s_setprio 0
	s_waitcnt lgkmcnt(0)
	s_setprio 1
	v_mfma_f32_16x16x32_bf16 v[94:97], v[216:219], v[224:227], v[94:97]
	v_mfma_f32_16x16x32_bf16 v[90:93], v[220:223], v[224:227], v[90:93]
	v_mfma_f32_16x16x32_bf16 v[86:89], v[232:235], v[224:227], v[86:89]
	v_mfma_f32_16x16x32_bf16 v[82:85], v[236:239], v[224:227], v[82:85]
	v_mfma_f32_16x16x32_bf16 v[78:81], v[216:219], v[228:231], v[78:81]
	v_mfma_f32_16x16x32_bf16 v[62:65], v[220:223], v[228:231], v[62:65]
	v_mfma_f32_16x16x32_bf16 v[46:49], v[232:235], v[228:231], v[46:49]
	v_mfma_f32_16x16x32_bf16 v[26:29], v[236:239], v[228:231], v[26:29]
	v_mfma_f32_16x16x32_bf16 v[38:41], v[216:219], v[240:243], v[38:41]
	v_mfma_f32_16x16x32_bf16 v[30:33], v[220:223], v[240:243], v[30:33]
	v_mfma_f32_16x16x32_bf16 v[22:25], v[232:235], v[240:243], v[22:25]
	v_mfma_f32_16x16x32_bf16 v[18:21], v[236:239], v[240:243], v[18:21]
	v_mfma_f32_16x16x32_bf16 v[14:17], v[216:219], v[244:247], v[14:17]
	v_mfma_f32_16x16x32_bf16 v[10:13], v[220:223], v[244:247], v[10:13]
	v_mfma_f32_16x16x32_bf16 v[6:9], v[232:235], v[244:247], v[6:9]
	v_mfma_f32_16x16x32_bf16 v[2:5], v[236:239], v[244:247], v[2:5]
	s_setprio 0
	s_waitcnt vmcnt(0)
	s_barrier
	ds_read_b128 v[152:155], v112 offset:49152
	ds_read_b128 v[156:159], v112 offset:51200
	ds_read_b128 v[160:163], v110 offset:32768
	ds_read_b128 v[164:167], v110 offset:34816
	ds_read_b128 v[168:171], v112 offset:53248
	ds_read_b128 v[172:175], v113 offset:49152
	ds_read_b128 v[208:211], v110 offset:36864
	ds_read_b128 v[212:215], v111 offset:32768
	ds_read_b128 v[216:219], v116 offset:49152
	ds_read_b128 v[220:223], v116 offset:51200
	ds_read_b128 v[224:227], v114 offset:32768
	ds_read_b128 v[228:231], v114 offset:34816
	ds_read_b128 v[232:235], v116 offset:53248
	ds_read_b128 v[236:239], v117 offset:49152
	ds_read_b128 v[240:243], v114 offset:36864
	ds_read_b128 v[244:247], v115 offset:32768
	s_setprio 1
	s_waitcnt lgkmcnt(13)
	v_mfma_f32_16x16x32_bf16 v[94:97], v[152:155], v[160:163], v[94:97]
	v_mfma_f32_16x16x32_bf16 v[90:93], v[156:159], v[160:163], v[90:93]
	s_waitcnt lgkmcnt(11)
	v_mfma_f32_16x16x32_bf16 v[86:89], v[168:171], v[160:163], v[86:89]
	s_waitcnt lgkmcnt(10)
	v_mfma_f32_16x16x32_bf16 v[82:85], v[172:175], v[160:163], v[82:85]
	v_mfma_f32_16x16x32_bf16 v[78:81], v[152:155], v[164:167], v[78:81]
	v_mfma_f32_16x16x32_bf16 v[62:65], v[156:159], v[164:167], v[62:65]
	v_mfma_f32_16x16x32_bf16 v[46:49], v[168:171], v[164:167], v[46:49]
	v_mfma_f32_16x16x32_bf16 v[26:29], v[172:175], v[164:167], v[26:29]
	s_waitcnt lgkmcnt(9)
	v_mfma_f32_16x16x32_bf16 v[38:41], v[152:155], v[208:211], v[38:41]
	v_mfma_f32_16x16x32_bf16 v[30:33], v[156:159], v[208:211], v[30:33]
	v_mfma_f32_16x16x32_bf16 v[22:25], v[168:171], v[208:211], v[22:25]
	v_mfma_f32_16x16x32_bf16 v[18:21], v[172:175], v[208:211], v[18:21]
	s_waitcnt lgkmcnt(8)
	v_mfma_f32_16x16x32_bf16 v[14:17], v[152:155], v[212:215], v[14:17]
	v_mfma_f32_16x16x32_bf16 v[10:13], v[156:159], v[212:215], v[10:13]
	v_mfma_f32_16x16x32_bf16 v[6:9], v[168:171], v[212:215], v[6:9]
	v_mfma_f32_16x16x32_bf16 v[2:5], v[172:175], v[212:215], v[2:5]
	s_setprio 0
	s_waitcnt lgkmcnt(0)
	s_barrier
	s_setprio 1
	v_mfma_f32_16x16x32_bf16 v[94:97], v[216:219], v[224:227], v[94:97]
	v_mfma_f32_16x16x32_bf16 v[90:93], v[220:223], v[224:227], v[90:93]
	v_mfma_f32_16x16x32_bf16 v[86:89], v[232:235], v[224:227], v[86:89]
	v_mfma_f32_16x16x32_bf16 v[82:85], v[236:239], v[224:227], v[82:85]
	v_mfma_f32_16x16x32_bf16 v[78:81], v[216:219], v[228:231], v[78:81]
	v_mfma_f32_16x16x32_bf16 v[62:65], v[220:223], v[228:231], v[62:65]
	v_mfma_f32_16x16x32_bf16 v[46:49], v[232:235], v[228:231], v[46:49]
	v_mfma_f32_16x16x32_bf16 v[26:29], v[236:239], v[228:231], v[26:29]
	v_mfma_f32_16x16x32_bf16 v[38:41], v[216:219], v[240:243], v[38:41]
	v_mfma_f32_16x16x32_bf16 v[30:33], v[220:223], v[240:243], v[30:33]
	v_mfma_f32_16x16x32_bf16 v[22:25], v[232:235], v[240:243], v[22:25]
	v_mfma_f32_16x16x32_bf16 v[18:21], v[236:239], v[240:243], v[18:21]
	v_mfma_f32_16x16x32_bf16 v[14:17], v[216:219], v[244:247], v[14:17]
	v_mfma_f32_16x16x32_bf16 v[10:13], v[220:223], v[244:247], v[10:13]
	v_mfma_f32_16x16x32_bf16 v[6:9], v[232:235], v[244:247], v[6:9]
	v_mfma_f32_16x16x32_bf16 v[2:5], v[236:239], v[244:247], v[2:5]
	s_setprio 0
	s_waitcnt vmcnt(0)
	v_readlane_b32 s36, v254, 40
	s_waitcnt vmcnt(7)
	v_or_b32_e32 v35, s2, v118
	v_readlane_b32 s48, v254, 52
	v_readlane_b32 s49, v254, 53
	v_or_b32_e32 v34, s3, v119
	s_waitcnt vmcnt(6)
	v_add_u32_e32 v42, v35, v120
	v_mov_b64_e32 v[36:37], s[48:49]
	v_mad_i64_i32 v[36:37], s[2:3], v42, s18, v[36:37]
	v_cmp_gt_i32_e32 vcc, s19, v34
	v_ashrrev_i32_e32 v35, 31, v34
	v_readlane_b32 s37, v254, 41
	v_readlane_b32 s38, v254, 42
	v_readlane_b32 s39, v254, 43
	v_readlane_b32 s40, v254, 44
	v_readlane_b32 s41, v254, 45
	v_readlane_b32 s42, v254, 46
	v_readlane_b32 s43, v254, 47
	v_readlane_b32 s44, v254, 48
	v_readlane_b32 s45, v254, 49
	v_readlane_b32 s46, v254, 50
	v_readlane_b32 s47, v254, 51
	v_readlane_b32 s50, v254, 54
	v_readlane_b32 s51, v254, 55
	s_and_saveexec_b64 s[2:3], vcc
	s_cbranch_execnz .LBB0_205
	s_or_b64 exec, exec, s[2:3]
	v_cmp_gt_i32_e64 s[4:5], s20, v34
	s_and_saveexec_b64 s[2:3], s[4:5]
	s_cbranch_execnz .LBB0_206

.LBB0_220:
	s_ashr_i32 s12, s2, 6
	s_ashr_i32 s13, s12, 31
	s_lshl_b64 s[16:17], s[12:13], 20
	s_add_u32 s18, s36, s16
	s_addc_u32 s19, s37, s17
	s_lshl_b32 s0, s2, 5
	s_and_b32 s16, s0, 0x780
	s_lshl_b32 s0, s2, 7
	s_and_b32 s17, s0, 0x180
	v_or_b32_e32 v2, s16, v1
	v_lshlrev_b32_e32 v98, 11, v2
	v_or_b32_e32 v2, s17, v1
	v_lshl_add_u64 v[104:105], v[100:101], 0, v[98:99]
	v_lshlrev_b32_e32 v98, 11, v2
	v_lshl_add_u64 v[2:3], s[18:19], 0, v[98:99]
	v_lshl_add_u64 v[108:109], v[2:3], 0, v[102:103]
	s_mov_b32 s18, -2
	s_mov_b32 s19, s1
	v_mov_b32_e32 v34, 0
	v_mov_b32_e32 v35, v99
	v_mov_b32_e32 v36, v99
	v_mov_b32_e32 v37, v99
	v_mov_b32_e32 v38, 0
	v_mov_b32_e32 v39, v99
	v_mov_b32_e32 v40, v99
	v_mov_b32_e32 v41, v99
	v_mov_b32_e32 v54, 0
	v_mov_b32_e32 v55, v99
	v_mov_b32_e32 v56, v99
	v_mov_b32_e32 v57, v99
	v_mov_b32_e32 v78, 0
	v_mov_b32_e32 v79, v99
	v_mov_b32_e32 v80, v99
	v_mov_b32_e32 v81, v99
	v_mov_b32_e32 v82, 0
	v_mov_b32_e32 v83, v99
	v_mov_b32_e32 v84, v99
	v_mov_b32_e32 v85, v99
	v_mov_b32_e32 v86, 0
	v_mov_b32_e32 v87, v99
	v_mov_b32_e32 v88, v99
	v_mov_b32_e32 v89, v99
	v_mov_b32_e32 v90, 0
	v_mov_b32_e32 v91, v99
	v_mov_b32_e32 v92, v99
	v_mov_b32_e32 v93, v99
	v_mov_b32_e32 v94, 0
	v_mov_b32_e32 v95, v99
	v_mov_b32_e32 v96, v99
	v_mov_b32_e32 v97, v99
	v_mov_b32_e32 v74, 0
	v_mov_b32_e32 v75, v99
	v_mov_b32_e32 v76, v99
	v_mov_b32_e32 v77, v99
	v_mov_b32_e32 v70, 0
	v_mov_b32_e32 v71, v99
	v_mov_b32_e32 v72, v99
	v_mov_b32_e32 v73, v99
	v_mov_b32_e32 v66, 0
	v_mov_b32_e32 v67, v99
	v_mov_b32_e32 v68, v99
	v_mov_b32_e32 v69, v99
	v_mov_b32_e32 v62, 0
	v_mov_b32_e32 v63, v99
	v_mov_b32_e32 v64, v99
	v_mov_b32_e32 v65, v99
	v_mov_b32_e32 v58, 0
	v_mov_b32_e32 v59, v99
	v_mov_b32_e32 v60, v99
	v_mov_b32_e32 v61, v99
	v_mov_b32_e32 v50, 0
	v_mov_b32_e32 v51, v99
	v_mov_b32_e32 v52, v99
	v_mov_b32_e32 v53, v99
	v_mov_b32_e32 v46, 0
	v_mov_b32_e32 v47, v99
	v_mov_b32_e32 v48, v99
	v_mov_b32_e32 v49, v99
	v_mov_b32_e32 v42, 0
	v_mov_b32_e32 v43, v99
	v_mov_b32_e32 v44, v99
	v_mov_b32_e32 v45, v99
	v_and_b32_e32 v181, 7, v106
	v_bfe_u32 v180, v106, 3, 3
	v_xor_b32_e32 v180, v181, v180
	v_sub_u32_e32 v180, v180, v181
	v_lshlrev_b32_e32 v180, 4, v180
	v_ashrrev_i32_e32 v181, 31, v180
	v_lshrrev_b32_e32 v186, 6, v106
	v_mov_b32_e32 v187, 0x110
	v_lshl_add_u32 v186, v186, 10, v187
	v_lshl_add_u64 v[188:189], v[104:105], 0, v[180:181]
	v_lshl_add_u64 v[196:197], v[108:109], 0, v[180:181]
	v_readfirstlane_b32 s20, v186
	v_add_co_u32_e32 v190, vcc, s3, v188
	v_addc_co_u32_e32 v191, vcc, 0, v189, vcc
	v_add_co_u32_e32 v192, vcc, s14, v188
	v_addc_co_u32_e32 v193, vcc, 0, v189, vcc
	v_add_co_u32_e32 v194, vcc, s15, v188
	v_addc_co_u32_e32 v195, vcc, 0, v189, vcc
	v_add_co_u32_e32 v198, vcc, s3, v196
	v_addc_co_u32_e32 v199, vcc, 0, v197, vcc
	v_add_co_u32_e32 v200, vcc, s14, v196
	v_addc_co_u32_e32 v201, vcc, 0, v197, vcc
	v_add_co_u32_e32 v202, vcc, s15, v196
	v_addc_co_u32_e32 v203, vcc, 0, v197, vcc
	s_add_u32 m0, s20, 0x0
	s_nop 0
	global_load_lds_dwordx4 v[188:189], off
	s_add_u32 m0, s20, 0x1000
	s_nop 0
	global_load_lds_dwordx4 v[190:191], off
	s_add_u32 m0, s20, 0x2000
	s_nop 0
	global_load_lds_dwordx4 v[192:193], off
	s_add_u32 m0, s20, 0x3000
	s_nop 0
	global_load_lds_dwordx4 v[194:195], off
	s_add_u32 m0, s20, 0x4000
	s_nop 0
	global_load_lds_dwordx4 v[196:197], off
	s_add_u32 m0, s20, 0x5000
	s_nop 0
	global_load_lds_dwordx4 v[198:199], off
	s_add_u32 m0, s20, 0x6000
	s_nop 0
	global_load_lds_dwordx4 v[200:201], off
	s_add_u32 m0, s20, 0x7000
	s_nop 0
	global_load_lds_dwordx4 v[202:203], off
	s_mov_b32 s0, 0x80
	s_add_u32 m0, s20, 0x8000
	v_lshl_add_u64 v[204:205], v[188:189], 0, s[0:1]
	global_load_lds_dwordx4 v[204:205], off
	s_add_u32 m0, s20, 0x9000
	v_lshl_add_u64 v[206:207], v[190:191], 0, s[0:1]
	global_load_lds_dwordx4 v[206:207], off
	s_add_u32 m0, s20, 0xa000
	v_lshl_add_u64 v[204:205], v[192:193], 0, s[0:1]
	global_load_lds_dwordx4 v[204:205], off
	s_add_u32 m0, s20, 0xb000
	v_lshl_add_u64 v[206:207], v[194:195], 0, s[0:1]
	global_load_lds_dwordx4 v[206:207], off
	s_add_u32 m0, s20, 0xc000
	v_lshl_add_u64 v[204:205], v[196:197], 0, s[0:1]
	global_load_lds_dwordx4 v[204:205], off
	s_add_u32 m0, s20, 0xd000
	v_lshl_add_u64 v[206:207], v[198:199], 0, s[0:1]
	global_load_lds_dwordx4 v[206:207], off
	s_add_u32 m0, s20, 0xe000
	v_lshl_add_u64 v[204:205], v[200:201], 0, s[0:1]
	global_load_lds_dwordx4 v[204:205], off
	s_add_u32 m0, s20, 0xf000
	v_lshl_add_u64 v[206:207], v[202:203], 0, s[0:1]
	global_load_lds_dwordx4 v[206:207], off
	s_mov_b32 s19, 0
	s_mov_b32 s18, 0
	s_waitcnt vmcnt(8)
	s_barrier
.Lglds2_3547:
	ds_read_b128 v[152:155], v112 offset:16384
	ds_read_b128 v[156:159], v112 offset:18432
	ds_read_b128 v[160:163], v110
	ds_read_b128 v[164:167], v110 offset:2048
	ds_read_b128 v[168:171], v112 offset:20480
	ds_read_b128 v[172:175], v113 offset:16384
	ds_read_b128 v[208:211], v110 offset:4096
	ds_read_b128 v[212:215], v111
	ds_read_b128 v[216:219], v116 offset:16384
	ds_read_b128 v[220:223], v116 offset:18432
	ds_read_b128 v[224:227], v114
	ds_read_b128 v[228:231], v114 offset:2048
	ds_read_b128 v[232:235], v116 offset:20480
	ds_read_b128 v[236:239], v117 offset:16384
	ds_read_b128 v[240:243], v114 offset:4096
	ds_read_b128 v[244:247], v115
	s_setprio 1
	s_waitcnt lgkmcnt(13)
	v_mfma_f32_16x16x32_bf16 v[94:97], v[152:155], v[160:163], v[94:97]
	v_mfma_f32_16x16x32_bf16 v[90:93], v[156:159], v[160:163], v[90:93]
	s_waitcnt lgkmcnt(11)
	v_mfma_f32_16x16x32_bf16 v[86:89], v[168:171], v[160:163], v[86:89]
	s_waitcnt lgkmcnt(10)
	v_mfma_f32_16x16x32_bf16 v[82:85], v[172:175], v[160:163], v[82:85]
	v_mfma_f32_16x16x32_bf16 v[78:81], v[152:155], v[164:167], v[78:81]
	v_mfma_f32_16x16x32_bf16 v[54:57], v[156:159], v[164:167], v[54:57]
	v_mfma_f32_16x16x32_bf16 v[38:41], v[168:171], v[164:167], v[38:41]
	v_mfma_f32_16x16x32_bf16 v[34:37], v[172:175], v[164:167], v[34:37]
	s_waitcnt lgkmcnt(9)
	v_mfma_f32_16x16x32_bf16 v[74:77], v[152:155], v[208:211], v[74:77]
	v_mfma_f32_16x16x32_bf16 v[70:73], v[156:159], v[208:211], v[70:73]
	v_mfma_f32_16x16x32_bf16 v[66:69], v[168:171], v[208:211], v[66:69]
	v_mfma_f32_16x16x32_bf16 v[62:65], v[172:175], v[208:211], v[62:65]
	s_waitcnt lgkmcnt(8)
	v_mfma_f32_16x16x32_bf16 v[58:61], v[152:155], v[212:215], v[58:61]
	v_mfma_f32_16x16x32_bf16 v[50:53], v[156:159], v[212:215], v[50:53]
	v_mfma_f32_16x16x32_bf16 v[46:49], v[168:171], v[212:215], v[46:49]
	v_mfma_f32_16x16x32_bf16 v[42:45], v[172:175], v[212:215], v[42:45]
	s_setprio 0
	s_waitcnt lgkmcnt(0)
	s_barrier
	s_add_i32 s0, s19, 0x80
	s_min_u32 s0, s0, 0x3c0
	s_lshl_b32 s0, s0, 1
	s_setprio 1
	v_mfma_f32_16x16x32_bf16 v[94:97], v[216:219], v[224:227], v[94:97]
	s_add_u32 m0, s20, 0x0
	v_lshl_add_u64 v[204:205], v[188:189], 0, s[0:1]
	global_load_lds_dwordx4 v[204:205], off
	v_mfma_f32_16x16x32_bf16 v[90:93], v[220:223], v[224:227], v[90:93]
	v_mfma_f32_16x16x32_bf16 v[86:89], v[232:235], v[224:227], v[86:89]
	s_add_u32 m0, s20, 0x1000
	v_lshl_add_u64 v[206:207], v[190:191], 0, s[0:1]
	global_load_lds_dwordx4 v[206:207], off
	v_mfma_f32_16x16x32_bf16 v[82:85], v[236:239], v[224:227], v[82:85]
	v_mfma_f32_16x16x32_bf16 v[78:81], v[216:219], v[228:231], v[78:81]
	s_add_u32 m0, s20, 0x2000
	v_lshl_add_u64 v[204:205], v[192:193], 0, s[0:1]
	global_load_lds_dwordx4 v[204:205], off
	v_mfma_f32_16x16x32_bf16 v[54:57], v[220:223], v[228:231], v[54:57]
	v_mfma_f32_16x16x32_bf16 v[38:41], v[232:235], v[228:231], v[38:41]
	s_add_u32 m0, s20, 0x3000
	v_lshl_add_u64 v[206:207], v[194:195], 0, s[0:1]
	global_load_lds_dwordx4 v[206:207], off
	v_mfma_f32_16x16x32_bf16 v[34:37], v[236:239], v[228:231], v[34:37]
	v_mfma_f32_16x16x32_bf16 v[74:77], v[216:219], v[240:243], v[74:77]
	s_add_u32 m0, s20, 0x4000
	v_lshl_add_u64 v[204:205], v[196:197], 0, s[0:1]
	global_load_lds_dwordx4 v[204:205], off
	v_mfma_f32_16x16x32_bf16 v[70:73], v[220:223], v[240:243], v[70:73]
	v_mfma_f32_16x16x32_bf16 v[66:69], v[232:235], v[240:243], v[66:69]
	s_add_u32 m0, s20, 0x5000
	v_lshl_add_u64 v[206:207], v[198:199], 0, s[0:1]
	global_load_lds_dwordx4 v[206:207], off
	v_mfma_f32_16x16x32_bf16 v[62:65], v[236:239], v[240:243], v[62:65]
	v_mfma_f32_16x16x32_bf16 v[58:61], v[216:219], v[244:247], v[58:61]
	s_add_u32 m0, s20, 0x6000
	v_lshl_add_u64 v[204:205], v[200:201], 0, s[0:1]
	global_load_lds_dwordx4 v[204:205], off
	v_mfma_f32_16x16x32_bf16 v[50:53], v[220:223], v[244:247], v[50:53]
	v_mfma_f32_16x16x32_bf16 v[46:49], v[232:235], v[244:247], v[46:49]
	s_add_u32 m0, s20, 0x7000
	v_lshl_add_u64 v[206:207], v[202:203], 0, s[0:1]
	global_load_lds_dwordx4 v[206:207], off
	v_mfma_f32_16x16x32_bf16 v[42:45], v[236:239], v[244:247], v[42:45]
	s_setprio 0
	s_waitcnt vmcnt(8)
	s_barrier
	ds_read_b128 v[152:155], v112 offset:49152
	ds_read_b128 v[156:159], v112 offset:51200
	ds_read_b128 v[160:163], v110 offset:32768
	ds_read_b128 v[164:167], v110 offset:34816
	ds_read_b128 v[168:171], v112 offset:53248
	ds_read_b128 v[172:175], v113 offset:49152
	ds_read_b128 v[208:211], v110 offset:36864
	ds_read_b128 v[212:215], v111 offset:32768
	ds_read_b128 v[216:219], v116 offset:49152
	ds_read_b128 v[220:223], v116 offset:51200
	ds_read_b128 v[224:227], v114 offset:32768
	ds_read_b128 v[228:231], v114 offset:34816
	ds_read_b128 v[232:235], v116 offset:53248
	ds_read_b128 v[236:239], v117 offset:49152
	ds_read_b128 v[240:243], v114 offset:36864
	ds_read_b128 v[244:247], v115 offset:32768
	s_setprio 1
	s_waitcnt lgkmcnt(13)
	v_mfma_f32_16x16x32_bf16 v[94:97], v[152:155], v[160:163], v[94:97]
	v_mfma_f32_16x16x32_bf16 v[90:93], v[156:159], v[160:163], v[90:93]
	s_waitcnt lgkmcnt(11)
	v_mfma_f32_16x16x32_bf16 v[86:89], v[168:171], v[160:163], v[86:89]
	s_waitcnt lgkmcnt(10)
	v_mfma_f32_16x16x32_bf16 v[82:85], v[172:175], v[160:163], v[82:85]
	v_mfma_f32_16x16x32_bf16 v[78:81], v[152:155], v[164:167], v[78:81]
	v_mfma_f32_16x16x32_bf16 v[54:57], v[156:159], v[164:167], v[54:57]
	v_mfma_f32_16x16x32_bf16 v[38:41], v[168:171], v[164:167], v[38:41]
	v_mfma_f32_16x16x32_bf16 v[34:37], v[172:175], v[164:167], v[34:37]
	s_waitcnt lgkmcnt(9)
	v_mfma_f32_16x16x32_bf16 v[74:77], v[152:155], v[208:211], v[74:77]
	v_mfma_f32_16x16x32_bf16 v[70:73], v[156:159], v[208:211], v[70:73]
	v_mfma_f32_16x16x32_bf16 v[66:69], v[168:171], v[208:211], v[66:69]
	v_mfma_f32_16x16x32_bf16 v[62:65], v[172:175], v[208:211], v[62:65]
	s_waitcnt lgkmcnt(8)
	v_mfma_f32_16x16x32_bf16 v[58:61], v[152:155], v[212:215], v[58:61]
	v_mfma_f32_16x16x32_bf16 v[50:53], v[156:159], v[212:215], v[50:53]
	v_mfma_f32_16x16x32_bf16 v[46:49], v[168:171], v[212:215], v[46:49]
	v_mfma_f32_16x16x32_bf16 v[42:45], v[172:175], v[212:215], v[42:45]
	s_setprio 0
	s_waitcnt lgkmcnt(0)
	s_barrier
	s_add_i32 s0, s19, 0xc0
	s_min_u32 s0, s0, 0x3c0
	s_lshl_b32 s0, s0, 1
	s_setprio 1
	v_mfma_f32_16x16x32_bf16 v[94:97], v[216:219], v[224:227], v[94:97]
	s_add_u32 m0, s20, 0x8000
	v_lshl_add_u64 v[204:205], v[188:189], 0, s[0:1]
	global_load_lds_dwordx4 v[204:205], off
	v_mfma_f32_16x16x32_bf16 v[90:93], v[220:223], v[224:227], v[90:93]
	v_mfma_f32_16x16x32_bf16 v[86:89], v[232:235], v[224:227], v[86:89]
	s_add_u32 m0, s20, 0x9000
	v_lshl_add_u64 v[206:207], v[190:191], 0, s[0:1]
	global_load_lds_dwordx4 v[206:207], off
	v_mfma_f32_16x16x32_bf16 v[82:85], v[236:239], v[224:227], v[82:85]
	v_mfma_f32_16x16x32_bf16 v[78:81], v[216:219], v[228:231], v[78:81]
	s_add_u32 m0, s20, 0xa000
	v_lshl_add_u64 v[204:205], v[192:193], 0, s[0:1]
	global_load_lds_dwordx4 v[204:205], off
	v_mfma_f32_16x16x32_bf16 v[54:57], v[220:223], v[228:231], v[54:57]
	v_mfma_f32_16x16x32_bf16 v[38:41], v[232:235], v[228:231], v[38:41]
	s_add_u32 m0, s20, 0xb000
	v_lshl_add_u64 v[206:207], v[194:195], 0, s[0:1]
	global_load_lds_dwordx4 v[206:207], off
	v_mfma_f32_16x16x32_bf16 v[34:37], v[236:239], v[228:231], v[34:37]
	v_mfma_f32_16x16x32_bf16 v[74:77], v[216:219], v[240:243], v[74:77]
	s_add_u32 m0, s20, 0xc000
	v_lshl_add_u64 v[204:205], v[196:197], 0, s[0:1]
	global_load_lds_dwordx4 v[204:205], off
	v_mfma_f32_16x16x32_bf16 v[70:73], v[220:223], v[240:243], v[70:73]
	v_mfma_f32_16x16x32_bf16 v[66:69], v[232:235], v[240:243], v[66:69]
	s_add_u32 m0, s20, 0xd000
	v_lshl_add_u64 v[206:207], v[198:199], 0, s[0:1]
	global_load_lds_dwordx4 v[206:207], off
	v_mfma_f32_16x16x32_bf16 v[62:65], v[236:239], v[240:243], v[62:65]
	v_mfma_f32_16x16x32_bf16 v[58:61], v[216:219], v[244:247], v[58:61]
	s_add_u32 m0, s20, 0xe000
	v_lshl_add_u64 v[204:205], v[200:201], 0, s[0:1]
	global_load_lds_dwordx4 v[204:205], off
	v_mfma_f32_16x16x32_bf16 v[50:53], v[220:223], v[244:247], v[50:53]
	v_mfma_f32_16x16x32_bf16 v[46:49], v[232:235], v[244:247], v[46:49]
	s_add_u32 m0, s20, 0xf000
	v_lshl_add_u64 v[206:207], v[202:203], 0, s[0:1]
	global_load_lds_dwordx4 v[206:207], off
	v_mfma_f32_16x16x32_bf16 v[42:45], v[236:239], v[244:247], v[42:45]
	s_setprio 0
	s_waitcnt vmcnt(8)
	s_barrier
	s_add_i32 s19, s19, 0x80
	s_add_i32 s18, s18, 2
	s_cmp_lt_u32 s18, 14
	s_cbranch_scc1 .Lglds2_3547
	ds_read_b128 v[152:155], v112 offset:16384
	ds_read_b128 v[156:159], v112 offset:18432
	ds_read_b128 v[160:163], v110
	ds_read_b128 v[164:167], v110 offset:2048
	ds_read_b128 v[168:171], v112 offset:20480
	ds_read_b128 v[172:175], v113 offset:16384
	ds_read_b128 v[208:211], v110 offset:4096
	ds_read_b128 v[212:215], v111
	ds_read_b128 v[216:219], v116 offset:16384
	ds_read_b128 v[220:223], v116 offset:18432
	ds_read_b128 v[224:227], v114
	ds_read_b128 v[228:231], v114 offset:2048
	ds_read_b128 v[232:235], v116 offset:20480
	ds_read_b128 v[236:239], v117 offset:16384
	ds_read_b128 v[240:243], v114 offset:4096
	ds_read_b128 v[244:247], v115
	s_setprio 1
	s_waitcnt lgkmcnt(13)
	v_mfma_f32_16x16x32_bf16 v[94:97], v[152:155], v[160:163], v[94:97]
	v_mfma_f32_16x16x32_bf16 v[90:93], v[156:159], v[160:163], v[90:93]
	s_waitcnt lgkmcnt(11)
	v_mfma_f32_16x16x32_bf16 v[86:89], v[168:171], v[160:163], v[86:89]
	s_waitcnt lgkmcnt(10)
	v_mfma_f32_16x16x32_bf16 v[82:85], v[172:175], v[160:163], v[82:85]
	v_mfma_f32_16x16x32_bf16 v[78:81], v[152:155], v[164:167], v[78:81]
	v_mfma_f32_16x16x32_bf16 v[54:57], v[156:159], v[164:167], v[54:57]
	v_mfma_f32_16x16x32_bf16 v[38:41], v[168:171], v[164:167], v[38:41]
	v_mfma_f32_16x16x32_bf16 v[34:37], v[172:175], v[164:167], v[34:37]
	s_waitcnt lgkmcnt(9)
	v_mfma_f32_16x16x32_bf16 v[74:77], v[152:155], v[208:211], v[74:77]
	v_mfma_f32_16x16x32_bf16 v[70:73], v[156:159], v[208:211], v[70:73]
	v_mfma_f32_16x16x32_bf16 v[66:69], v[168:171], v[208:211], v[66:69]
	v_mfma_f32_16x16x32_bf16 v[62:65], v[172:175], v[208:211], v[62:65]
	s_waitcnt lgkmcnt(8)
	v_mfma_f32_16x16x32_bf16 v[58:61], v[152:155], v[212:215], v[58:61]
	v_mfma_f32_16x16x32_bf16 v[50:53], v[156:159], v[212:215], v[50:53]
	v_mfma_f32_16x16x32_bf16 v[46:49], v[168:171], v[212:215], v[46:49]
	v_mfma_f32_16x16x32_bf16 v[42:45], v[172:175], v[212:215], v[42:45]
	s_setprio 0
	s_waitcnt lgkmcnt(0)
	s_setprio 1
	v_mfma_f32_16x16x32_bf16 v[94:97], v[216:219], v[224:227], v[94:97]
	v_mfma_f32_16x16x32_bf16 v[90:93], v[220:223], v[224:227], v[90:93]
	v_mfma_f32_16x16x32_bf16 v[86:89], v[232:235], v[224:227], v[86:89]
	v_mfma_f32_16x16x32_bf16 v[82:85], v[236:239], v[224:227], v[82:85]
	v_mfma_f32_16x16x32_bf16 v[78:81], v[216:219], v[228:231], v[78:81]
	v_mfma_f32_16x16x32_bf16 v[54:57], v[220:223], v[228:231], v[54:57]
	v_mfma_f32_16x16x32_bf16 v[38:41], v[232:235], v[228:231], v[38:41]
	v_mfma_f32_16x16x32_bf16 v[34:37], v[236:239], v[228:231], v[34:37]
	v_mfma_f32_16x16x32_bf16 v[74:77], v[216:219], v[240:243], v[74:77]
	v_mfma_f32_16x16x32_bf16 v[70:73], v[220:223], v[240:243], v[70:73]
	v_mfma_f32_16x16x32_bf16 v[66:69], v[232:235], v[240:243], v[66:69]
	v_mfma_f32_16x16x32_bf16 v[62:65], v[236:239], v[240:243], v[62:65]
	v_mfma_f32_16x16x32_bf16 v[58:61], v[216:219], v[244:247], v[58:61]
	v_mfma_f32_16x16x32_bf16 v[50:53], v[220:223], v[244:247], v[50:53]
	v_mfma_f32_16x16x32_bf16 v[46:49], v[232:235], v[244:247], v[46:49]
	v_mfma_f32_16x16x32_bf16 v[42:45], v[236:239], v[244:247], v[42:45]
	s_setprio 0
	s_waitcnt vmcnt(0)
	s_barrier
	ds_read_b128 v[152:155], v112 offset:49152
	ds_read_b128 v[156:159], v112 offset:51200
	ds_read_b128 v[160:163], v110 offset:32768
	ds_read_b128 v[164:167], v110 offset:34816
	ds_read_b128 v[168:171], v112 offset:53248
	ds_read_b128 v[172:175], v113 offset:49152
	ds_read_b128 v[208:211], v110 offset:36864
	ds_read_b128 v[212:215], v111 offset:32768
	ds_read_b128 v[216:219], v116 offset:49152
	ds_read_b128 v[220:223], v116 offset:51200
	ds_read_b128 v[224:227], v114 offset:32768
	ds_read_b128 v[228:231], v114 offset:34816
	ds_read_b128 v[232:235], v116 offset:53248
	ds_read_b128 v[236:239], v117 offset:49152
	ds_read_b128 v[240:243], v114 offset:36864
	ds_read_b128 v[244:247], v115 offset:32768
	s_setprio 1
	s_waitcnt lgkmcnt(13)
	v_mfma_f32_16x16x32_bf16 v[94:97], v[152:155], v[160:163], v[94:97]
	v_mfma_f32_16x16x32_bf16 v[90:93], v[156:159], v[160:163], v[90:93]
	s_waitcnt lgkmcnt(11)
	v_mfma_f32_16x16x32_bf16 v[86:89], v[168:171], v[160:163], v[86:89]
	s_waitcnt lgkmcnt(10)
	v_mfma_f32_16x16x32_bf16 v[82:85], v[172:175], v[160:163], v[82:85]
	v_mfma_f32_16x16x32_bf16 v[78:81], v[152:155], v[164:167], v[78:81]
	v_mfma_f32_16x16x32_bf16 v[54:57], v[156:159], v[164:167], v[54:57]
	v_mfma_f32_16x16x32_bf16 v[38:41], v[168:171], v[164:167], v[38:41]
	v_mfma_f32_16x16x32_bf16 v[34:37], v[172:175], v[164:167], v[34:37]
	s_waitcnt lgkmcnt(9)
	v_mfma_f32_16x16x32_bf16 v[74:77], v[152:155], v[208:211], v[74:77]
	v_mfma_f32_16x16x32_bf16 v[70:73], v[156:159], v[208:211], v[70:73]
	v_mfma_f32_16x16x32_bf16 v[66:69], v[168:171], v[208:211], v[66:69]
	v_mfma_f32_16x16x32_bf16 v[62:65], v[172:175], v[208:211], v[62:65]
	s_waitcnt lgkmcnt(8)
	v_mfma_f32_16x16x32_bf16 v[58:61], v[152:155], v[212:215], v[58:61]
	v_mfma_f32_16x16x32_bf16 v[50:53], v[156:159], v[212:215], v[50:53]
	v_mfma_f32_16x16x32_bf16 v[46:49], v[168:171], v[212:215], v[46:49]
	v_mfma_f32_16x16x32_bf16 v[42:45], v[172:175], v[212:215], v[42:45]
	s_setprio 0
	s_waitcnt lgkmcnt(0)
	s_barrier
	s_setprio 1
	v_mfma_f32_16x16x32_bf16 v[94:97], v[216:219], v[224:227], v[94:97]
	v_mfma_f32_16x16x32_bf16 v[90:93], v[220:223], v[224:227], v[90:93]
	v_mfma_f32_16x16x32_bf16 v[86:89], v[232:235], v[224:227], v[86:89]
	v_mfma_f32_16x16x32_bf16 v[82:85], v[236:239], v[224:227], v[82:85]
	v_mfma_f32_16x16x32_bf16 v[78:81], v[216:219], v[228:231], v[78:81]
	v_mfma_f32_16x16x32_bf16 v[54:57], v[220:223], v[228:231], v[54:57]
	v_mfma_f32_16x16x32_bf16 v[38:41], v[232:235], v[228:231], v[38:41]
	v_mfma_f32_16x16x32_bf16 v[34:37], v[236:239], v[228:231], v[34:37]
	v_mfma_f32_16x16x32_bf16 v[74:77], v[216:219], v[240:243], v[74:77]
	v_mfma_f32_16x16x32_bf16 v[70:73], v[220:223], v[240:243], v[70:73]
	v_mfma_f32_16x16x32_bf16 v[66:69], v[232:235], v[240:243], v[66:69]
	v_mfma_f32_16x16x32_bf16 v[62:65], v[236:239], v[240:243], v[62:65]
	v_mfma_f32_16x16x32_bf16 v[58:61], v[216:219], v[244:247], v[58:61]
	v_mfma_f32_16x16x32_bf16 v[50:53], v[220:223], v[244:247], v[50:53]
	v_mfma_f32_16x16x32_bf16 v[46:49], v[232:235], v[244:247], v[46:49]
	v_mfma_f32_16x16x32_bf16 v[42:45], v[236:239], v[244:247], v[42:45]
	s_setprio 0
	s_waitcnt vmcnt(0)
	v_readlane_b32 s36, v254, 40
	s_lshl_b64 s[12:13], s[12:13], 21
	v_readlane_b32 s50, v254, 54
	v_readlane_b32 s51, v254, 55
	s_add_u32 s12, s50, s12
	s_addc_u32 s13, s51, s13
	s_waitcnt vmcnt(7)
	v_or_b32_e32 v4, s17, v119
	v_add_lshl_u32 v98, v118, s16, 10
	v_lshl_add_u64 v[2:3], s[12:13], 0, v[98:99]
	v_lshlrev_b32_e32 v98, 1, v4
	v_lshl_add_u64 v[4:5], v[2:3], 0, v[98:99]
	s_waitcnt vmcnt(6)
	v_cvt_pk_bf16_f32 v6, v94, v95
	v_cvt_pk_bf16_f32 v7, v96, v97
	global_store_dwordx2 v[4:5], v[6:7], off
	v_cvt_pk_bf16_f32 v6, v90, v91
	v_cvt_pk_bf16_f32 v7, v92, v93
	global_store_dwordx2 v[4:5], v[6:7], off offset:32
	v_cvt_pk_bf16_f32 v6, v86, v87
	v_cvt_pk_bf16_f32 v7, v88, v89
	global_store_dwordx2 v[4:5], v[6:7], off offset:64
	v_cvt_pk_bf16_f32 v6, v82, v83
	v_cvt_pk_bf16_f32 v7, v84, v85
	global_store_dwordx2 v[4:5], v[6:7], off offset:96
	v_lshl_add_u64 v[4:5], v[2:3], 0, s[4:5]
	v_lshl_add_u64 v[6:7], v[4:5], 0, v[98:99]
	v_cvt_pk_bf16_f32 v8, v78, v79
	v_cvt_pk_bf16_f32 v9, v80, v81
	global_store_dwordx2 v[6:7], v[8:9], off
	v_or_b32_e32 v6, 32, v98
	v_mov_b32_e32 v7, v99
	v_lshl_add_u64 v[8:9], v[4:5], 0, v[6:7]
	s_waitcnt vmcnt(10)
	v_cvt_pk_bf16_f32 v10, v54, v55
	v_cvt_pk_bf16_f32 v11, v56, v57
	global_store_dwordx2 v[8:9], v[10:11], off
	v_or_b32_e32 v8, 64, v98
	v_mov_b32_e32 v9, v99
	v_lshl_add_u64 v[10:11], v[4:5], 0, v[8:9]
	v_cvt_pk_bf16_f32 v12, v38, v39
	v_cvt_pk_bf16_f32 v13, v40, v41
	global_store_dwordx2 v[10:11], v[12:13], off
	v_or_b32_e32 v10, 0x60, v98
	v_mov_b32_e32 v11, v99
	v_lshl_add_u64 v[4:5], v[4:5], 0, v[10:11]
	v_cvt_pk_bf16_f32 v12, v34, v35
	v_cvt_pk_bf16_f32 v13, v36, v37
	global_store_dwordx2 v[4:5], v[12:13], off
	v_lshl_add_u64 v[4:5], v[2:3], 0, s[6:7]
	v_lshl_add_u64 v[12:13], v[4:5], 0, v[98:99]
	s_waitcnt vmcnt(11)
	v_cvt_pk_bf16_f32 v14, v74, v75
	v_cvt_pk_bf16_f32 v15, v76, v77
	global_store_dwordx2 v[12:13], v[14:15], off
	v_lshl_add_u64 v[12:13], v[4:5], 0, v[6:7]
	v_cvt_pk_bf16_f32 v14, v70, v71
	v_cvt_pk_bf16_f32 v15, v72, v73
	global_store_dwordx2 v[12:13], v[14:15], off
	v_lshl_add_u64 v[12:13], v[4:5], 0, v[8:9]
	v_cvt_pk_bf16_f32 v14, v66, v67
	v_cvt_pk_bf16_f32 v15, v68, v69
	global_store_dwordx2 v[12:13], v[14:15], off
	v_lshl_add_u64 v[4:5], v[4:5], 0, v[10:11]
	v_cvt_pk_bf16_f32 v12, v62, v63
	v_cvt_pk_bf16_f32 v13, v64, v65
	v_lshl_add_u64 v[2:3], v[2:3], 0, s[8:9]
	global_store_dwordx2 v[4:5], v[12:13], off
	v_lshl_add_u64 v[4:5], v[2:3], 0, v[98:99]
	v_cvt_pk_bf16_f32 v12, v58, v59
	v_cvt_pk_bf16_f32 v13, v60, v61
	global_store_dwordx2 v[4:5], v[12:13], off
	v_lshl_add_u64 v[4:5], v[2:3], 0, v[6:7]
	v_cvt_pk_bf16_f32 v6, v50, v51
	v_cvt_pk_bf16_f32 v7, v52, v53
	v_readlane_b32 s12, v254, 0
	global_store_dwordx2 v[4:5], v[6:7], off
	v_lshl_add_u64 v[4:5], v[2:3], 0, v[8:9]
	v_cvt_pk_bf16_f32 v6, v46, v47
	v_cvt_pk_bf16_f32 v7, v48, v49
	s_add_i32 s2, s2, s12
	v_readlane_b32 s37, v254, 41
	global_store_dwordx2 v[4:5], v[6:7], off
	v_lshl_add_u64 v[2:3], v[2:3], 0, v[10:11]
	v_cvt_pk_bf16_f32 v4, v42, v43
	v_cvt_pk_bf16_f32 v5, v44, v45
	s_cmpk_lt_i32 s2, 0x80
	v_readlane_b32 s38, v254, 42
	v_readlane_b32 s39, v254, 43
	v_readlane_b32 s40, v254, 44
	v_readlane_b32 s41, v254, 45
	v_readlane_b32 s42, v254, 46
	v_readlane_b32 s43, v254, 47
	v_readlane_b32 s44, v254, 48
	v_readlane_b32 s45, v254, 49
	v_readlane_b32 s46, v254, 50
	v_readlane_b32 s47, v254, 51
	v_readlane_b32 s48, v254, 52
	v_readlane_b32 s49, v254, 53
	v_readlane_b32 s13, v254, 1
	global_store_dwordx2 v[2:3], v[4:5], off
	s_cbranch_scc1 .LBB0_220

.LBB0_422:
	s_and_b32 s4, s7, 0xf8
	s_or_b32 s4, s4, s2
	s_lshl_b32 s11, s4, 7
	s_lshl_b32 s4, s7, 7
	v_or_b32_e32 v2, s11, v1
	s_and_b32 s12, s4, 0x380
	v_lshlrev_b32_e32 v98, 11, v2
	v_lshl_add_u64 v[104:105], v[102:103], 0, v[98:99]
	v_or_b32_e32 v2, s12, v1
	v_lshlrev_b32_e32 v98, 11, v2
	v_lshl_add_u64 v[108:109], v[100:101], 0, v[98:99]
	v_and_b32_e32 v177, 7, v106
	v_bfe_u32 v176, v106, 3, 3
	v_xor_b32_e32 v176, v177, v176
	v_sub_u32_e32 v176, v176, v177
	v_lshlrev_b32_e32 v176, 4, v176
	v_ashrrev_i32_e32 v177, 31, v176
	v_lshrrev_b32_e32 v182, 6, v106
	v_mov_b32_e32 v183, 0x110
	v_lshl_add_u32 v182, v182, 10, v183
	v_lshl_add_u64 v[184:185], v[104:105], 0, v[176:177]
	v_lshl_add_u64 v[192:193], v[108:109], 0, v[176:177]
	v_readfirstlane_b32 s15, v182
	v_add_co_u32_e32 v186, vcc, s8, v184
	v_addc_co_u32_e32 v187, vcc, 0, v185, vcc
	v_add_co_u32_e32 v188, vcc, s9, v184
	v_addc_co_u32_e32 v189, vcc, 0, v185, vcc
	v_add_co_u32_e32 v190, vcc, s10, v184
	v_addc_co_u32_e32 v191, vcc, 0, v185, vcc
	v_add_co_u32_e32 v194, vcc, s8, v192
	v_addc_co_u32_e32 v195, vcc, 0, v193, vcc
	v_add_co_u32_e32 v196, vcc, s9, v192
	v_addc_co_u32_e32 v197, vcc, 0, v193, vcc
	v_add_co_u32_e32 v198, vcc, s10, v192
	v_addc_co_u32_e32 v199, vcc, 0, v193, vcc
	v_mov_b32_e32 v30, 0
	v_mov_b32_e32 v31, v99
	v_mov_b32_e32 v32, v99
	v_mov_b32_e32 v33, v99
	v_mov_b32_e32 v62, 0
	v_mov_b32_e32 v63, v99
	v_mov_b32_e32 v64, v99
	v_mov_b32_e32 v65, v99
	v_mov_b32_e32 v74, 0
	v_mov_b32_e32 v75, v99
	v_mov_b32_e32 v76, v99
	v_mov_b32_e32 v77, v99
	v_mov_b32_e32 v78, 0
	v_mov_b32_e32 v79, v99
	v_mov_b32_e32 v80, v99
	v_mov_b32_e32 v81, v99
	v_mov_b32_e32 v82, 0
	v_mov_b32_e32 v83, v99
	v_mov_b32_e32 v84, v99
	v_mov_b32_e32 v85, v99
	v_mov_b32_e32 v86, 0
	v_mov_b32_e32 v87, v99
	v_mov_b32_e32 v88, v99
	v_mov_b32_e32 v89, v99
	v_mov_b32_e32 v90, 0
	v_mov_b32_e32 v91, v99
	v_mov_b32_e32 v92, v99
	v_mov_b32_e32 v93, v99
	v_mov_b32_e32 v94, 0
	v_mov_b32_e32 v95, v99
	v_mov_b32_e32 v96, v99
	v_mov_b32_e32 v97, v99
	v_mov_b32_e32 v66, 0
	v_mov_b32_e32 v67, v99
	v_mov_b32_e32 v68, v99
	v_mov_b32_e32 v69, v99
	v_mov_b32_e32 v38, 0
	v_mov_b32_e32 v39, v99
	v_mov_b32_e32 v40, v99
	v_mov_b32_e32 v41, v99
	v_mov_b32_e32 v34, 0
	v_mov_b32_e32 v35, v99
	v_mov_b32_e32 v36, v99
	v_mov_b32_e32 v37, v99
	v_mov_b32_e32 v18, 0
	v_mov_b32_e32 v19, v99
	v_mov_b32_e32 v20, v99
	v_mov_b32_e32 v21, v99
	v_mov_b32_e32 v14, 0
	v_mov_b32_e32 v15, v99
	v_mov_b32_e32 v16, v99
	v_mov_b32_e32 v17, v99
	v_mov_b32_e32 v10, 0
	v_mov_b32_e32 v11, v99
	v_mov_b32_e32 v12, v99
	v_mov_b32_e32 v13, v99
	v_mov_b32_e32 v6, 0
	v_mov_b32_e32 v7, v99
	v_mov_b32_e32 v8, v99
	v_mov_b32_e32 v9, v99
	v_mov_b32_e32 v2, 0
	v_mov_b32_e32 v3, v99
	v_mov_b32_e32 v4, v99
	v_mov_b32_e32 v5, v99
	s_add_u32 m0, s15, 0x0
	s_nop 0
	global_load_lds_dwordx4 v[184:185], off
	s_add_u32 m0, s15, 0x1000
	s_nop 0
	global_load_lds_dwordx4 v[186:187], off
	s_add_u32 m0, s15, 0x2000
	s_nop 0
	global_load_lds_dwordx4 v[188:189], off
	s_add_u32 m0, s15, 0x3000
	s_nop 0
	global_load_lds_dwordx4 v[190:191], off
	s_add_u32 m0, s15, 0x4000
	s_nop 0
	global_load_lds_dwordx4 v[192:193], off
	s_add_u32 m0, s15, 0x5000
	s_nop 0
	global_load_lds_dwordx4 v[194:195], off
	s_add_u32 m0, s15, 0x6000
	s_nop 0
	global_load_lds_dwordx4 v[196:197], off
	s_add_u32 m0, s15, 0x7000
	s_nop 0
	global_load_lds_dwordx4 v[198:199], off
	s_mov_b32 s4, 0x80
	s_add_u32 m0, s15, 0x8000
	v_lshl_add_u64 v[200:201], v[184:185], 0, s[4:5]
	global_load_lds_dwordx4 v[200:201], off
	s_add_u32 m0, s15, 0x9000
	v_lshl_add_u64 v[202:203], v[186:187], 0, s[4:5]
	global_load_lds_dwordx4 v[202:203], off
	s_add_u32 m0, s15, 0xa000
	v_lshl_add_u64 v[200:201], v[188:189], 0, s[4:5]
	global_load_lds_dwordx4 v[200:201], off
	s_add_u32 m0, s15, 0xb000
	v_lshl_add_u64 v[202:203], v[190:191], 0, s[4:5]
	global_load_lds_dwordx4 v[202:203], off
	s_add_u32 m0, s15, 0xc000
	v_lshl_add_u64 v[200:201], v[192:193], 0, s[4:5]
	global_load_lds_dwordx4 v[200:201], off
	s_add_u32 m0, s15, 0xd000
	v_lshl_add_u64 v[202:203], v[194:195], 0, s[4:5]
	global_load_lds_dwordx4 v[202:203], off
	s_add_u32 m0, s15, 0xe000
	v_lshl_add_u64 v[200:201], v[196:197], 0, s[4:5]
	global_load_lds_dwordx4 v[200:201], off
	s_add_u32 m0, s15, 0xf000
	v_lshl_add_u64 v[202:203], v[198:199], 0, s[4:5]
	global_load_lds_dwordx4 v[202:203], off
	s_mov_b32 s14, 0
	s_mov_b32 s13, 0
	s_waitcnt vmcnt(8)
	s_barrier
.Lglds2_12468:
	ds_read_b128 v[152:155], v112 offset:16384
	ds_read_b128 v[156:159], v112 offset:18432
	ds_read_b128 v[160:163], v110
	ds_read_b128 v[164:167], v110 offset:2048
	ds_read_b128 v[168:171], v112 offset:20480
	ds_read_b128 v[172:175], v113 offset:16384
	ds_read_b128 v[204:207], v110 offset:4096
	ds_read_b128 v[208:211], v111
	ds_read_b128 v[212:215], v116 offset:16384
	ds_read_b128 v[216:219], v116 offset:18432
	ds_read_b128 v[220:223], v114
	ds_read_b128 v[224:227], v114 offset:2048
	ds_read_b128 v[228:231], v116 offset:20480
	ds_read_b128 v[232:235], v117 offset:16384
	ds_read_b128 v[236:239], v114 offset:4096
	ds_read_b128 v[240:243], v115
	s_setprio 1
	s_waitcnt lgkmcnt(13)
	v_mfma_f32_16x16x32_bf16 v[94:97], v[152:155], v[160:163], v[94:97]
	v_mfma_f32_16x16x32_bf16 v[90:93], v[156:159], v[160:163], v[90:93]
	s_waitcnt lgkmcnt(11)
	v_mfma_f32_16x16x32_bf16 v[86:89], v[168:171], v[160:163], v[86:89]
	s_waitcnt lgkmcnt(10)
	v_mfma_f32_16x16x32_bf16 v[82:85], v[172:175], v[160:163], v[82:85]
	v_mfma_f32_16x16x32_bf16 v[78:81], v[152:155], v[164:167], v[78:81]
	v_mfma_f32_16x16x32_bf16 v[74:77], v[156:159], v[164:167], v[74:77]
	v_mfma_f32_16x16x32_bf16 v[62:65], v[168:171], v[164:167], v[62:65]
	v_mfma_f32_16x16x32_bf16 v[30:33], v[172:175], v[164:167], v[30:33]
	s_waitcnt lgkmcnt(9)
	v_mfma_f32_16x16x32_bf16 v[66:69], v[152:155], v[204:207], v[66:69]
	v_mfma_f32_16x16x32_bf16 v[38:41], v[156:159], v[204:207], v[38:41]
	v_mfma_f32_16x16x32_bf16 v[34:37], v[168:171], v[204:207], v[34:37]
	v_mfma_f32_16x16x32_bf16 v[18:21], v[172:175], v[204:207], v[18:21]
	s_waitcnt lgkmcnt(8)
	v_mfma_f32_16x16x32_bf16 v[14:17], v[152:155], v[208:211], v[14:17]
	v_mfma_f32_16x16x32_bf16 v[10:13], v[156:159], v[208:211], v[10:13]
	v_mfma_f32_16x16x32_bf16 v[6:9], v[168:171], v[208:211], v[6:9]
	v_mfma_f32_16x16x32_bf16 v[2:5], v[172:175], v[208:211], v[2:5]
	s_setprio 0
	s_waitcnt lgkmcnt(0)
	s_barrier
	s_add_i32 s4, s14, 0x80
	s_min_u32 s4, s4, 0x3c0
	s_lshl_b32 s4, s4, 1
	s_setprio 1
	v_mfma_f32_16x16x32_bf16 v[94:97], v[212:215], v[220:223], v[94:97]
	s_add_u32 m0, s15, 0x0
	v_lshl_add_u64 v[200:201], v[184:185], 0, s[4:5]
	global_load_lds_dwordx4 v[200:201], off
	v_mfma_f32_16x16x32_bf16 v[90:93], v[216:219], v[220:223], v[90:93]
	v_mfma_f32_16x16x32_bf16 v[86:89], v[228:231], v[220:223], v[86:89]
	s_add_u32 m0, s15, 0x1000
	v_lshl_add_u64 v[202:203], v[186:187], 0, s[4:5]
	global_load_lds_dwordx4 v[202:203], off
	v_mfma_f32_16x16x32_bf16 v[82:85], v[232:235], v[220:223], v[82:85]
	v_mfma_f32_16x16x32_bf16 v[78:81], v[212:215], v[224:227], v[78:81]
	s_add_u32 m0, s15, 0x2000
	v_lshl_add_u64 v[200:201], v[188:189], 0, s[4:5]
	global_load_lds_dwordx4 v[200:201], off
	v_mfma_f32_16x16x32_bf16 v[74:77], v[216:219], v[224:227], v[74:77]
	v_mfma_f32_16x16x32_bf16 v[62:65], v[228:231], v[224:227], v[62:65]
	s_add_u32 m0, s15, 0x3000
	v_lshl_add_u64 v[202:203], v[190:191], 0, s[4:5]
	global_load_lds_dwordx4 v[202:203], off
	v_mfma_f32_16x16x32_bf16 v[30:33], v[232:235], v[224:227], v[30:33]
	v_mfma_f32_16x16x32_bf16 v[66:69], v[212:215], v[236:239], v[66:69]
	s_add_u32 m0, s15, 0x4000
	v_lshl_add_u64 v[200:201], v[192:193], 0, s[4:5]
	global_load_lds_dwordx4 v[200:201], off
	v_mfma_f32_16x16x32_bf16 v[38:41], v[216:219], v[236:239], v[38:41]
	v_mfma_f32_16x16x32_bf16 v[34:37], v[228:231], v[236:239], v[34:37]
	s_add_u32 m0, s15, 0x5000
	v_lshl_add_u64 v[202:203], v[194:195], 0, s[4:5]
	global_load_lds_dwordx4 v[202:203], off
	v_mfma_f32_16x16x32_bf16 v[18:21], v[232:235], v[236:239], v[18:21]
	v_mfma_f32_16x16x32_bf16 v[14:17], v[212:215], v[240:243], v[14:17]
	s_add_u32 m0, s15, 0x6000
	v_lshl_add_u64 v[200:201], v[196:197], 0, s[4:5]
	global_load_lds_dwordx4 v[200:201], off
	v_mfma_f32_16x16x32_bf16 v[10:13], v[216:219], v[240:243], v[10:13]
	v_mfma_f32_16x16x32_bf16 v[6:9], v[228:231], v[240:243], v[6:9]
	s_add_u32 m0, s15, 0x7000
	v_lshl_add_u64 v[202:203], v[198:199], 0, s[4:5]
	global_load_lds_dwordx4 v[202:203], off
	v_mfma_f32_16x16x32_bf16 v[2:5], v[232:235], v[240:243], v[2:5]
	s_setprio 0
	s_waitcnt vmcnt(8)
	s_barrier
	ds_read_b128 v[152:155], v112 offset:49152
	ds_read_b128 v[156:159], v112 offset:51200
	ds_read_b128 v[160:163], v110 offset:32768
	ds_read_b128 v[164:167], v110 offset:34816
	ds_read_b128 v[168:171], v112 offset:53248
	ds_read_b128 v[172:175], v113 offset:49152
	ds_read_b128 v[204:207], v110 offset:36864
	ds_read_b128 v[208:211], v111 offset:32768
	ds_read_b128 v[212:215], v116 offset:49152
	ds_read_b128 v[216:219], v116 offset:51200
	ds_read_b128 v[220:223], v114 offset:32768
	ds_read_b128 v[224:227], v114 offset:34816
	ds_read_b128 v[228:231], v116 offset:53248
	ds_read_b128 v[232:235], v117 offset:49152
	ds_read_b128 v[236:239], v114 offset:36864
	ds_read_b128 v[240:243], v115 offset:32768
	s_setprio 1
	s_waitcnt lgkmcnt(13)
	v_mfma_f32_16x16x32_bf16 v[94:97], v[152:155], v[160:163], v[94:97]
	v_mfma_f32_16x16x32_bf16 v[90:93], v[156:159], v[160:163], v[90:93]
	s_waitcnt lgkmcnt(11)
	v_mfma_f32_16x16x32_bf16 v[86:89], v[168:171], v[160:163], v[86:89]
	s_waitcnt lgkmcnt(10)
	v_mfma_f32_16x16x32_bf16 v[82:85], v[172:175], v[160:163], v[82:85]
	v_mfma_f32_16x16x32_bf16 v[78:81], v[152:155], v[164:167], v[78:81]
	v_mfma_f32_16x16x32_bf16 v[74:77], v[156:159], v[164:167], v[74:77]
	v_mfma_f32_16x16x32_bf16 v[62:65], v[168:171], v[164:167], v[62:65]
	v_mfma_f32_16x16x32_bf16 v[30:33], v[172:175], v[164:167], v[30:33]
	s_waitcnt lgkmcnt(9)
	v_mfma_f32_16x16x32_bf16 v[66:69], v[152:155], v[204:207], v[66:69]
	v_mfma_f32_16x16x32_bf16 v[38:41], v[156:159], v[204:207], v[38:41]
	v_mfma_f32_16x16x32_bf16 v[34:37], v[168:171], v[204:207], v[34:37]
	v_mfma_f32_16x16x32_bf16 v[18:21], v[172:175], v[204:207], v[18:21]
	s_waitcnt lgkmcnt(8)
	v_mfma_f32_16x16x32_bf16 v[14:17], v[152:155], v[208:211], v[14:17]
	v_mfma_f32_16x16x32_bf16 v[10:13], v[156:159], v[208:211], v[10:13]
	v_mfma_f32_16x16x32_bf16 v[6:9], v[168:171], v[208:211], v[6:9]
	v_mfma_f32_16x16x32_bf16 v[2:5], v[172:175], v[208:211], v[2:5]
	s_setprio 0
	s_waitcnt lgkmcnt(0)
	s_barrier
	s_add_i32 s4, s14, 0xc0
	s_min_u32 s4, s4, 0x3c0
	s_lshl_b32 s4, s4, 1
	s_setprio 1
	v_mfma_f32_16x16x32_bf16 v[94:97], v[212:215], v[220:223], v[94:97]
	s_add_u32 m0, s15, 0x8000
	v_lshl_add_u64 v[200:201], v[184:185], 0, s[4:5]
	global_load_lds_dwordx4 v[200:201], off
	v_mfma_f32_16x16x32_bf16 v[90:93], v[216:219], v[220:223], v[90:93]
	v_mfma_f32_16x16x32_bf16 v[86:89], v[228:231], v[220:223], v[86:89]
	s_add_u32 m0, s15, 0x9000
	v_lshl_add_u64 v[202:203], v[186:187], 0, s[4:5]
	global_load_lds_dwordx4 v[202:203], off
	v_mfma_f32_16x16x32_bf16 v[82:85], v[232:235], v[220:223], v[82:85]
	v_mfma_f32_16x16x32_bf16 v[78:81], v[212:215], v[224:227], v[78:81]
	s_add_u32 m0, s15, 0xa000
	v_lshl_add_u64 v[200:201], v[188:189], 0, s[4:5]
	global_load_lds_dwordx4 v[200:201], off
	v_mfma_f32_16x16x32_bf16 v[74:77], v[216:219], v[224:227], v[74:77]
	v_mfma_f32_16x16x32_bf16 v[62:65], v[228:231], v[224:227], v[62:65]
	s_add_u32 m0, s15, 0xb000
	v_lshl_add_u64 v[202:203], v[190:191], 0, s[4:5]
	global_load_lds_dwordx4 v[202:203], off
	v_mfma_f32_16x16x32_bf16 v[30:33], v[232:235], v[224:227], v[30:33]
	v_mfma_f32_16x16x32_bf16 v[66:69], v[212:215], v[236:239], v[66:69]
	s_add_u32 m0, s15, 0xc000
	v_lshl_add_u64 v[200:201], v[192:193], 0, s[4:5]
	global_load_lds_dwordx4 v[200:201], off
	v_mfma_f32_16x16x32_bf16 v[38:41], v[216:219], v[236:239], v[38:41]
	v_mfma_f32_16x16x32_bf16 v[34:37], v[228:231], v[236:239], v[34:37]
	s_add_u32 m0, s15, 0xd000
	v_lshl_add_u64 v[202:203], v[194:195], 0, s[4:5]
	global_load_lds_dwordx4 v[202:203], off
	v_mfma_f32_16x16x32_bf16 v[18:21], v[232:235], v[236:239], v[18:21]
	v_mfma_f32_16x16x32_bf16 v[14:17], v[212:215], v[240:243], v[14:17]
	s_add_u32 m0, s15, 0xe000
	v_lshl_add_u64 v[200:201], v[196:197], 0, s[4:5]
	global_load_lds_dwordx4 v[200:201], off
	v_mfma_f32_16x16x32_bf16 v[10:13], v[216:219], v[240:243], v[10:13]
	v_mfma_f32_16x16x32_bf16 v[6:9], v[228:231], v[240:243], v[6:9]
	s_add_u32 m0, s15, 0xf000
	v_lshl_add_u64 v[202:203], v[198:199], 0, s[4:5]
	global_load_lds_dwordx4 v[202:203], off
	v_mfma_f32_16x16x32_bf16 v[2:5], v[232:235], v[240:243], v[2:5]
	s_setprio 0
	s_waitcnt vmcnt(8)
	s_barrier
	s_add_i32 s14, s14, 0x80
	s_add_i32 s13, s13, 2
	s_cmp_lt_u32 s13, 14
	s_cbranch_scc1 .Lglds2_12468
	ds_read_b128 v[152:155], v112 offset:16384
	ds_read_b128 v[156:159], v112 offset:18432
	ds_read_b128 v[160:163], v110
	ds_read_b128 v[164:167], v110 offset:2048
	ds_read_b128 v[168:171], v112 offset:20480
	ds_read_b128 v[172:175], v113 offset:16384
	ds_read_b128 v[204:207], v110 offset:4096
	ds_read_b128 v[208:211], v111
	ds_read_b128 v[212:215], v116 offset:16384
	ds_read_b128 v[216:219], v116 offset:18432
	ds_read_b128 v[220:223], v114
	ds_read_b128 v[224:227], v114 offset:2048
	ds_read_b128 v[228:231], v116 offset:20480
	ds_read_b128 v[232:235], v117 offset:16384
	ds_read_b128 v[236:239], v114 offset:4096
	ds_read_b128 v[240:243], v115
	s_setprio 1
	s_waitcnt lgkmcnt(13)
	v_mfma_f32_16x16x32_bf16 v[94:97], v[152:155], v[160:163], v[94:97]
	v_mfma_f32_16x16x32_bf16 v[90:93], v[156:159], v[160:163], v[90:93]
	s_waitcnt lgkmcnt(11)
	v_mfma_f32_16x16x32_bf16 v[86:89], v[168:171], v[160:163], v[86:89]
	s_waitcnt lgkmcnt(10)
	v_mfma_f32_16x16x32_bf16 v[82:85], v[172:175], v[160:163], v[82:85]
	v_mfma_f32_16x16x32_bf16 v[78:81], v[152:155], v[164:167], v[78:81]
	v_mfma_f32_16x16x32_bf16 v[74:77], v[156:159], v[164:167], v[74:77]
	v_mfma_f32_16x16x32_bf16 v[62:65], v[168:171], v[164:167], v[62:65]
	v_mfma_f32_16x16x32_bf16 v[30:33], v[172:175], v[164:167], v[30:33]
	s_waitcnt lgkmcnt(9)
	v_mfma_f32_16x16x32_bf16 v[66:69], v[152:155], v[204:207], v[66:69]
	v_mfma_f32_16x16x32_bf16 v[38:41], v[156:159], v[204:207], v[38:41]
	v_mfma_f32_16x16x32_bf16 v[34:37], v[168:171], v[204:207], v[34:37]
	v_mfma_f32_16x16x32_bf16 v[18:21], v[172:175], v[204:207], v[18:21]
	s_waitcnt lgkmcnt(8)
	v_mfma_f32_16x16x32_bf16 v[14:17], v[152:155], v[208:211], v[14:17]
	v_mfma_f32_16x16x32_bf16 v[10:13], v[156:159], v[208:211], v[10:13]
	v_mfma_f32_16x16x32_bf16 v[6:9], v[168:171], v[208:211], v[6:9]
	v_mfma_f32_16x16x32_bf16 v[2:5], v[172:175], v[208:211], v[2:5]
	s_setprio 0
	s_waitcnt lgkmcnt(0)
	s_setprio 1
	v_mfma_f32_16x16x32_bf16 v[94:97], v[212:215], v[220:223], v[94:97]
	v_mfma_f32_16x16x32_bf16 v[90:93], v[216:219], v[220:223], v[90:93]
	v_mfma_f32_16x16x32_bf16 v[86:89], v[228:231], v[220:223], v[86:89]
	v_mfma_f32_16x16x32_bf16 v[82:85], v[232:235], v[220:223], v[82:85]
	v_mfma_f32_16x16x32_bf16 v[78:81], v[212:215], v[224:227], v[78:81]
	v_mfma_f32_16x16x32_bf16 v[74:77], v[216:219], v[224:227], v[74:77]
	v_mfma_f32_16x16x32_bf16 v[62:65], v[228:231], v[224:227], v[62:65]
	v_mfma_f32_16x16x32_bf16 v[30:33], v[232:235], v[224:227], v[30:33]
	v_mfma_f32_16x16x32_bf16 v[66:69], v[212:215], v[236:239], v[66:69]
	v_mfma_f32_16x16x32_bf16 v[38:41], v[216:219], v[236:239], v[38:41]
	v_mfma_f32_16x16x32_bf16 v[34:37], v[228:231], v[236:239], v[34:37]
	v_mfma_f32_16x16x32_bf16 v[18:21], v[232:235], v[236:239], v[18:21]
	v_mfma_f32_16x16x32_bf16 v[14:17], v[212:215], v[240:243], v[14:17]
	v_mfma_f32_16x16x32_bf16 v[10:13], v[216:219], v[240:243], v[10:13]
	v_mfma_f32_16x16x32_bf16 v[6:9], v[228:231], v[240:243], v[6:9]
	v_mfma_f32_16x16x32_bf16 v[2:5], v[232:235], v[240:243], v[2:5]
	s_setprio 0
	s_waitcnt vmcnt(0)
	s_barrier
	ds_read_b128 v[152:155], v112 offset:49152
	ds_read_b128 v[156:159], v112 offset:51200
	ds_read_b128 v[160:163], v110 offset:32768
	ds_read_b128 v[164:167], v110 offset:34816
	ds_read_b128 v[168:171], v112 offset:53248
	ds_read_b128 v[172:175], v113 offset:49152
	ds_read_b128 v[204:207], v110 offset:36864
	ds_read_b128 v[208:211], v111 offset:32768
	ds_read_b128 v[212:215], v116 offset:49152
	ds_read_b128 v[216:219], v116 offset:51200
	ds_read_b128 v[220:223], v114 offset:32768
	ds_read_b128 v[224:227], v114 offset:34816
	ds_read_b128 v[228:231], v116 offset:53248
	ds_read_b128 v[232:235], v117 offset:49152
	ds_read_b128 v[236:239], v114 offset:36864
	ds_read_b128 v[240:243], v115 offset:32768
	s_setprio 1
	s_waitcnt lgkmcnt(13)
	v_mfma_f32_16x16x32_bf16 v[94:97], v[152:155], v[160:163], v[94:97]
	v_mfma_f32_16x16x32_bf16 v[90:93], v[156:159], v[160:163], v[90:93]
	s_waitcnt lgkmcnt(11)
	v_mfma_f32_16x16x32_bf16 v[86:89], v[168:171], v[160:163], v[86:89]
	s_waitcnt lgkmcnt(10)
	v_mfma_f32_16x16x32_bf16 v[82:85], v[172:175], v[160:163], v[82:85]
	v_mfma_f32_16x16x32_bf16 v[78:81], v[152:155], v[164:167], v[78:81]
	v_mfma_f32_16x16x32_bf16 v[74:77], v[156:159], v[164:167], v[74:77]
	v_mfma_f32_16x16x32_bf16 v[62:65], v[168:171], v[164:167], v[62:65]
	v_mfma_f32_16x16x32_bf16 v[30:33], v[172:175], v[164:167], v[30:33]
	s_waitcnt lgkmcnt(9)
	v_mfma_f32_16x16x32_bf16 v[66:69], v[152:155], v[204:207], v[66:69]
	v_mfma_f32_16x16x32_bf16 v[38:41], v[156:159], v[204:207], v[38:41]
	v_mfma_f32_16x16x32_bf16 v[34:37], v[168:171], v[204:207], v[34:37]
	v_mfma_f32_16x16x32_bf16 v[18:21], v[172:175], v[204:207], v[18:21]
	s_waitcnt lgkmcnt(8)
	v_mfma_f32_16x16x32_bf16 v[14:17], v[152:155], v[208:211], v[14:17]
	v_mfma_f32_16x16x32_bf16 v[10:13], v[156:159], v[208:211], v[10:13]
	v_mfma_f32_16x16x32_bf16 v[6:9], v[168:171], v[208:211], v[6:9]
	v_mfma_f32_16x16x32_bf16 v[2:5], v[172:175], v[208:211], v[2:5]
	s_setprio 0
	s_waitcnt lgkmcnt(0)
	s_barrier
	s_setprio 1
	v_mfma_f32_16x16x32_bf16 v[94:97], v[212:215], v[220:223], v[94:97]
	v_mfma_f32_16x16x32_bf16 v[90:93], v[216:219], v[220:223], v[90:93]
	v_mfma_f32_16x16x32_bf16 v[86:89], v[228:231], v[220:223], v[86:89]
	v_mfma_f32_16x16x32_bf16 v[82:85], v[232:235], v[220:223], v[82:85]
	v_mfma_f32_16x16x32_bf16 v[78:81], v[212:215], v[224:227], v[78:81]
	v_mfma_f32_16x16x32_bf16 v[74:77], v[216:219], v[224:227], v[74:77]
	v_mfma_f32_16x16x32_bf16 v[62:65], v[228:231], v[224:227], v[62:65]
	v_mfma_f32_16x16x32_bf16 v[30:33], v[232:235], v[224:227], v[30:33]
	v_mfma_f32_16x16x32_bf16 v[66:69], v[212:215], v[236:239], v[66:69]
	v_mfma_f32_16x16x32_bf16 v[38:41], v[216:219], v[236:239], v[38:41]
	v_mfma_f32_16x16x32_bf16 v[34:37], v[228:231], v[236:239], v[34:37]
	v_mfma_f32_16x16x32_bf16 v[18:21], v[232:235], v[236:239], v[18:21]
	v_mfma_f32_16x16x32_bf16 v[14:17], v[212:215], v[240:243], v[14:17]
	v_mfma_f32_16x16x32_bf16 v[10:13], v[216:219], v[240:243], v[10:13]
	v_mfma_f32_16x16x32_bf16 v[6:9], v[228:231], v[240:243], v[6:9]
	v_mfma_f32_16x16x32_bf16 v[2:5], v[232:235], v[240:243], v[2:5]
	s_setprio 0
	s_waitcnt vmcnt(0)
	s_waitcnt vmcnt(0)
	v_or_b32_e32 v170, s12, v119
	v_add_lshl_u32 v98, v118, s11, 10
	v_readlane_b32 s12, v254, 8
	v_readlane_b32 s13, v254, 9
	v_readlane_b32 s14, v254, 10
	v_readlane_b32 s15, v254, 11
	v_readlane_b32 s16, v254, 12
	v_readlane_b32 s17, v254, 13
	v_readlane_b32 s18, v254, 14
	v_readlane_b32 s19, v254, 15
	v_readlane_b32 s20, v254, 16
	v_readlane_b32 s21, v254, 17
	v_readlane_b32 s22, v254, 18
	v_readlane_b32 s23, v254, 19
	v_readlane_b32 s24, v254, 20
	v_readlane_b32 s25, v254, 21
	v_readlane_b32 s26, v254, 22
	v_readlane_b32 s27, v254, 23
	v_lshlrev_b32_e32 v168, 2, v170
	v_mov_b32_e32 v169, v99
	v_lshlrev_b64 v[174:175], 2, v[98:99]
	v_lshl_add_u64 v[152:153], s[12:13], 0, v[174:175]
	v_lshl_add_u64 v[160:161], s[82:83], 0, v[174:175]
	v_lshl_add_u64 v[152:153], v[152:153], 0, v[168:169]
	v_lshl_add_u64 v[160:161], v[160:161], 0, v[168:169]
	global_load_dwordx4 v[120:123], v[152:153], off
	global_load_dwordx4 v[124:127], v[152:153], off offset:64
	global_load_dwordx4 v[128:131], v[152:153], off offset:128
	global_load_dwordx4 v[132:135], v[152:153], off offset:192
	v_or_b32_e32 v172, 0x4000, v98
	v_mov_b32_e32 v173, v99
	v_lshlrev_b64 v[174:175], 2, v[172:173]
	v_lshl_add_u64 v[154:155], s[12:13], 0, v[174:175]
	v_lshl_add_u64 v[162:163], s[82:83], 0, v[174:175]
	v_lshl_add_u64 v[154:155], v[154:155], 0, v[168:169]
	v_lshl_add_u64 v[162:163], v[162:163], 0, v[168:169]
	global_load_dwordx4 v[136:139], v[154:155], off
	global_load_dwordx4 v[140:143], v[154:155], off offset:64
	global_load_dwordx4 v[144:147], v[154:155], off offset:128
	global_load_dwordx4 v[148:151], v[154:155], off offset:192
	v_or_b32_e32 v172, 0x8000, v98
	v_mov_b32_e32 v173, v99
	v_lshlrev_b64 v[174:175], 2, v[172:173]
	v_lshl_add_u64 v[156:157], s[12:13], 0, v[174:175]
	v_lshl_add_u64 v[164:165], s[82:83], 0, v[174:175]
	v_lshl_add_u64 v[156:157], v[156:157], 0, v[168:169]
	v_lshl_add_u64 v[164:165], v[164:165], 0, v[168:169]
	global_load_dwordx4 v[22:25], v[156:157], off
	global_load_dwordx4 v[26:29], v[156:157], off offset:64
	global_load_dwordx4 v[42:45], v[156:157], off offset:128
	global_load_dwordx4 v[46:49], v[156:157], off offset:192
	v_or_b32_e32 v172, 0xc000, v98
	v_mov_b32_e32 v173, v99
	v_lshlrev_b64 v[174:175], 2, v[172:173]
	v_lshl_add_u64 v[158:159], s[12:13], 0, v[174:175]
	v_lshl_add_u64 v[166:167], s[82:83], 0, v[174:175]
	v_lshl_add_u64 v[158:159], v[158:159], 0, v[168:169]
	v_lshl_add_u64 v[166:167], v[166:167], 0, v[168:169]
	global_load_dwordx4 v[50:53], v[158:159], off
	global_load_dwordx4 v[54:57], v[158:159], off offset:64
	global_load_dwordx4 v[58:61], v[158:159], off offset:128
	global_load_dwordx4 v[70:73], v[158:159], off offset:192
	s_waitcnt vmcnt(15)
	v_pk_fma_f32 v[120:121], v[120:121], s[6:7], v[94:95] op_sel_hi:[1,0,1]
	v_pk_fma_f32 v[122:123], v[122:123], s[6:7], v[96:97] op_sel_hi:[1,0,1]
	s_waitcnt vmcnt(14)
	v_pk_fma_f32 v[124:125], v[124:125], s[6:7], v[90:91] op_sel_hi:[1,0,1]
	v_pk_fma_f32 v[126:127], v[126:127], s[6:7], v[92:93] op_sel_hi:[1,0,1]
	s_waitcnt vmcnt(13)
	v_pk_fma_f32 v[128:129], v[128:129], s[6:7], v[86:87] op_sel_hi:[1,0,1]
	v_pk_fma_f32 v[130:131], v[130:131], s[6:7], v[88:89] op_sel_hi:[1,0,1]
	s_waitcnt vmcnt(12)
	v_pk_fma_f32 v[132:133], v[132:133], s[6:7], v[82:83] op_sel_hi:[1,0,1]
	v_pk_fma_f32 v[134:135], v[134:135], s[6:7], v[84:85] op_sel_hi:[1,0,1]
	s_waitcnt vmcnt(11)
	v_pk_fma_f32 v[136:137], v[136:137], s[6:7], v[78:79] op_sel_hi:[1,0,1]
	v_pk_fma_f32 v[138:139], v[138:139], s[6:7], v[80:81] op_sel_hi:[1,0,1]
	s_waitcnt vmcnt(10)
	v_pk_fma_f32 v[140:141], v[140:141], s[6:7], v[74:75] op_sel_hi:[1,0,1]
	v_pk_fma_f32 v[142:143], v[142:143], s[6:7], v[76:77] op_sel_hi:[1,0,1]
	s_waitcnt vmcnt(9)
	v_pk_fma_f32 v[144:145], v[144:145], s[6:7], v[62:63] op_sel_hi:[1,0,1]
	v_pk_fma_f32 v[146:147], v[146:147], s[6:7], v[64:65] op_sel_hi:[1,0,1]
	s_waitcnt vmcnt(8)
	v_pk_fma_f32 v[148:149], v[148:149], s[6:7], v[30:31] op_sel_hi:[1,0,1]
	v_pk_fma_f32 v[150:151], v[150:151], s[6:7], v[32:33] op_sel_hi:[1,0,1]
	s_waitcnt vmcnt(7)
	v_pk_fma_f32 v[22:23], v[22:23], s[6:7], v[66:67] op_sel_hi:[1,0,1]
	v_pk_fma_f32 v[24:25], v[24:25], s[6:7], v[68:69] op_sel_hi:[1,0,1]
	s_waitcnt vmcnt(6)
	v_pk_fma_f32 v[26:27], v[26:27], s[6:7], v[38:39] op_sel_hi:[1,0,1]
	v_pk_fma_f32 v[28:29], v[28:29], s[6:7], v[40:41] op_sel_hi:[1,0,1]
	s_waitcnt vmcnt(5)
	v_pk_fma_f32 v[42:43], v[42:43], s[6:7], v[34:35] op_sel_hi:[1,0,1]
	v_pk_fma_f32 v[44:45], v[44:45], s[6:7], v[36:37] op_sel_hi:[1,0,1]
	s_waitcnt vmcnt(4)
	v_pk_fma_f32 v[46:47], v[46:47], s[6:7], v[18:19] op_sel_hi:[1,0,1]
	v_pk_fma_f32 v[48:49], v[48:49], s[6:7], v[20:21] op_sel_hi:[1,0,1]
	s_waitcnt vmcnt(3)
	v_pk_fma_f32 v[50:51], v[50:51], s[6:7], v[14:15] op_sel_hi:[1,0,1]
	v_pk_fma_f32 v[52:53], v[52:53], s[6:7], v[16:17] op_sel_hi:[1,0,1]
	s_waitcnt vmcnt(2)
	v_pk_fma_f32 v[54:55], v[54:55], s[6:7], v[10:11] op_sel_hi:[1,0,1]
	v_pk_fma_f32 v[56:57], v[56:57], s[6:7], v[12:13] op_sel_hi:[1,0,1]
	s_waitcnt vmcnt(1)
	v_pk_fma_f32 v[58:59], v[58:59], s[6:7], v[6:7] op_sel_hi:[1,0,1]
	v_pk_fma_f32 v[60:61], v[60:61], s[6:7], v[8:9] op_sel_hi:[1,0,1]
	s_waitcnt vmcnt(0)
	v_pk_fma_f32 v[70:71], v[70:71], s[6:7], v[2:3] op_sel_hi:[1,0,1]
	v_pk_fma_f32 v[72:73], v[72:73], s[6:7], v[4:5] op_sel_hi:[1,0,1]
	global_store_dwordx4 v[160:161], v[120:123], off
	global_store_dwordx4 v[160:161], v[124:127], off offset:64
	global_store_dwordx4 v[160:161], v[128:131], off offset:128
	global_store_dwordx4 v[160:161], v[132:135], off offset:192
	global_store_dwordx4 v[162:163], v[136:139], off
	global_store_dwordx4 v[162:163], v[140:143], off offset:64
	global_store_dwordx4 v[162:163], v[144:147], off offset:128
	global_store_dwordx4 v[162:163], v[148:151], off offset:192
	global_store_dwordx4 v[164:165], v[22:25], off
	global_store_dwordx4 v[164:165], v[26:29], off offset:64
	global_store_dwordx4 v[164:165], v[42:45], off offset:128
	global_store_dwordx4 v[164:165], v[46:49], off offset:192
	global_store_dwordx4 v[166:167], v[50:53], off
	global_store_dwordx4 v[166:167], v[54:57], off offset:64
	global_store_dwordx4 v[166:167], v[58:61], off offset:128
	global_store_dwordx4 v[166:167], v[70:73], off offset:192
	s_add_i32 s7, s7, s3
	s_cmpk_lt_u32 s7, 0x100
	s_cbranch_scc1 .LBB0_422

.LBB0_518:
	s_lshr_b32 s4, s6, 1
	s_and_b32 s4, s4, 0xf8
	s_or_b32 s4, s4, s2
	s_lshl_b32 s10, s4, 7
	s_lshl_b32 s4, s6, 7
	v_or_b32_e32 v2, s10, v1
	s_and_b32 s11, s4, 0x780
	v_lshlrev_b32_e32 v98, 10, v2
	v_lshl_add_u64 v[104:105], v[100:101], 0, v[98:99]
	v_or_b32_e32 v2, s11, v1
	v_lshlrev_b32_e32 v98, 10, v2
	v_lshl_add_u64 v[108:109], v[102:103], 0, v[98:99]
	v_and_b32_e32 v177, 7, v106
	v_bfe_u32 v176, v106, 3, 3
	v_xor_b32_e32 v176, v177, v176
	v_sub_u32_e32 v176, v176, v177
	v_lshlrev_b32_e32 v176, 4, v176
	v_ashrrev_i32_e32 v177, 31, v176
	v_lshrrev_b32_e32 v182, 6, v106
	v_mov_b32_e32 v183, 0x110
	v_lshl_add_u32 v182, v182, 10, v183
	v_lshl_add_u64 v[184:185], v[104:105], 0, v[176:177]
	v_lshl_add_u64 v[192:193], v[108:109], 0, v[176:177]
	v_readfirstlane_b32 s14, v182
	v_add_co_u32_e32 v186, vcc, s7, v184
	v_addc_co_u32_e32 v187, vcc, 0, v185, vcc
	v_add_co_u32_e32 v188, vcc, s8, v184
	v_addc_co_u32_e32 v189, vcc, 0, v185, vcc
	v_add_co_u32_e32 v190, vcc, s9, v184
	v_addc_co_u32_e32 v191, vcc, 0, v185, vcc
	v_add_co_u32_e32 v194, vcc, s7, v192
	v_addc_co_u32_e32 v195, vcc, 0, v193, vcc
	v_add_co_u32_e32 v196, vcc, s8, v192
	v_addc_co_u32_e32 v197, vcc, 0, v193, vcc
	v_add_co_u32_e32 v198, vcc, s9, v192
	v_addc_co_u32_e32 v199, vcc, 0, v193, vcc
	v_mov_b32_e32 v30, 0
	v_mov_b32_e32 v31, v99
	v_mov_b32_e32 v32, v99
	v_mov_b32_e32 v33, v99
	v_mov_b32_e32 v38, 0
	v_mov_b32_e32 v39, v99
	v_mov_b32_e32 v40, v99
	v_mov_b32_e32 v41, v99
	v_mov_b32_e32 v50, 0
	v_mov_b32_e32 v51, v99
	v_mov_b32_e32 v52, v99
	v_mov_b32_e32 v53, v99
	v_mov_b32_e32 v74, 0
	v_mov_b32_e32 v75, v99
	v_mov_b32_e32 v76, v99
	v_mov_b32_e32 v77, v99
	v_mov_b32_e32 v82, 0
	v_mov_b32_e32 v83, v99
	v_mov_b32_e32 v84, v99
	v_mov_b32_e32 v85, v99
	v_mov_b32_e32 v86, 0
	v_mov_b32_e32 v87, v99
	v_mov_b32_e32 v88, v99
	v_mov_b32_e32 v89, v99
	v_mov_b32_e32 v90, 0
	v_mov_b32_e32 v91, v99
	v_mov_b32_e32 v92, v99
	v_mov_b32_e32 v93, v99
	v_mov_b32_e32 v94, 0
	v_mov_b32_e32 v95, v99
	v_mov_b32_e32 v96, v99
	v_mov_b32_e32 v97, v99
	v_mov_b32_e32 v34, 0
	v_mov_b32_e32 v35, v99
	v_mov_b32_e32 v36, v99
	v_mov_b32_e32 v37, v99
	v_mov_b32_e32 v26, 0
	v_mov_b32_e32 v27, v99
	v_mov_b32_e32 v28, v99
	v_mov_b32_e32 v29, v99
	v_mov_b32_e32 v22, 0
	v_mov_b32_e32 v23, v99
	v_mov_b32_e32 v24, v99
	v_mov_b32_e32 v25, v99
	v_mov_b32_e32 v18, 0
	v_mov_b32_e32 v19, v99
	v_mov_b32_e32 v20, v99
	v_mov_b32_e32 v21, v99
	v_mov_b32_e32 v14, 0
	v_mov_b32_e32 v15, v99
	v_mov_b32_e32 v16, v99
	v_mov_b32_e32 v17, v99
	v_mov_b32_e32 v10, 0
	v_mov_b32_e32 v11, v99
	v_mov_b32_e32 v12, v99
	v_mov_b32_e32 v13, v99
	v_mov_b32_e32 v6, 0
	v_mov_b32_e32 v7, v99
	v_mov_b32_e32 v8, v99
	v_mov_b32_e32 v9, v99
	v_mov_b32_e32 v2, 0
	v_mov_b32_e32 v3, v99
	v_mov_b32_e32 v4, v99
	v_mov_b32_e32 v5, v99
	s_add_u32 m0, s14, 0x0
	s_nop 0
	global_load_lds_dwordx4 v[184:185], off
	s_add_u32 m0, s14, 0x1000
	s_nop 0
	global_load_lds_dwordx4 v[186:187], off
	s_add_u32 m0, s14, 0x2000
	s_nop 0
	global_load_lds_dwordx4 v[188:189], off
	s_add_u32 m0, s14, 0x3000
	s_nop 0
	global_load_lds_dwordx4 v[190:191], off
	s_add_u32 m0, s14, 0x4000
	s_nop 0
	global_load_lds_dwordx4 v[192:193], off
	s_add_u32 m0, s14, 0x5000
	s_nop 0
	global_load_lds_dwordx4 v[194:195], off
	s_add_u32 m0, s14, 0x6000
	s_nop 0
	global_load_lds_dwordx4 v[196:197], off
	s_add_u32 m0, s14, 0x7000
	s_nop 0
	global_load_lds_dwordx4 v[198:199], off
	s_mov_b32 s4, 0x80
	s_add_u32 m0, s14, 0x8000
	v_lshl_add_u64 v[200:201], v[184:185], 0, s[4:5]
	global_load_lds_dwordx4 v[200:201], off
	s_add_u32 m0, s14, 0x9000
	v_lshl_add_u64 v[202:203], v[186:187], 0, s[4:5]
	global_load_lds_dwordx4 v[202:203], off
	s_add_u32 m0, s14, 0xa000
	v_lshl_add_u64 v[200:201], v[188:189], 0, s[4:5]
	global_load_lds_dwordx4 v[200:201], off
	s_add_u32 m0, s14, 0xb000
	v_lshl_add_u64 v[202:203], v[190:191], 0, s[4:5]
	global_load_lds_dwordx4 v[202:203], off
	s_add_u32 m0, s14, 0xc000
	v_lshl_add_u64 v[200:201], v[192:193], 0, s[4:5]
	global_load_lds_dwordx4 v[200:201], off
	s_add_u32 m0, s14, 0xd000
	v_lshl_add_u64 v[202:203], v[194:195], 0, s[4:5]
	global_load_lds_dwordx4 v[202:203], off
	s_add_u32 m0, s14, 0xe000
	v_lshl_add_u64 v[200:201], v[196:197], 0, s[4:5]
	global_load_lds_dwordx4 v[200:201], off
	s_add_u32 m0, s14, 0xf000
	v_lshl_add_u64 v[202:203], v[198:199], 0, s[4:5]
	global_load_lds_dwordx4 v[202:203], off
	s_mov_b32 s13, 0
	s_mov_b32 s12, 0
	s_waitcnt vmcnt(8)
	s_barrier
.Lglds2_14401:
	ds_read_b128 v[152:155], v112 offset:16384
	ds_read_b128 v[156:159], v112 offset:18432
	ds_read_b128 v[160:163], v110
	ds_read_b128 v[164:167], v110 offset:2048
	ds_read_b128 v[168:171], v112 offset:20480
	ds_read_b128 v[172:175], v113 offset:16384
	ds_read_b128 v[204:207], v110 offset:4096
	ds_read_b128 v[208:211], v111
	ds_read_b128 v[212:215], v116 offset:16384
	ds_read_b128 v[216:219], v116 offset:18432
	ds_read_b128 v[220:223], v114
	ds_read_b128 v[224:227], v114 offset:2048
	ds_read_b128 v[228:231], v116 offset:20480
	ds_read_b128 v[232:235], v117 offset:16384
	ds_read_b128 v[236:239], v114 offset:4096
	ds_read_b128 v[240:243], v115
	s_setprio 1
	s_waitcnt lgkmcnt(13)
	v_mfma_i32_16x16x64_i8 v[94:97], v[152:155], v[160:163], v[94:97]
	v_mfma_i32_16x16x64_i8 v[90:93], v[156:159], v[160:163], v[90:93]
	s_waitcnt lgkmcnt(11)
	v_mfma_i32_16x16x64_i8 v[86:89], v[168:171], v[160:163], v[86:89]
	s_waitcnt lgkmcnt(10)
	v_mfma_i32_16x16x64_i8 v[82:85], v[172:175], v[160:163], v[82:85]
	v_mfma_i32_16x16x64_i8 v[74:77], v[152:155], v[164:167], v[74:77]
	v_mfma_i32_16x16x64_i8 v[50:53], v[156:159], v[164:167], v[50:53]
	v_mfma_i32_16x16x64_i8 v[38:41], v[168:171], v[164:167], v[38:41]
	v_mfma_i32_16x16x64_i8 v[30:33], v[172:175], v[164:167], v[30:33]
	s_waitcnt lgkmcnt(9)
	v_mfma_i32_16x16x64_i8 v[34:37], v[152:155], v[204:207], v[34:37]
	v_mfma_i32_16x16x64_i8 v[26:29], v[156:159], v[204:207], v[26:29]
	v_mfma_i32_16x16x64_i8 v[22:25], v[168:171], v[204:207], v[22:25]
	v_mfma_i32_16x16x64_i8 v[18:21], v[172:175], v[204:207], v[18:21]
	s_waitcnt lgkmcnt(8)
	v_mfma_i32_16x16x64_i8 v[14:17], v[152:155], v[208:211], v[14:17]
	v_mfma_i32_16x16x64_i8 v[10:13], v[156:159], v[208:211], v[10:13]
	v_mfma_i32_16x16x64_i8 v[6:9], v[168:171], v[208:211], v[6:9]
	v_mfma_i32_16x16x64_i8 v[2:5], v[172:175], v[208:211], v[2:5]
	s_setprio 0
	s_waitcnt lgkmcnt(0)
	s_barrier
	s_add_i32 s4, s13, 0x80
	s_min_u32 s4, s4, 0x1c0
	s_lshl_b32 s4, s4, 1
	s_setprio 1
	v_mfma_i32_16x16x64_i8 v[94:97], v[212:215], v[220:223], v[94:97]
	s_add_u32 m0, s14, 0x0
	v_lshl_add_u64 v[200:201], v[184:185], 0, s[4:5]
	global_load_lds_dwordx4 v[200:201], off
	v_mfma_i32_16x16x64_i8 v[90:93], v[216:219], v[220:223], v[90:93]
	v_mfma_i32_16x16x64_i8 v[86:89], v[228:231], v[220:223], v[86:89]
	s_add_u32 m0, s14, 0x1000
	v_lshl_add_u64 v[202:203], v[186:187], 0, s[4:5]
	global_load_lds_dwordx4 v[202:203], off
	v_mfma_i32_16x16x64_i8 v[82:85], v[232:235], v[220:223], v[82:85]
	v_mfma_i32_16x16x64_i8 v[74:77], v[212:215], v[224:227], v[74:77]
	s_add_u32 m0, s14, 0x2000
	v_lshl_add_u64 v[200:201], v[188:189], 0, s[4:5]
	global_load_lds_dwordx4 v[200:201], off
	v_mfma_i32_16x16x64_i8 v[50:53], v[216:219], v[224:227], v[50:53]
	v_mfma_i32_16x16x64_i8 v[38:41], v[228:231], v[224:227], v[38:41]
	s_add_u32 m0, s14, 0x3000
	v_lshl_add_u64 v[202:203], v[190:191], 0, s[4:5]
	global_load_lds_dwordx4 v[202:203], off
	v_mfma_i32_16x16x64_i8 v[30:33], v[232:235], v[224:227], v[30:33]
	v_mfma_i32_16x16x64_i8 v[34:37], v[212:215], v[236:239], v[34:37]
	s_add_u32 m0, s14, 0x4000
	v_lshl_add_u64 v[200:201], v[192:193], 0, s[4:5]
	global_load_lds_dwordx4 v[200:201], off
	v_mfma_i32_16x16x64_i8 v[26:29], v[216:219], v[236:239], v[26:29]
	v_mfma_i32_16x16x64_i8 v[22:25], v[228:231], v[236:239], v[22:25]
	s_add_u32 m0, s14, 0x5000
	v_lshl_add_u64 v[202:203], v[194:195], 0, s[4:5]
	global_load_lds_dwordx4 v[202:203], off
	v_mfma_i32_16x16x64_i8 v[18:21], v[232:235], v[236:239], v[18:21]
	v_mfma_i32_16x16x64_i8 v[14:17], v[212:215], v[240:243], v[14:17]
	s_add_u32 m0, s14, 0x6000
	v_lshl_add_u64 v[200:201], v[196:197], 0, s[4:5]
	global_load_lds_dwordx4 v[200:201], off
	v_mfma_i32_16x16x64_i8 v[10:13], v[216:219], v[240:243], v[10:13]
	v_mfma_i32_16x16x64_i8 v[6:9], v[228:231], v[240:243], v[6:9]
	s_add_u32 m0, s14, 0x7000
	v_lshl_add_u64 v[202:203], v[198:199], 0, s[4:5]
	global_load_lds_dwordx4 v[202:203], off
	v_mfma_i32_16x16x64_i8 v[2:5], v[232:235], v[240:243], v[2:5]
	s_setprio 0
	s_waitcnt vmcnt(8)
	s_barrier
	ds_read_b128 v[152:155], v112 offset:49152
	ds_read_b128 v[156:159], v112 offset:51200
	ds_read_b128 v[160:163], v110 offset:32768
	ds_read_b128 v[164:167], v110 offset:34816
	ds_read_b128 v[168:171], v112 offset:53248
	ds_read_b128 v[172:175], v113 offset:49152
	ds_read_b128 v[204:207], v110 offset:36864
	ds_read_b128 v[208:211], v111 offset:32768
	ds_read_b128 v[212:215], v116 offset:49152
	ds_read_b128 v[216:219], v116 offset:51200
	ds_read_b128 v[220:223], v114 offset:32768
	ds_read_b128 v[224:227], v114 offset:34816
	ds_read_b128 v[228:231], v116 offset:53248
	ds_read_b128 v[232:235], v117 offset:49152
	ds_read_b128 v[236:239], v114 offset:36864
	ds_read_b128 v[240:243], v115 offset:32768
	s_setprio 1
	s_waitcnt lgkmcnt(13)
	v_mfma_i32_16x16x64_i8 v[94:97], v[152:155], v[160:163], v[94:97]
	v_mfma_i32_16x16x64_i8 v[90:93], v[156:159], v[160:163], v[90:93]
	s_waitcnt lgkmcnt(11)
	v_mfma_i32_16x16x64_i8 v[86:89], v[168:171], v[160:163], v[86:89]
	s_waitcnt lgkmcnt(10)
	v_mfma_i32_16x16x64_i8 v[82:85], v[172:175], v[160:163], v[82:85]
	v_mfma_i32_16x16x64_i8 v[74:77], v[152:155], v[164:167], v[74:77]
	v_mfma_i32_16x16x64_i8 v[50:53], v[156:159], v[164:167], v[50:53]
	v_mfma_i32_16x16x64_i8 v[38:41], v[168:171], v[164:167], v[38:41]
	v_mfma_i32_16x16x64_i8 v[30:33], v[172:175], v[164:167], v[30:33]
	s_waitcnt lgkmcnt(9)
	v_mfma_i32_16x16x64_i8 v[34:37], v[152:155], v[204:207], v[34:37]
	v_mfma_i32_16x16x64_i8 v[26:29], v[156:159], v[204:207], v[26:29]
	v_mfma_i32_16x16x64_i8 v[22:25], v[168:171], v[204:207], v[22:25]
	v_mfma_i32_16x16x64_i8 v[18:21], v[172:175], v[204:207], v[18:21]
	s_waitcnt lgkmcnt(8)
	v_mfma_i32_16x16x64_i8 v[14:17], v[152:155], v[208:211], v[14:17]
	v_mfma_i32_16x16x64_i8 v[10:13], v[156:159], v[208:211], v[10:13]
	v_mfma_i32_16x16x64_i8 v[6:9], v[168:171], v[208:211], v[6:9]
	v_mfma_i32_16x16x64_i8 v[2:5], v[172:175], v[208:211], v[2:5]
	s_setprio 0
	s_waitcnt lgkmcnt(0)
	s_barrier
	s_add_i32 s4, s13, 0xc0
	s_min_u32 s4, s4, 0x1c0
	s_lshl_b32 s4, s4, 1
	s_setprio 1
	v_mfma_i32_16x16x64_i8 v[94:97], v[212:215], v[220:223], v[94:97]
	s_add_u32 m0, s14, 0x8000
	v_lshl_add_u64 v[200:201], v[184:185], 0, s[4:5]
	global_load_lds_dwordx4 v[200:201], off
	v_mfma_i32_16x16x64_i8 v[90:93], v[216:219], v[220:223], v[90:93]
	v_mfma_i32_16x16x64_i8 v[86:89], v[228:231], v[220:223], v[86:89]
	s_add_u32 m0, s14, 0x9000
	v_lshl_add_u64 v[202:203], v[186:187], 0, s[4:5]
	global_load_lds_dwordx4 v[202:203], off
	v_mfma_i32_16x16x64_i8 v[82:85], v[232:235], v[220:223], v[82:85]
	v_mfma_i32_16x16x64_i8 v[74:77], v[212:215], v[224:227], v[74:77]
	s_add_u32 m0, s14, 0xa000
	v_lshl_add_u64 v[200:201], v[188:189], 0, s[4:5]
	global_load_lds_dwordx4 v[200:201], off
	v_mfma_i32_16x16x64_i8 v[50:53], v[216:219], v[224:227], v[50:53]
	v_mfma_i32_16x16x64_i8 v[38:41], v[228:231], v[224:227], v[38:41]
	s_add_u32 m0, s14, 0xb000
	v_lshl_add_u64 v[202:203], v[190:191], 0, s[4:5]
	global_load_lds_dwordx4 v[202:203], off
	v_mfma_i32_16x16x64_i8 v[30:33], v[232:235], v[224:227], v[30:33]
	v_mfma_i32_16x16x64_i8 v[34:37], v[212:215], v[236:239], v[34:37]
	s_add_u32 m0, s14, 0xc000
	v_lshl_add_u64 v[200:201], v[192:193], 0, s[4:5]
	global_load_lds_dwordx4 v[200:201], off
	v_mfma_i32_16x16x64_i8 v[26:29], v[216:219], v[236:239], v[26:29]
	v_mfma_i32_16x16x64_i8 v[22:25], v[228:231], v[236:239], v[22:25]
	s_add_u32 m0, s14, 0xd000
	v_lshl_add_u64 v[202:203], v[194:195], 0, s[4:5]
	global_load_lds_dwordx4 v[202:203], off
	v_mfma_i32_16x16x64_i8 v[18:21], v[232:235], v[236:239], v[18:21]
	v_mfma_i32_16x16x64_i8 v[14:17], v[212:215], v[240:243], v[14:17]
	s_add_u32 m0, s14, 0xe000
	v_lshl_add_u64 v[200:201], v[196:197], 0, s[4:5]
	global_load_lds_dwordx4 v[200:201], off
	v_mfma_i32_16x16x64_i8 v[10:13], v[216:219], v[240:243], v[10:13]
	v_mfma_i32_16x16x64_i8 v[6:9], v[228:231], v[240:243], v[6:9]
	s_add_u32 m0, s14, 0xf000
	v_lshl_add_u64 v[202:203], v[198:199], 0, s[4:5]
	global_load_lds_dwordx4 v[202:203], off
	v_mfma_i32_16x16x64_i8 v[2:5], v[232:235], v[240:243], v[2:5]
	s_setprio 0
	s_waitcnt vmcnt(8)
	s_barrier
	s_add_i32 s13, s13, 0x80
	s_add_i32 s12, s12, 2
	s_cmp_lt_u32 s12, 6
	s_cbranch_scc1 .Lglds2_14401
	ds_read_b128 v[152:155], v112 offset:16384
	ds_read_b128 v[156:159], v112 offset:18432
	ds_read_b128 v[160:163], v110
	ds_read_b128 v[164:167], v110 offset:2048
	ds_read_b128 v[168:171], v112 offset:20480
	ds_read_b128 v[172:175], v113 offset:16384
	ds_read_b128 v[204:207], v110 offset:4096
	ds_read_b128 v[208:211], v111
	ds_read_b128 v[212:215], v116 offset:16384
	ds_read_b128 v[216:219], v116 offset:18432
	ds_read_b128 v[220:223], v114
	ds_read_b128 v[224:227], v114 offset:2048
	ds_read_b128 v[228:231], v116 offset:20480
	ds_read_b128 v[232:235], v117 offset:16384
	ds_read_b128 v[236:239], v114 offset:4096
	ds_read_b128 v[240:243], v115
	s_setprio 1
	s_waitcnt lgkmcnt(13)
	v_mfma_i32_16x16x64_i8 v[94:97], v[152:155], v[160:163], v[94:97]
	v_mfma_i32_16x16x64_i8 v[90:93], v[156:159], v[160:163], v[90:93]
	s_waitcnt lgkmcnt(11)
	v_mfma_i32_16x16x64_i8 v[86:89], v[168:171], v[160:163], v[86:89]
	s_waitcnt lgkmcnt(10)
	v_mfma_i32_16x16x64_i8 v[82:85], v[172:175], v[160:163], v[82:85]
	v_mfma_i32_16x16x64_i8 v[74:77], v[152:155], v[164:167], v[74:77]
	v_mfma_i32_16x16x64_i8 v[50:53], v[156:159], v[164:167], v[50:53]
	v_mfma_i32_16x16x64_i8 v[38:41], v[168:171], v[164:167], v[38:41]
	v_mfma_i32_16x16x64_i8 v[30:33], v[172:175], v[164:167], v[30:33]
	s_waitcnt lgkmcnt(9)
	v_mfma_i32_16x16x64_i8 v[34:37], v[152:155], v[204:207], v[34:37]
	v_mfma_i32_16x16x64_i8 v[26:29], v[156:159], v[204:207], v[26:29]
	v_mfma_i32_16x16x64_i8 v[22:25], v[168:171], v[204:207], v[22:25]
	v_mfma_i32_16x16x64_i8 v[18:21], v[172:175], v[204:207], v[18:21]
	s_waitcnt lgkmcnt(8)
	v_mfma_i32_16x16x64_i8 v[14:17], v[152:155], v[208:211], v[14:17]
	v_mfma_i32_16x16x64_i8 v[10:13], v[156:159], v[208:211], v[10:13]
	v_mfma_i32_16x16x64_i8 v[6:9], v[168:171], v[208:211], v[6:9]
	v_mfma_i32_16x16x64_i8 v[2:5], v[172:175], v[208:211], v[2:5]
	s_setprio 0
	s_waitcnt lgkmcnt(0)
	s_setprio 1
	v_mfma_i32_16x16x64_i8 v[94:97], v[212:215], v[220:223], v[94:97]
	v_mfma_i32_16x16x64_i8 v[90:93], v[216:219], v[220:223], v[90:93]
	v_mfma_i32_16x16x64_i8 v[86:89], v[228:231], v[220:223], v[86:89]
	v_mfma_i32_16x16x64_i8 v[82:85], v[232:235], v[220:223], v[82:85]
	v_mfma_i32_16x16x64_i8 v[74:77], v[212:215], v[224:227], v[74:77]
	v_mfma_i32_16x16x64_i8 v[50:53], v[216:219], v[224:227], v[50:53]
	v_mfma_i32_16x16x64_i8 v[38:41], v[228:231], v[224:227], v[38:41]
	v_mfma_i32_16x16x64_i8 v[30:33], v[232:235], v[224:227], v[30:33]
	v_mfma_i32_16x16x64_i8 v[34:37], v[212:215], v[236:239], v[34:37]
	v_mfma_i32_16x16x64_i8 v[26:29], v[216:219], v[236:239], v[26:29]
	v_mfma_i32_16x16x64_i8 v[22:25], v[228:231], v[236:239], v[22:25]
	v_mfma_i32_16x16x64_i8 v[18:21], v[232:235], v[236:239], v[18:21]
	v_mfma_i32_16x16x64_i8 v[14:17], v[212:215], v[240:243], v[14:17]
	v_mfma_i32_16x16x64_i8 v[10:13], v[216:219], v[240:243], v[10:13]
	v_mfma_i32_16x16x64_i8 v[6:9], v[228:231], v[240:243], v[6:9]
	v_mfma_i32_16x16x64_i8 v[2:5], v[232:235], v[240:243], v[2:5]
	s_setprio 0
	s_waitcnt vmcnt(0)
	s_barrier
	ds_read_b128 v[152:155], v112 offset:49152
	ds_read_b128 v[156:159], v112 offset:51200
	ds_read_b128 v[160:163], v110 offset:32768
	ds_read_b128 v[164:167], v110 offset:34816
	ds_read_b128 v[168:171], v112 offset:53248
	ds_read_b128 v[172:175], v113 offset:49152
	ds_read_b128 v[204:207], v110 offset:36864
	ds_read_b128 v[208:211], v111 offset:32768
	ds_read_b128 v[212:215], v116 offset:49152
	ds_read_b128 v[216:219], v116 offset:51200
	ds_read_b128 v[220:223], v114 offset:32768
	ds_read_b128 v[224:227], v114 offset:34816
	ds_read_b128 v[228:231], v116 offset:53248
	ds_read_b128 v[232:235], v117 offset:49152
	ds_read_b128 v[236:239], v114 offset:36864
	ds_read_b128 v[240:243], v115 offset:32768
	s_setprio 1
	s_waitcnt lgkmcnt(13)
	v_mfma_i32_16x16x64_i8 v[94:97], v[152:155], v[160:163], v[94:97]
	v_mfma_i32_16x16x64_i8 v[90:93], v[156:159], v[160:163], v[90:93]
	s_waitcnt lgkmcnt(11)
	v_mfma_i32_16x16x64_i8 v[86:89], v[168:171], v[160:163], v[86:89]
	s_waitcnt lgkmcnt(10)
	v_mfma_i32_16x16x64_i8 v[82:85], v[172:175], v[160:163], v[82:85]
	v_mfma_i32_16x16x64_i8 v[74:77], v[152:155], v[164:167], v[74:77]
	v_mfma_i32_16x16x64_i8 v[50:53], v[156:159], v[164:167], v[50:53]
	v_mfma_i32_16x16x64_i8 v[38:41], v[168:171], v[164:167], v[38:41]
	v_mfma_i32_16x16x64_i8 v[30:33], v[172:175], v[164:167], v[30:33]
	s_waitcnt lgkmcnt(9)
	v_mfma_i32_16x16x64_i8 v[34:37], v[152:155], v[204:207], v[34:37]
	v_mfma_i32_16x16x64_i8 v[26:29], v[156:159], v[204:207], v[26:29]
	v_mfma_i32_16x16x64_i8 v[22:25], v[168:171], v[204:207], v[22:25]
	v_mfma_i32_16x16x64_i8 v[18:21], v[172:175], v[204:207], v[18:21]
	s_waitcnt lgkmcnt(8)
	v_mfma_i32_16x16x64_i8 v[14:17], v[152:155], v[208:211], v[14:17]
	v_mfma_i32_16x16x64_i8 v[10:13], v[156:159], v[208:211], v[10:13]
	v_mfma_i32_16x16x64_i8 v[6:9], v[168:171], v[208:211], v[6:9]
	v_mfma_i32_16x16x64_i8 v[2:5], v[172:175], v[208:211], v[2:5]
	s_setprio 0
	s_waitcnt lgkmcnt(0)
	s_barrier
	s_setprio 1
	v_mfma_i32_16x16x64_i8 v[94:97], v[212:215], v[220:223], v[94:97]
	v_mfma_i32_16x16x64_i8 v[90:93], v[216:219], v[220:223], v[90:93]
	v_mfma_i32_16x16x64_i8 v[86:89], v[228:231], v[220:223], v[86:89]
	v_mfma_i32_16x16x64_i8 v[82:85], v[232:235], v[220:223], v[82:85]
	v_mfma_i32_16x16x64_i8 v[74:77], v[212:215], v[224:227], v[74:77]
	v_mfma_i32_16x16x64_i8 v[50:53], v[216:219], v[224:227], v[50:53]
	v_mfma_i32_16x16x64_i8 v[38:41], v[228:231], v[224:227], v[38:41]
	v_mfma_i32_16x16x64_i8 v[30:33], v[232:235], v[224:227], v[30:33]
	v_mfma_i32_16x16x64_i8 v[34:37], v[212:215], v[236:239], v[34:37]
	v_mfma_i32_16x16x64_i8 v[26:29], v[216:219], v[236:239], v[26:29]
	v_mfma_i32_16x16x64_i8 v[22:25], v[228:231], v[236:239], v[22:25]
	v_mfma_i32_16x16x64_i8 v[18:21], v[232:235], v[236:239], v[18:21]
	v_mfma_i32_16x16x64_i8 v[14:17], v[212:215], v[240:243], v[14:17]
	v_mfma_i32_16x16x64_i8 v[10:13], v[216:219], v[240:243], v[10:13]
	v_mfma_i32_16x16x64_i8 v[6:9], v[228:231], v[240:243], v[6:9]
	v_mfma_i32_16x16x64_i8 v[2:5], v[232:235], v[240:243], v[2:5]
	s_setprio 0
	s_waitcnt vmcnt(0)
	v_cvt_f32_i32_e32 v94, v94
	v_cvt_f32_i32_e32 v95, v95
	v_cvt_f32_i32_e32 v96, v96
	v_cvt_f32_i32_e32 v97, v97
	v_cvt_f32_i32_e32 v90, v90
	v_cvt_f32_i32_e32 v91, v91
	v_cvt_f32_i32_e32 v92, v92
	v_cvt_f32_i32_e32 v93, v93
	v_cvt_f32_i32_e32 v86, v86
	v_cvt_f32_i32_e32 v87, v87
	v_cvt_f32_i32_e32 v88, v88
	v_cvt_f32_i32_e32 v89, v89
	v_cvt_f32_i32_e32 v82, v82
	v_cvt_f32_i32_e32 v83, v83
	v_cvt_f32_i32_e32 v84, v84
	v_cvt_f32_i32_e32 v85, v85
	v_cvt_f32_i32_e32 v74, v74
	v_cvt_f32_i32_e32 v75, v75
	v_cvt_f32_i32_e32 v76, v76
	v_cvt_f32_i32_e32 v77, v77
	v_cvt_f32_i32_e32 v50, v50
	v_cvt_f32_i32_e32 v51, v51
	v_cvt_f32_i32_e32 v52, v52
	v_cvt_f32_i32_e32 v53, v53
	v_cvt_f32_i32_e32 v38, v38
	v_cvt_f32_i32_e32 v39, v39
	v_cvt_f32_i32_e32 v40, v40
	v_cvt_f32_i32_e32 v41, v41
	v_cvt_f32_i32_e32 v30, v30
	v_cvt_f32_i32_e32 v31, v31
	v_cvt_f32_i32_e32 v32, v32
	v_cvt_f32_i32_e32 v33, v33
	v_cvt_f32_i32_e32 v34, v34
	v_cvt_f32_i32_e32 v35, v35
	v_cvt_f32_i32_e32 v36, v36
	v_cvt_f32_i32_e32 v37, v37
	v_cvt_f32_i32_e32 v26, v26
	v_cvt_f32_i32_e32 v27, v27
	v_cvt_f32_i32_e32 v28, v28
	v_cvt_f32_i32_e32 v29, v29
	v_cvt_f32_i32_e32 v22, v22
	v_cvt_f32_i32_e32 v23, v23
	v_cvt_f32_i32_e32 v24, v24
	v_cvt_f32_i32_e32 v25, v25
	v_cvt_f32_i32_e32 v18, v18
	v_cvt_f32_i32_e32 v19, v19
	v_cvt_f32_i32_e32 v20, v20
	v_cvt_f32_i32_e32 v21, v21
	v_cvt_f32_i32_e32 v14, v14
	v_cvt_f32_i32_e32 v15, v15
	v_cvt_f32_i32_e32 v16, v16
	v_cvt_f32_i32_e32 v17, v17
	v_cvt_f32_i32_e32 v10, v10
	v_cvt_f32_i32_e32 v11, v11
	v_cvt_f32_i32_e32 v12, v12
	v_cvt_f32_i32_e32 v13, v13
	v_cvt_f32_i32_e32 v6, v6
	v_cvt_f32_i32_e32 v7, v7
	v_cvt_f32_i32_e32 v8, v8
	v_cvt_f32_i32_e32 v9, v9
	v_cvt_f32_i32_e32 v2, v2
	v_cvt_f32_i32_e32 v3, v3
	v_cvt_f32_i32_e32 v4, v4
	v_cvt_f32_i32_e32 v5, v5
	s_waitcnt vmcnt(0)
	v_add_u32_e32 v98, s10, v118
	v_or_b32_e32 v146, s11, v119
	v_lshl_add_u64 v[144:145], v[98:99], 2, s[68:69]
	v_lshlrev_b32_e32 v148, 2, v146
	global_load_dword v136, v[144:145], off
	global_load_dword v138, v[144:145], off offset:64
	global_load_dword v140, v[144:145], off offset:128
	global_load_dword v142, v[144:145], off offset:192
	global_load_dwordx4 v[120:123], v148, s[74:75]
	global_load_dwordx4 v[124:127], v148, s[74:75] offset:64
	global_load_dwordx4 v[128:131], v148, s[74:75] offset:128
	global_load_dwordx4 v[132:135], v148, s[74:75] offset:192
	v_lshlrev_b32_e32 v146, 1, v146
	v_mov_b32_e32 v147, v99
	v_lshlrev_b64 v[42:43], 12, v[98:99]
	v_lshl_add_u64 v[42:43], s[64:65], 0, v[42:43]
	v_lshl_add_u64 v[42:43], v[42:43], 0, v[146:147]
	v_or_b32_e32 v54, 16, v98
	v_mov_b32_e32 v55, v99
	v_lshlrev_b64 v[44:45], 12, v[54:55]
	v_lshl_add_u64 v[44:45], s[64:65], 0, v[44:45]
	v_lshl_add_u64 v[44:45], v[44:45], 0, v[146:147]
	v_or_b32_e32 v54, 32, v98
	v_mov_b32_e32 v55, v99
	v_lshlrev_b64 v[46:47], 12, v[54:55]
	v_lshl_add_u64 v[46:47], s[64:65], 0, v[46:47]
	v_lshl_add_u64 v[46:47], v[46:47], 0, v[146:147]
	v_or_b32_e32 v54, 48, v98
	v_mov_b32_e32 v55, v99
	v_lshlrev_b64 v[48:49], 12, v[54:55]
	v_lshl_add_u64 v[48:49], s[64:65], 0, v[48:49]
	v_lshl_add_u64 v[48:49], v[48:49], 0, v[146:147]
	s_waitcnt vmcnt(0)
	v_pk_mul_f32 v[94:95], v[136:137], v[94:95] op_sel_hi:[0,1]
	v_pk_mul_f32 v[96:97], v[136:137], v[96:97] op_sel_hi:[0,1]
	v_pk_mul_f32 v[94:95], v[120:121], v[94:95]
	v_pk_mul_f32 v[96:97], v[96:97], v[122:123]
	v_cvt_pk_bf16_f32 v94, v94, v95
	v_cvt_pk_bf16_f32 v95, v96, v97
	global_store_dwordx2 v[42:43], v[94:95], off
	v_pk_mul_f32 v[90:91], v[136:137], v[90:91] op_sel_hi:[0,1]
	v_pk_mul_f32 v[92:93], v[136:137], v[92:93] op_sel_hi:[0,1]
	v_pk_mul_f32 v[90:91], v[124:125], v[90:91]
	v_pk_mul_f32 v[92:93], v[92:93], v[126:127]
	v_cvt_pk_bf16_f32 v90, v90, v91
	v_cvt_pk_bf16_f32 v91, v92, v93
	global_store_dwordx2 v[42:43], v[90:91], off offset:32
	v_pk_mul_f32 v[86:87], v[136:137], v[86:87] op_sel_hi:[0,1]
	v_pk_mul_f32 v[88:89], v[136:137], v[88:89] op_sel_hi:[0,1]
	v_pk_mul_f32 v[86:87], v[128:129], v[86:87]
	v_pk_mul_f32 v[88:89], v[88:89], v[130:131]
	v_cvt_pk_bf16_f32 v86, v86, v87
	v_cvt_pk_bf16_f32 v87, v88, v89
	global_store_dwordx2 v[42:43], v[86:87], off offset:64
	v_pk_mul_f32 v[82:83], v[136:137], v[82:83] op_sel_hi:[0,1]
	v_pk_mul_f32 v[84:85], v[136:137], v[84:85] op_sel_hi:[0,1]
	v_pk_mul_f32 v[82:83], v[132:133], v[82:83]
	v_pk_mul_f32 v[84:85], v[84:85], v[134:135]
	v_cvt_pk_bf16_f32 v82, v82, v83
	v_cvt_pk_bf16_f32 v83, v84, v85
	global_store_dwordx2 v[42:43], v[82:83], off offset:96
	v_pk_mul_f32 v[74:75], v[138:139], v[74:75] op_sel_hi:[0,1]
	v_pk_mul_f32 v[76:77], v[138:139], v[76:77] op_sel_hi:[0,1]
	v_pk_mul_f32 v[74:75], v[120:121], v[74:75]
	v_pk_mul_f32 v[76:77], v[76:77], v[122:123]
	v_cvt_pk_bf16_f32 v74, v74, v75
	v_cvt_pk_bf16_f32 v75, v76, v77
	global_store_dwordx2 v[44:45], v[74:75], off
	v_pk_mul_f32 v[50:51], v[138:139], v[50:51] op_sel_hi:[0,1]
	v_pk_mul_f32 v[52:53], v[138:139], v[52:53] op_sel_hi:[0,1]
	v_pk_mul_f32 v[50:51], v[124:125], v[50:51]
	v_pk_mul_f32 v[52:53], v[52:53], v[126:127]
	v_cvt_pk_bf16_f32 v50, v50, v51
	v_cvt_pk_bf16_f32 v51, v52, v53
	global_store_dwordx2 v[44:45], v[50:51], off offset:32
	v_pk_mul_f32 v[38:39], v[138:139], v[38:39] op_sel_hi:[0,1]
	v_pk_mul_f32 v[40:41], v[138:139], v[40:41] op_sel_hi:[0,1]
	v_pk_mul_f32 v[38:39], v[128:129], v[38:39]
	v_pk_mul_f32 v[40:41], v[40:41], v[130:131]
	v_cvt_pk_bf16_f32 v38, v38, v39
	v_cvt_pk_bf16_f32 v39, v40, v41
	global_store_dwordx2 v[44:45], v[38:39], off offset:64
	v_pk_mul_f32 v[30:31], v[138:139], v[30:31] op_sel_hi:[0,1]
	v_pk_mul_f32 v[32:33], v[138:139], v[32:33] op_sel_hi:[0,1]
	v_pk_mul_f32 v[30:31], v[132:133], v[30:31]
	v_pk_mul_f32 v[32:33], v[32:33], v[134:135]
	v_cvt_pk_bf16_f32 v30, v30, v31
	v_cvt_pk_bf16_f32 v31, v32, v33
	global_store_dwordx2 v[44:45], v[30:31], off offset:96
	v_pk_mul_f32 v[34:35], v[140:141], v[34:35] op_sel_hi:[0,1]
	v_pk_mul_f32 v[36:37], v[140:141], v[36:37] op_sel_hi:[0,1]
	v_pk_mul_f32 v[34:35], v[120:121], v[34:35]
	v_pk_mul_f32 v[36:37], v[36:37], v[122:123]
	v_cvt_pk_bf16_f32 v34, v34, v35
	v_cvt_pk_bf16_f32 v35, v36, v37
	global_store_dwordx2 v[46:47], v[34:35], off
	v_pk_mul_f32 v[26:27], v[140:141], v[26:27] op_sel_hi:[0,1]
	v_pk_mul_f32 v[28:29], v[140:141], v[28:29] op_sel_hi:[0,1]
	v_pk_mul_f32 v[26:27], v[124:125], v[26:27]
	v_pk_mul_f32 v[28:29], v[28:29], v[126:127]
	v_cvt_pk_bf16_f32 v26, v26, v27
	v_cvt_pk_bf16_f32 v27, v28, v29
	global_store_dwordx2 v[46:47], v[26:27], off offset:32
	v_pk_mul_f32 v[22:23], v[140:141], v[22:23] op_sel_hi:[0,1]
	v_pk_mul_f32 v[24:25], v[140:141], v[24:25] op_sel_hi:[0,1]
	v_pk_mul_f32 v[22:23], v[128:129], v[22:23]
	v_pk_mul_f32 v[24:25], v[24:25], v[130:131]
	v_cvt_pk_bf16_f32 v22, v22, v23
	v_cvt_pk_bf16_f32 v23, v24, v25
	global_store_dwordx2 v[46:47], v[22:23], off offset:64
	v_pk_mul_f32 v[18:19], v[140:141], v[18:19] op_sel_hi:[0,1]
	v_pk_mul_f32 v[20:21], v[140:141], v[20:21] op_sel_hi:[0,1]
	v_pk_mul_f32 v[18:19], v[132:133], v[18:19]
	v_pk_mul_f32 v[20:21], v[20:21], v[134:135]
	v_cvt_pk_bf16_f32 v18, v18, v19
	v_cvt_pk_bf16_f32 v19, v20, v21
	global_store_dwordx2 v[46:47], v[18:19], off offset:96
	v_pk_mul_f32 v[14:15], v[142:143], v[14:15] op_sel_hi:[0,1]
	v_pk_mul_f32 v[16:17], v[142:143], v[16:17] op_sel_hi:[0,1]
	v_pk_mul_f32 v[14:15], v[120:121], v[14:15]
	v_pk_mul_f32 v[16:17], v[16:17], v[122:123]
	v_cvt_pk_bf16_f32 v14, v14, v15
	v_cvt_pk_bf16_f32 v15, v16, v17
	global_store_dwordx2 v[48:49], v[14:15], off
	v_pk_mul_f32 v[10:11], v[142:143], v[10:11] op_sel_hi:[0,1]
	v_pk_mul_f32 v[12:13], v[142:143], v[12:13] op_sel_hi:[0,1]
	v_pk_mul_f32 v[10:11], v[124:125], v[10:11]
	v_pk_mul_f32 v[12:13], v[12:13], v[126:127]
	v_cvt_pk_bf16_f32 v10, v10, v11
	v_cvt_pk_bf16_f32 v11, v12, v13
	global_store_dwordx2 v[48:49], v[10:11], off offset:32
	v_pk_mul_f32 v[6:7], v[142:143], v[6:7] op_sel_hi:[0,1]
	v_pk_mul_f32 v[8:9], v[142:143], v[8:9] op_sel_hi:[0,1]
	v_pk_mul_f32 v[6:7], v[128:129], v[6:7]
	v_pk_mul_f32 v[8:9], v[8:9], v[130:131]
	v_cvt_pk_bf16_f32 v6, v6, v7
	v_cvt_pk_bf16_f32 v7, v8, v9
	global_store_dwordx2 v[48:49], v[6:7], off offset:64
	v_pk_mul_f32 v[2:3], v[142:143], v[2:3] op_sel_hi:[0,1]
	v_pk_mul_f32 v[4:5], v[142:143], v[4:5] op_sel_hi:[0,1]
	v_pk_mul_f32 v[2:3], v[132:133], v[2:3]
	v_pk_mul_f32 v[4:5], v[4:5], v[134:135]
	v_cvt_pk_bf16_f32 v2, v2, v3
	v_cvt_pk_bf16_f32 v3, v4, v5
	global_store_dwordx2 v[48:49], v[2:3], off offset:96
	s_add_i32 s6, s6, s3
	s_cmpk_lt_u32 s6, 0x200
	s_cbranch_scc1 .LBB0_518

.LBB0_664:
	s_cmpk_lt_u32 s3, 0x1c0
	s_cselect_b32 s4, 1, 2
	s_cselect_b32 s13, 7, 6
	s_cmpk_gt_u32 s3, 0xdf
	s_cselect_b32 s4, s4, 0
	s_mul_i32 s14, s4, 0xff20
	s_add_i32 s16, s14, s3
	s_sext_i32_i16 s14, s16
	v_cvt_f32_ubyte0_e32 v3, s13
	v_cvt_f32_i32_e32 v2, s14
	v_rcp_iflag_f32_e32 v4, v3
	s_ashr_i32 s14, s14, 30
	s_or_b32 s17, s14, 1
	s_mul_i32 s4, s4, 7
	v_mul_f32_e32 v4, v2, v4
	v_trunc_f32_e32 v4, v4
	v_fma_f32 v2, -v4, v3, v2
	v_cvt_i32_f32_e32 v4, v4
	v_cmp_ge_f32_e64 s[14:15], |v2|, v3
	s_and_b64 s[14:15], s[14:15], exec
	s_cselect_b32 s14, s17, 0
	v_readfirstlane_b32 s15, v4
	s_add_i32 s14, s15, s14
	s_sext_i32_i16 s15, s14
	s_mul_i32 s14, s14, s13
	s_sub_i32 s13, s16, s14
	s_sext_i32_i16 s13, s13
	s_add_i32 s4, s4, s13
	s_lshl_b32 s13, s15, 10
	s_or_b32 s13, s13, s6
	v_or_b32_e32 v2, s13, v1
	v_ashrrev_i32_e32 v3, 31, v2
	s_lshl_b32 s14, s4, 7
	v_lshlrev_b64 v[2:3], 12, v[2:3]
	v_lshl_add_u64 v[104:105], v[100:101], 0, v[2:3]
	v_or_b32_e32 v2, s14, v1
	v_ashrrev_i32_e32 v3, 31, v2
	v_lshlrev_b64 v[2:3], 11, v[2:3]
	v_add_co_u32_e32 v6, vcc, s7, v104
	v_lshl_add_u64 v[108:109], v[102:103], 0, v[2:3]
	v_and_b32_e32 v181, 7, v106
	v_bfe_u32 v180, v106, 3, 3
	v_xor_b32_e32 v180, v181, v180
	v_sub_u32_e32 v180, v180, v181
	v_lshlrev_b32_e32 v180, 4, v180
	v_ashrrev_i32_e32 v181, 31, v180
	v_lshrrev_b32_e32 v186, 6, v106
	v_mov_b32_e32 v187, 0x110
	v_lshl_add_u32 v186, v186, 10, v187
	v_lshl_add_u64 v[188:189], v[104:105], 0, v[180:181]
	v_lshl_add_u64 v[196:197], v[108:109], 0, v[180:181]
	v_readfirstlane_b32 s17, v186
	v_add_co_u32_e32 v190, vcc, s7, v188
	v_addc_co_u32_e32 v191, vcc, 0, v189, vcc
	v_add_co_u32_e32 v192, vcc, s9, v188
	v_addc_co_u32_e32 v193, vcc, 0, v189, vcc
	v_add_co_u32_e32 v194, vcc, s10, v188
	v_addc_co_u32_e32 v195, vcc, 0, v189, vcc
	v_add_co_u32_e32 v198, vcc, s8, v196
	v_addc_co_u32_e32 v199, vcc, 0, v197, vcc
	v_add_co_u32_e32 v200, vcc, s7, v196
	v_addc_co_u32_e32 v201, vcc, 0, v197, vcc
	v_add_co_u32_e32 v202, vcc, s11, v196
	v_addc_co_u32_e32 v203, vcc, 0, v197, vcc
	v_mov_b32_e32 v34, 0
	v_mov_b32_e32 v35, v99
	v_mov_b32_e32 v36, v99
	v_mov_b32_e32 v37, v99
	v_mov_b32_e32 v38, 0
	v_mov_b32_e32 v39, v99
	v_mov_b32_e32 v40, v99
	v_mov_b32_e32 v41, v99
	v_mov_b32_e32 v42, 0
	v_mov_b32_e32 v43, v99
	v_mov_b32_e32 v44, v99
	v_mov_b32_e32 v45, v99
	v_mov_b32_e32 v54, 0
	v_mov_b32_e32 v55, v99
	v_mov_b32_e32 v56, v99
	v_mov_b32_e32 v57, v99
	v_mov_b32_e32 v82, 0
	v_mov_b32_e32 v83, v99
	v_mov_b32_e32 v84, v99
	v_mov_b32_e32 v85, v99
	v_mov_b32_e32 v86, 0
	v_mov_b32_e32 v87, v99
	v_mov_b32_e32 v88, v99
	v_mov_b32_e32 v89, v99
	v_mov_b32_e32 v90, 0
	v_mov_b32_e32 v91, v99
	v_mov_b32_e32 v92, v99
	v_mov_b32_e32 v93, v99
	v_mov_b32_e32 v94, 0
	v_mov_b32_e32 v95, v99
	v_mov_b32_e32 v96, v99
	v_mov_b32_e32 v97, v99
	v_mov_b32_e32 v78, 0
	v_mov_b32_e32 v79, v99
	v_mov_b32_e32 v80, v99
	v_mov_b32_e32 v81, v99
	v_mov_b32_e32 v74, 0
	v_mov_b32_e32 v75, v99
	v_mov_b32_e32 v76, v99
	v_mov_b32_e32 v77, v99
	v_mov_b32_e32 v70, 0
	v_mov_b32_e32 v71, v99
	v_mov_b32_e32 v72, v99
	v_mov_b32_e32 v73, v99
	v_mov_b32_e32 v66, 0
	v_mov_b32_e32 v67, v99
	v_mov_b32_e32 v68, v99
	v_mov_b32_e32 v69, v99
	v_mov_b32_e32 v62, 0
	v_mov_b32_e32 v63, v99
	v_mov_b32_e32 v64, v99
	v_mov_b32_e32 v65, v99
	v_mov_b32_e32 v58, 0
	v_mov_b32_e32 v59, v99
	v_mov_b32_e32 v60, v99
	v_mov_b32_e32 v61, v99
	v_mov_b32_e32 v50, 0
	v_mov_b32_e32 v51, v99
	v_mov_b32_e32 v52, v99
	v_mov_b32_e32 v53, v99
	v_mov_b32_e32 v46, 0
	v_mov_b32_e32 v47, v99
	v_mov_b32_e32 v48, v99
	v_mov_b32_e32 v49, v99
	s_add_u32 m0, s17, 0x0
	s_nop 0
	global_load_lds_dwordx4 v[188:189], off
	s_add_u32 m0, s17, 0x1000
	s_nop 0
	global_load_lds_dwordx4 v[190:191], off
	s_add_u32 m0, s17, 0x2000
	s_nop 0
	global_load_lds_dwordx4 v[192:193], off
	s_add_u32 m0, s17, 0x3000
	s_nop 0
	global_load_lds_dwordx4 v[194:195], off
	s_add_u32 m0, s17, 0x4000
	s_nop 0
	global_load_lds_dwordx4 v[196:197], off
	s_add_u32 m0, s17, 0x5000
	s_nop 0
	global_load_lds_dwordx4 v[198:199], off
	s_add_u32 m0, s17, 0x6000
	s_nop 0
	global_load_lds_dwordx4 v[200:201], off
	s_add_u32 m0, s17, 0x7000
	s_nop 0
	global_load_lds_dwordx4 v[202:203], off
	s_mov_b32 s4, 0x80
	s_add_u32 m0, s17, 0x8000
	v_lshl_add_u64 v[204:205], v[188:189], 0, s[4:5]
	global_load_lds_dwordx4 v[204:205], off
	s_add_u32 m0, s17, 0x9000
	v_lshl_add_u64 v[206:207], v[190:191], 0, s[4:5]
	global_load_lds_dwordx4 v[206:207], off
	s_add_u32 m0, s17, 0xa000
	v_lshl_add_u64 v[204:205], v[192:193], 0, s[4:5]
	global_load_lds_dwordx4 v[204:205], off
	s_add_u32 m0, s17, 0xb000
	v_lshl_add_u64 v[206:207], v[194:195], 0, s[4:5]
	global_load_lds_dwordx4 v[206:207], off
	s_add_u32 m0, s17, 0xc000
	v_lshl_add_u64 v[204:205], v[196:197], 0, s[4:5]
	global_load_lds_dwordx4 v[204:205], off
	s_add_u32 m0, s17, 0xd000
	v_lshl_add_u64 v[206:207], v[198:199], 0, s[4:5]
	global_load_lds_dwordx4 v[206:207], off
	s_add_u32 m0, s17, 0xe000
	v_lshl_add_u64 v[204:205], v[200:201], 0, s[4:5]
	global_load_lds_dwordx4 v[204:205], off
	s_add_u32 m0, s17, 0xf000
	v_lshl_add_u64 v[206:207], v[202:203], 0, s[4:5]
	global_load_lds_dwordx4 v[206:207], off
	s_mov_b32 s16, 0
	s_mov_b32 s15, 0
	s_waitcnt vmcnt(8)
	s_barrier
.Lglds2_22142:
	ds_read_b128 v[152:155], v112 offset:16384
	ds_read_b128 v[156:159], v112 offset:18432
	ds_read_b128 v[160:163], v110
	ds_read_b128 v[164:167], v110 offset:2048
	ds_read_b128 v[168:171], v112 offset:20480
	ds_read_b128 v[172:175], v113 offset:16384
	ds_read_b128 v[208:211], v110 offset:4096
	ds_read_b128 v[212:215], v111
	ds_read_b128 v[216:219], v116 offset:16384
	ds_read_b128 v[220:223], v116 offset:18432
	ds_read_b128 v[224:227], v114
	ds_read_b128 v[228:231], v114 offset:2048
	ds_read_b128 v[232:235], v116 offset:20480
	ds_read_b128 v[236:239], v117 offset:16384
	ds_read_b128 v[240:243], v114 offset:4096
	ds_read_b128 v[244:247], v115
	s_setprio 1
	s_waitcnt lgkmcnt(13)
	v_mfma_f32_16x16x32_bf16 v[94:97], v[152:155], v[160:163], v[94:97]
	v_mfma_f32_16x16x32_bf16 v[90:93], v[156:159], v[160:163], v[90:93]
	s_waitcnt lgkmcnt(11)
	v_mfma_f32_16x16x32_bf16 v[86:89], v[168:171], v[160:163], v[86:89]
	s_waitcnt lgkmcnt(10)
	v_mfma_f32_16x16x32_bf16 v[82:85], v[172:175], v[160:163], v[82:85]
	v_mfma_f32_16x16x32_bf16 v[54:57], v[152:155], v[164:167], v[54:57]
	v_mfma_f32_16x16x32_bf16 v[42:45], v[156:159], v[164:167], v[42:45]
	v_mfma_f32_16x16x32_bf16 v[38:41], v[168:171], v[164:167], v[38:41]
	v_mfma_f32_16x16x32_bf16 v[34:37], v[172:175], v[164:167], v[34:37]
	s_waitcnt lgkmcnt(9)
	v_mfma_f32_16x16x32_bf16 v[78:81], v[152:155], v[208:211], v[78:81]
	v_mfma_f32_16x16x32_bf16 v[74:77], v[156:159], v[208:211], v[74:77]
	v_mfma_f32_16x16x32_bf16 v[70:73], v[168:171], v[208:211], v[70:73]
	v_mfma_f32_16x16x32_bf16 v[66:69], v[172:175], v[208:211], v[66:69]
	s_waitcnt lgkmcnt(8)
	v_mfma_f32_16x16x32_bf16 v[62:65], v[152:155], v[212:215], v[62:65]
	v_mfma_f32_16x16x32_bf16 v[58:61], v[156:159], v[212:215], v[58:61]
	v_mfma_f32_16x16x32_bf16 v[50:53], v[168:171], v[212:215], v[50:53]
	v_mfma_f32_16x16x32_bf16 v[46:49], v[172:175], v[212:215], v[46:49]
	s_setprio 0
	s_waitcnt lgkmcnt(0)
	s_barrier
	s_add_i32 s4, s16, 0x80
	s_min_u32 s4, s4, 0x3c0
	s_lshl_b32 s4, s4, 1
	s_setprio 1
	v_mfma_f32_16x16x32_bf16 v[94:97], v[216:219], v[224:227], v[94:97]
	s_add_u32 m0, s17, 0x0
	v_lshl_add_u64 v[204:205], v[188:189], 0, s[4:5]
	global_load_lds_dwordx4 v[204:205], off
	v_mfma_f32_16x16x32_bf16 v[90:93], v[220:223], v[224:227], v[90:93]
	v_mfma_f32_16x16x32_bf16 v[86:89], v[232:235], v[224:227], v[86:89]
	s_add_u32 m0, s17, 0x1000
	v_lshl_add_u64 v[206:207], v[190:191], 0, s[4:5]
	global_load_lds_dwordx4 v[206:207], off
	v_mfma_f32_16x16x32_bf16 v[82:85], v[236:239], v[224:227], v[82:85]
	v_mfma_f32_16x16x32_bf16 v[54:57], v[216:219], v[228:231], v[54:57]
	s_add_u32 m0, s17, 0x2000
	v_lshl_add_u64 v[204:205], v[192:193], 0, s[4:5]
	global_load_lds_dwordx4 v[204:205], off
	v_mfma_f32_16x16x32_bf16 v[42:45], v[220:223], v[228:231], v[42:45]
	v_mfma_f32_16x16x32_bf16 v[38:41], v[232:235], v[228:231], v[38:41]
	s_add_u32 m0, s17, 0x3000
	v_lshl_add_u64 v[206:207], v[194:195], 0, s[4:5]
	global_load_lds_dwordx4 v[206:207], off
	v_mfma_f32_16x16x32_bf16 v[34:37], v[236:239], v[228:231], v[34:37]
	v_mfma_f32_16x16x32_bf16 v[78:81], v[216:219], v[240:243], v[78:81]
	s_add_u32 m0, s17, 0x4000
	v_lshl_add_u64 v[204:205], v[196:197], 0, s[4:5]
	global_load_lds_dwordx4 v[204:205], off
	v_mfma_f32_16x16x32_bf16 v[74:77], v[220:223], v[240:243], v[74:77]
	v_mfma_f32_16x16x32_bf16 v[70:73], v[232:235], v[240:243], v[70:73]
	s_add_u32 m0, s17, 0x5000
	v_lshl_add_u64 v[206:207], v[198:199], 0, s[4:5]
	global_load_lds_dwordx4 v[206:207], off
	v_mfma_f32_16x16x32_bf16 v[66:69], v[236:239], v[240:243], v[66:69]
	v_mfma_f32_16x16x32_bf16 v[62:65], v[216:219], v[244:247], v[62:65]
	s_add_u32 m0, s17, 0x6000
	v_lshl_add_u64 v[204:205], v[200:201], 0, s[4:5]
	global_load_lds_dwordx4 v[204:205], off
	v_mfma_f32_16x16x32_bf16 v[58:61], v[220:223], v[244:247], v[58:61]
	v_mfma_f32_16x16x32_bf16 v[50:53], v[232:235], v[244:247], v[50:53]
	s_add_u32 m0, s17, 0x7000
	v_lshl_add_u64 v[206:207], v[202:203], 0, s[4:5]
	global_load_lds_dwordx4 v[206:207], off
	v_mfma_f32_16x16x32_bf16 v[46:49], v[236:239], v[244:247], v[46:49]
	s_setprio 0
	s_waitcnt vmcnt(8)
	s_barrier
	ds_read_b128 v[152:155], v112 offset:49152
	ds_read_b128 v[156:159], v112 offset:51200
	ds_read_b128 v[160:163], v110 offset:32768
	ds_read_b128 v[164:167], v110 offset:34816
	ds_read_b128 v[168:171], v112 offset:53248
	ds_read_b128 v[172:175], v113 offset:49152
	ds_read_b128 v[208:211], v110 offset:36864
	ds_read_b128 v[212:215], v111 offset:32768
	ds_read_b128 v[216:219], v116 offset:49152
	ds_read_b128 v[220:223], v116 offset:51200
	ds_read_b128 v[224:227], v114 offset:32768
	ds_read_b128 v[228:231], v114 offset:34816
	ds_read_b128 v[232:235], v116 offset:53248
	ds_read_b128 v[236:239], v117 offset:49152
	ds_read_b128 v[240:243], v114 offset:36864
	ds_read_b128 v[244:247], v115 offset:32768
	s_setprio 1
	s_waitcnt lgkmcnt(13)
	v_mfma_f32_16x16x32_bf16 v[94:97], v[152:155], v[160:163], v[94:97]
	v_mfma_f32_16x16x32_bf16 v[90:93], v[156:159], v[160:163], v[90:93]
	s_waitcnt lgkmcnt(11)
	v_mfma_f32_16x16x32_bf16 v[86:89], v[168:171], v[160:163], v[86:89]
	s_waitcnt lgkmcnt(10)
	v_mfma_f32_16x16x32_bf16 v[82:85], v[172:175], v[160:163], v[82:85]
	v_mfma_f32_16x16x32_bf16 v[54:57], v[152:155], v[164:167], v[54:57]
	v_mfma_f32_16x16x32_bf16 v[42:45], v[156:159], v[164:167], v[42:45]
	v_mfma_f32_16x16x32_bf16 v[38:41], v[168:171], v[164:167], v[38:41]
	v_mfma_f32_16x16x32_bf16 v[34:37], v[172:175], v[164:167], v[34:37]
	s_waitcnt lgkmcnt(9)
	v_mfma_f32_16x16x32_bf16 v[78:81], v[152:155], v[208:211], v[78:81]
	v_mfma_f32_16x16x32_bf16 v[74:77], v[156:159], v[208:211], v[74:77]
	v_mfma_f32_16x16x32_bf16 v[70:73], v[168:171], v[208:211], v[70:73]
	v_mfma_f32_16x16x32_bf16 v[66:69], v[172:175], v[208:211], v[66:69]
	s_waitcnt lgkmcnt(8)
	v_mfma_f32_16x16x32_bf16 v[62:65], v[152:155], v[212:215], v[62:65]
	v_mfma_f32_16x16x32_bf16 v[58:61], v[156:159], v[212:215], v[58:61]
	v_mfma_f32_16x16x32_bf16 v[50:53], v[168:171], v[212:215], v[50:53]
	v_mfma_f32_16x16x32_bf16 v[46:49], v[172:175], v[212:215], v[46:49]
	s_setprio 0
	s_waitcnt lgkmcnt(0)
	s_barrier
	s_add_i32 s4, s16, 0xc0
	s_min_u32 s4, s4, 0x3c0
	s_lshl_b32 s4, s4, 1
	s_setprio 1
	v_mfma_f32_16x16x32_bf16 v[94:97], v[216:219], v[224:227], v[94:97]
	s_add_u32 m0, s17, 0x8000
	v_lshl_add_u64 v[204:205], v[188:189], 0, s[4:5]
	global_load_lds_dwordx4 v[204:205], off
	v_mfma_f32_16x16x32_bf16 v[90:93], v[220:223], v[224:227], v[90:93]
	v_mfma_f32_16x16x32_bf16 v[86:89], v[232:235], v[224:227], v[86:89]
	s_add_u32 m0, s17, 0x9000
	v_lshl_add_u64 v[206:207], v[190:191], 0, s[4:5]
	global_load_lds_dwordx4 v[206:207], off
	v_mfma_f32_16x16x32_bf16 v[82:85], v[236:239], v[224:227], v[82:85]
	v_mfma_f32_16x16x32_bf16 v[54:57], v[216:219], v[228:231], v[54:57]
	s_add_u32 m0, s17, 0xa000
	v_lshl_add_u64 v[204:205], v[192:193], 0, s[4:5]
	global_load_lds_dwordx4 v[204:205], off
	v_mfma_f32_16x16x32_bf16 v[42:45], v[220:223], v[228:231], v[42:45]
	v_mfma_f32_16x16x32_bf16 v[38:41], v[232:235], v[228:231], v[38:41]
	s_add_u32 m0, s17, 0xb000
	v_lshl_add_u64 v[206:207], v[194:195], 0, s[4:5]
	global_load_lds_dwordx4 v[206:207], off
	v_mfma_f32_16x16x32_bf16 v[34:37], v[236:239], v[228:231], v[34:37]
	v_mfma_f32_16x16x32_bf16 v[78:81], v[216:219], v[240:243], v[78:81]
	s_add_u32 m0, s17, 0xc000
	v_lshl_add_u64 v[204:205], v[196:197], 0, s[4:5]
	global_load_lds_dwordx4 v[204:205], off
	v_mfma_f32_16x16x32_bf16 v[74:77], v[220:223], v[240:243], v[74:77]
	v_mfma_f32_16x16x32_bf16 v[70:73], v[232:235], v[240:243], v[70:73]
	s_add_u32 m0, s17, 0xd000
	v_lshl_add_u64 v[206:207], v[198:199], 0, s[4:5]
	global_load_lds_dwordx4 v[206:207], off
	v_mfma_f32_16x16x32_bf16 v[66:69], v[236:239], v[240:243], v[66:69]
	v_mfma_f32_16x16x32_bf16 v[62:65], v[216:219], v[244:247], v[62:65]
	s_add_u32 m0, s17, 0xe000
	v_lshl_add_u64 v[204:205], v[200:201], 0, s[4:5]
	global_load_lds_dwordx4 v[204:205], off
	v_mfma_f32_16x16x32_bf16 v[58:61], v[220:223], v[244:247], v[58:61]
	v_mfma_f32_16x16x32_bf16 v[50:53], v[232:235], v[244:247], v[50:53]
	s_add_u32 m0, s17, 0xf000
	v_lshl_add_u64 v[206:207], v[202:203], 0, s[4:5]
	global_load_lds_dwordx4 v[206:207], off
	v_mfma_f32_16x16x32_bf16 v[46:49], v[236:239], v[244:247], v[46:49]
	s_setprio 0
	s_waitcnt vmcnt(8)
	s_barrier
	s_add_i32 s16, s16, 0x80
	s_add_i32 s15, s15, 2
	s_cmp_lt_u32 s15, 14
	s_cbranch_scc1 .Lglds2_22142
	ds_read_b128 v[152:155], v112 offset:16384
	ds_read_b128 v[156:159], v112 offset:18432
	ds_read_b128 v[160:163], v110
	ds_read_b128 v[164:167], v110 offset:2048
	ds_read_b128 v[168:171], v112 offset:20480
	ds_read_b128 v[172:175], v113 offset:16384
	ds_read_b128 v[208:211], v110 offset:4096
	ds_read_b128 v[212:215], v111
	ds_read_b128 v[216:219], v116 offset:16384
	ds_read_b128 v[220:223], v116 offset:18432
	ds_read_b128 v[224:227], v114
	ds_read_b128 v[228:231], v114 offset:2048
	ds_read_b128 v[232:235], v116 offset:20480
	ds_read_b128 v[236:239], v117 offset:16384
	ds_read_b128 v[240:243], v114 offset:4096
	ds_read_b128 v[244:247], v115
	s_setprio 1
	s_waitcnt lgkmcnt(13)
	v_mfma_f32_16x16x32_bf16 v[94:97], v[152:155], v[160:163], v[94:97]
	v_mfma_f32_16x16x32_bf16 v[90:93], v[156:159], v[160:163], v[90:93]
	s_waitcnt lgkmcnt(11)
	v_mfma_f32_16x16x32_bf16 v[86:89], v[168:171], v[160:163], v[86:89]
	s_waitcnt lgkmcnt(10)
	v_mfma_f32_16x16x32_bf16 v[82:85], v[172:175], v[160:163], v[82:85]
	v_mfma_f32_16x16x32_bf16 v[54:57], v[152:155], v[164:167], v[54:57]
	v_mfma_f32_16x16x32_bf16 v[42:45], v[156:159], v[164:167], v[42:45]
	v_mfma_f32_16x16x32_bf16 v[38:41], v[168:171], v[164:167], v[38:41]
	v_mfma_f32_16x16x32_bf16 v[34:37], v[172:175], v[164:167], v[34:37]
	s_waitcnt lgkmcnt(9)
	v_mfma_f32_16x16x32_bf16 v[78:81], v[152:155], v[208:211], v[78:81]
	v_mfma_f32_16x16x32_bf16 v[74:77], v[156:159], v[208:211], v[74:77]
	v_mfma_f32_16x16x32_bf16 v[70:73], v[168:171], v[208:211], v[70:73]
	v_mfma_f32_16x16x32_bf16 v[66:69], v[172:175], v[208:211], v[66:69]
	s_waitcnt lgkmcnt(8)
	v_mfma_f32_16x16x32_bf16 v[62:65], v[152:155], v[212:215], v[62:65]
	v_mfma_f32_16x16x32_bf16 v[58:61], v[156:159], v[212:215], v[58:61]
	v_mfma_f32_16x16x32_bf16 v[50:53], v[168:171], v[212:215], v[50:53]
	v_mfma_f32_16x16x32_bf16 v[46:49], v[172:175], v[212:215], v[46:49]
	s_setprio 0
	s_waitcnt lgkmcnt(0)
	s_setprio 1
	v_mfma_f32_16x16x32_bf16 v[94:97], v[216:219], v[224:227], v[94:97]
	v_mfma_f32_16x16x32_bf16 v[90:93], v[220:223], v[224:227], v[90:93]
	v_mfma_f32_16x16x32_bf16 v[86:89], v[232:235], v[224:227], v[86:89]
	v_mfma_f32_16x16x32_bf16 v[82:85], v[236:239], v[224:227], v[82:85]
	v_mfma_f32_16x16x32_bf16 v[54:57], v[216:219], v[228:231], v[54:57]
	v_mfma_f32_16x16x32_bf16 v[42:45], v[220:223], v[228:231], v[42:45]
	v_mfma_f32_16x16x32_bf16 v[38:41], v[232:235], v[228:231], v[38:41]
	v_mfma_f32_16x16x32_bf16 v[34:37], v[236:239], v[228:231], v[34:37]
	v_mfma_f32_16x16x32_bf16 v[78:81], v[216:219], v[240:243], v[78:81]
	v_mfma_f32_16x16x32_bf16 v[74:77], v[220:223], v[240:243], v[74:77]
	v_mfma_f32_16x16x32_bf16 v[70:73], v[232:235], v[240:243], v[70:73]
	v_mfma_f32_16x16x32_bf16 v[66:69], v[236:239], v[240:243], v[66:69]
	v_mfma_f32_16x16x32_bf16 v[62:65], v[216:219], v[244:247], v[62:65]
	v_mfma_f32_16x16x32_bf16 v[58:61], v[220:223], v[244:247], v[58:61]
	v_mfma_f32_16x16x32_bf16 v[50:53], v[232:235], v[244:247], v[50:53]
	v_mfma_f32_16x16x32_bf16 v[46:49], v[236:239], v[244:247], v[46:49]
	s_setprio 0
	s_waitcnt vmcnt(0)
	s_barrier
	ds_read_b128 v[152:155], v112 offset:49152
	ds_read_b128 v[156:159], v112 offset:51200
	ds_read_b128 v[160:163], v110 offset:32768
	ds_read_b128 v[164:167], v110 offset:34816
	ds_read_b128 v[168:171], v112 offset:53248
	ds_read_b128 v[172:175], v113 offset:49152
	ds_read_b128 v[208:211], v110 offset:36864
	ds_read_b128 v[212:215], v111 offset:32768
	ds_read_b128 v[216:219], v116 offset:49152
	ds_read_b128 v[220:223], v116 offset:51200
	ds_read_b128 v[224:227], v114 offset:32768
	ds_read_b128 v[228:231], v114 offset:34816
	ds_read_b128 v[232:235], v116 offset:53248
	ds_read_b128 v[236:239], v117 offset:49152
	ds_read_b128 v[240:243], v114 offset:36864
	ds_read_b128 v[244:247], v115 offset:32768
	s_setprio 1
	s_waitcnt lgkmcnt(13)
	v_mfma_f32_16x16x32_bf16 v[94:97], v[152:155], v[160:163], v[94:97]
	v_mfma_f32_16x16x32_bf16 v[90:93], v[156:159], v[160:163], v[90:93]
	s_waitcnt lgkmcnt(11)
	v_mfma_f32_16x16x32_bf16 v[86:89], v[168:171], v[160:163], v[86:89]
	s_waitcnt lgkmcnt(10)
	v_mfma_f32_16x16x32_bf16 v[82:85], v[172:175], v[160:163], v[82:85]
	v_mfma_f32_16x16x32_bf16 v[54:57], v[152:155], v[164:167], v[54:57]
	v_mfma_f32_16x16x32_bf16 v[42:45], v[156:159], v[164:167], v[42:45]
	v_mfma_f32_16x16x32_bf16 v[38:41], v[168:171], v[164:167], v[38:41]
	v_mfma_f32_16x16x32_bf16 v[34:37], v[172:175], v[164:167], v[34:37]
	s_waitcnt lgkmcnt(9)
	v_mfma_f32_16x16x32_bf16 v[78:81], v[152:155], v[208:211], v[78:81]
	v_mfma_f32_16x16x32_bf16 v[74:77], v[156:159], v[208:211], v[74:77]
	v_mfma_f32_16x16x32_bf16 v[70:73], v[168:171], v[208:211], v[70:73]
	v_mfma_f32_16x16x32_bf16 v[66:69], v[172:175], v[208:211], v[66:69]
	s_waitcnt lgkmcnt(8)
	v_mfma_f32_16x16x32_bf16 v[62:65], v[152:155], v[212:215], v[62:65]
	v_mfma_f32_16x16x32_bf16 v[58:61], v[156:159], v[212:215], v[58:61]
	v_mfma_f32_16x16x32_bf16 v[50:53], v[168:171], v[212:215], v[50:53]
	v_mfma_f32_16x16x32_bf16 v[46:49], v[172:175], v[212:215], v[46:49]
	s_setprio 0
	s_waitcnt lgkmcnt(0)
	s_barrier
	s_setprio 1
	v_mfma_f32_16x16x32_bf16 v[94:97], v[216:219], v[224:227], v[94:97]
	v_mfma_f32_16x16x32_bf16 v[90:93], v[220:223], v[224:227], v[90:93]
	v_mfma_f32_16x16x32_bf16 v[86:89], v[232:235], v[224:227], v[86:89]
	v_mfma_f32_16x16x32_bf16 v[82:85], v[236:239], v[224:227], v[82:85]
	v_mfma_f32_16x16x32_bf16 v[54:57], v[216:219], v[228:231], v[54:57]
	v_mfma_f32_16x16x32_bf16 v[42:45], v[220:223], v[228:231], v[42:45]
	v_mfma_f32_16x16x32_bf16 v[38:41], v[232:235], v[228:231], v[38:41]
	v_mfma_f32_16x16x32_bf16 v[34:37], v[236:239], v[228:231], v[34:37]
	v_mfma_f32_16x16x32_bf16 v[78:81], v[216:219], v[240:243], v[78:81]
	v_mfma_f32_16x16x32_bf16 v[74:77], v[220:223], v[240:243], v[74:77]
	v_mfma_f32_16x16x32_bf16 v[70:73], v[232:235], v[240:243], v[70:73]
	v_mfma_f32_16x16x32_bf16 v[66:69], v[236:239], v[240:243], v[66:69]
	v_mfma_f32_16x16x32_bf16 v[62:65], v[216:219], v[244:247], v[62:65]
	v_mfma_f32_16x16x32_bf16 v[58:61], v[220:223], v[244:247], v[58:61]
	v_mfma_f32_16x16x32_bf16 v[50:53], v[232:235], v[244:247], v[50:53]
	v_mfma_f32_16x16x32_bf16 v[46:49], v[236:239], v[244:247], v[46:49]
	s_setprio 0
	s_waitcnt vmcnt(0)
	s_waitcnt vmcnt(7)
	v_or_b32_e32 v2, s14, v119
	s_waitcnt vmcnt(5)
	v_add_u32_e32 v10, s13, v118
	v_mov_b64_e32 v[4:5], s[64:65]
	v_ashrrev_i32_e32 v3, 31, v2
	v_mad_i64_i32 v[6:7], s[14:15], v10, s12, v[4:5]
	v_lshlrev_b64 v[2:3], 1, v[2:3]
	v_lshl_add_u64 v[6:7], v[6:7], 0, v[2:3]
	v_cvt_pk_bf16_f32 v8, v94, v95
	v_cvt_pk_bf16_f32 v9, v96, v97
	global_store_dwordx2 v[6:7], v[8:9], off
	v_cvt_pk_bf16_f32 v8, v90, v91
	v_cvt_pk_bf16_f32 v9, v92, v93
	global_store_dwordx2 v[6:7], v[8:9], off offset:32
	v_cvt_pk_bf16_f32 v8, v86, v87
	v_cvt_pk_bf16_f32 v9, v88, v89
	global_store_dwordx2 v[6:7], v[8:9], off offset:64
	v_cvt_pk_bf16_f32 v8, v82, v83
	v_cvt_pk_bf16_f32 v9, v84, v85
	global_store_dwordx2 v[6:7], v[8:9], off offset:96
	v_or_b32_e32 v6, 16, v10
	v_mad_i64_i32 v[6:7], s[14:15], v6, s12, v[4:5]
	v_lshl_add_u64 v[6:7], v[6:7], 0, v[2:3]
	v_cvt_pk_bf16_f32 v8, v54, v55
	v_cvt_pk_bf16_f32 v9, v56, v57
	global_store_dwordx2 v[6:7], v[8:9], off
	v_cvt_pk_bf16_f32 v8, v42, v43
	v_cvt_pk_bf16_f32 v9, v44, v45
	global_store_dwordx2 v[6:7], v[8:9], off offset:32
	v_cvt_pk_bf16_f32 v8, v38, v39
	v_cvt_pk_bf16_f32 v9, v40, v41
	global_store_dwordx2 v[6:7], v[8:9], off offset:64
	v_cvt_pk_bf16_f32 v8, v34, v35
	v_cvt_pk_bf16_f32 v9, v36, v37
	global_store_dwordx2 v[6:7], v[8:9], off offset:96
	v_or_b32_e32 v6, 32, v10
	v_mad_i64_i32 v[6:7], s[14:15], v6, s12, v[4:5]
	v_lshl_add_u64 v[6:7], v[6:7], 0, v[2:3]
	v_cvt_pk_bf16_f32 v8, v78, v79
	v_cvt_pk_bf16_f32 v9, v80, v81
	global_store_dwordx2 v[6:7], v[8:9], off
	v_cvt_pk_bf16_f32 v8, v74, v75
	v_cvt_pk_bf16_f32 v9, v76, v77
	global_store_dwordx2 v[6:7], v[8:9], off offset:32
	v_cvt_pk_bf16_f32 v8, v70, v71
	v_cvt_pk_bf16_f32 v9, v72, v73
	global_store_dwordx2 v[6:7], v[8:9], off offset:64
	v_cvt_pk_bf16_f32 v8, v66, v67
	v_cvt_pk_bf16_f32 v9, v68, v69
	global_store_dwordx2 v[6:7], v[8:9], off offset:96
	v_or_b32_e32 v6, 48, v10
	v_mad_i64_i32 v[4:5], s[14:15], v6, s12, v[4:5]
	v_lshl_add_u64 v[2:3], v[4:5], 0, v[2:3]
	v_cvt_pk_bf16_f32 v4, v62, v63
	v_cvt_pk_bf16_f32 v5, v64, v65
	global_store_dwordx2 v[2:3], v[4:5], off
	v_cvt_pk_bf16_f32 v4, v58, v59
	v_cvt_pk_bf16_f32 v5, v60, v61
	global_store_dwordx2 v[2:3], v[4:5], off offset:32
	v_cvt_pk_bf16_f32 v4, v50, v51
	v_cvt_pk_bf16_f32 v5, v52, v53
	s_add_i32 s3, s3, s2
	global_store_dwordx2 v[2:3], v[4:5], off offset:64
	v_cvt_pk_bf16_f32 v4, v46, v47
	v_cvt_pk_bf16_f32 v5, v48, v49
	s_cmpk_lt_u32 s3, 0x280
	global_store_dwordx2 v[2:3], v[4:5], off offset:96
	s_cbranch_scc1 .LBB0_664

.LBB0_798:
	s_and_b32 s4, s7, 0xf8
	s_or_b32 s4, s4, s2
	s_lshl_b32 s11, s4, 7
	s_lshl_b32 s4, s7, 7
	v_or_b32_e32 v0, s11, v107
	s_and_b32 s12, s4, 0x380
	v_lshlrev_b32_e32 v96, 11, v0
	v_lshl_add_u64 v[102:103], v[100:101], 0, v[96:97]
	v_or_b32_e32 v0, s12, v107
	v_lshlrev_b32_e32 v96, 11, v0
	v_lshl_add_u64 v[104:105], v[98:99], 0, v[96:97]
	v_and_b32_e32 v181, 7, v106
	v_bfe_u32 v180, v106, 3, 3
	v_xor_b32_e32 v180, v181, v180
	v_sub_u32_e32 v180, v180, v181
	v_lshlrev_b32_e32 v180, 4, v180
	v_ashrrev_i32_e32 v181, 31, v180
	v_lshrrev_b32_e32 v186, 6, v106
	v_mov_b32_e32 v187, 0x110
	v_lshl_add_u32 v186, v186, 10, v187
	v_lshl_add_u64 v[188:189], v[102:103], 0, v[180:181]
	v_lshl_add_u64 v[196:197], v[104:105], 0, v[180:181]
	v_readfirstlane_b32 s15, v186
	v_add_co_u32_e32 v190, vcc, s8, v188
	v_addc_co_u32_e32 v191, vcc, 0, v189, vcc
	v_add_co_u32_e32 v192, vcc, s9, v188
	v_addc_co_u32_e32 v193, vcc, 0, v189, vcc
	v_add_co_u32_e32 v194, vcc, s10, v188
	v_addc_co_u32_e32 v195, vcc, 0, v189, vcc
	v_add_co_u32_e32 v198, vcc, s8, v196
	v_addc_co_u32_e32 v199, vcc, 0, v197, vcc
	v_add_co_u32_e32 v200, vcc, s9, v196
	v_addc_co_u32_e32 v201, vcc, 0, v197, vcc
	v_add_co_u32_e32 v202, vcc, s10, v196
	v_addc_co_u32_e32 v203, vcc, 0, v197, vcc
	v_mov_b32_e32 v28, 0
	v_mov_b32_e32 v29, v97
	v_mov_b32_e32 v30, v97
	v_mov_b32_e32 v31, v97
	v_mov_b32_e32 v60, 0
	v_mov_b32_e32 v61, v97
	v_mov_b32_e32 v62, v97
	v_mov_b32_e32 v63, v97
	v_mov_b32_e32 v72, 0
	v_mov_b32_e32 v73, v97
	v_mov_b32_e32 v74, v97
	v_mov_b32_e32 v75, v97
	v_mov_b32_e32 v76, 0
	v_mov_b32_e32 v77, v97
	v_mov_b32_e32 v78, v97
	v_mov_b32_e32 v79, v97
	v_mov_b32_e32 v80, 0
	v_mov_b32_e32 v81, v97
	v_mov_b32_e32 v82, v97
	v_mov_b32_e32 v83, v97
	v_mov_b32_e32 v84, 0
	v_mov_b32_e32 v85, v97
	v_mov_b32_e32 v86, v97
	v_mov_b32_e32 v87, v97
	v_mov_b32_e32 v88, 0
	v_mov_b32_e32 v89, v97
	v_mov_b32_e32 v90, v97
	v_mov_b32_e32 v91, v97
	v_mov_b32_e32 v92, 0
	v_mov_b32_e32 v93, v97
	v_mov_b32_e32 v94, v97
	v_mov_b32_e32 v95, v97
	v_mov_b32_e32 v64, 0
	v_mov_b32_e32 v65, v97
	v_mov_b32_e32 v66, v97
	v_mov_b32_e32 v67, v97
	v_mov_b32_e32 v36, 0
	v_mov_b32_e32 v37, v97
	v_mov_b32_e32 v38, v97
	v_mov_b32_e32 v39, v97
	v_mov_b32_e32 v32, 0
	v_mov_b32_e32 v33, v97
	v_mov_b32_e32 v34, v97
	v_mov_b32_e32 v35, v97
	v_mov_b32_e32 v16, 0
	v_mov_b32_e32 v17, v97
	v_mov_b32_e32 v18, v97
	v_mov_b32_e32 v19, v97
	v_mov_b32_e32 v12, 0
	v_mov_b32_e32 v13, v97
	v_mov_b32_e32 v14, v97
	v_mov_b32_e32 v15, v97
	v_mov_b32_e32 v8, 0
	v_mov_b32_e32 v9, v97
	v_mov_b32_e32 v10, v97
	v_mov_b32_e32 v11, v97
	v_mov_b32_e32 v4, 0
	v_mov_b32_e32 v5, v97
	v_mov_b32_e32 v6, v97
	v_mov_b32_e32 v7, v97
	v_mov_b32_e32 v0, 0
	v_mov_b32_e32 v1, v97
	v_mov_b32_e32 v2, v97
	v_mov_b32_e32 v3, v97
	s_add_u32 m0, s15, 0x0
	s_nop 0
	global_load_lds_dwordx4 v[188:189], off
	s_add_u32 m0, s15, 0x1000
	s_nop 0
	global_load_lds_dwordx4 v[190:191], off
	s_add_u32 m0, s15, 0x2000
	s_nop 0
	global_load_lds_dwordx4 v[192:193], off
	s_add_u32 m0, s15, 0x3000
	s_nop 0
	global_load_lds_dwordx4 v[194:195], off
	s_add_u32 m0, s15, 0x4000
	s_nop 0
	global_load_lds_dwordx4 v[196:197], off
	s_add_u32 m0, s15, 0x5000
	s_nop 0
	global_load_lds_dwordx4 v[198:199], off
	s_add_u32 m0, s15, 0x6000
	s_nop 0
	global_load_lds_dwordx4 v[200:201], off
	s_add_u32 m0, s15, 0x7000
	s_nop 0
	global_load_lds_dwordx4 v[202:203], off
	s_mov_b32 s4, 0x80
	s_add_u32 m0, s15, 0x8000
	v_lshl_add_u64 v[204:205], v[188:189], 0, s[4:5]
	global_load_lds_dwordx4 v[204:205], off
	s_add_u32 m0, s15, 0x9000
	v_lshl_add_u64 v[206:207], v[190:191], 0, s[4:5]
	global_load_lds_dwordx4 v[206:207], off
	s_add_u32 m0, s15, 0xa000
	v_lshl_add_u64 v[204:205], v[192:193], 0, s[4:5]
	global_load_lds_dwordx4 v[204:205], off
	s_add_u32 m0, s15, 0xb000
	v_lshl_add_u64 v[206:207], v[194:195], 0, s[4:5]
	global_load_lds_dwordx4 v[206:207], off
	s_add_u32 m0, s15, 0xc000
	v_lshl_add_u64 v[204:205], v[196:197], 0, s[4:5]
	global_load_lds_dwordx4 v[204:205], off
	s_add_u32 m0, s15, 0xd000
	v_lshl_add_u64 v[206:207], v[198:199], 0, s[4:5]
	global_load_lds_dwordx4 v[206:207], off
	s_add_u32 m0, s15, 0xe000
	v_lshl_add_u64 v[204:205], v[200:201], 0, s[4:5]
	global_load_lds_dwordx4 v[204:205], off
	s_add_u32 m0, s15, 0xf000
	v_lshl_add_u64 v[206:207], v[202:203], 0, s[4:5]
	global_load_lds_dwordx4 v[206:207], off
	s_mov_b32 s14, 0
	s_mov_b32 s13, 0
	s_waitcnt vmcnt(8)
	s_barrier
.Lglds2_26323:
	ds_read_b128 v[152:155], v111 offset:16384
	ds_read_b128 v[156:159], v111 offset:18432
	ds_read_b128 v[160:163], v109
	ds_read_b128 v[164:167], v109 offset:2048
	ds_read_b128 v[168:171], v111 offset:20480
	ds_read_b128 v[172:175], v112 offset:16384
	ds_read_b128 v[208:211], v109 offset:4096
	ds_read_b128 v[212:215], v110
	ds_read_b128 v[216:219], v115 offset:16384
	ds_read_b128 v[220:223], v115 offset:18432
	ds_read_b128 v[224:227], v113
	ds_read_b128 v[228:231], v113 offset:2048
	ds_read_b128 v[232:235], v115 offset:20480
	ds_read_b128 v[236:239], v116 offset:16384
	ds_read_b128 v[240:243], v113 offset:4096
	ds_read_b128 v[244:247], v114
	s_setprio 1
	s_waitcnt lgkmcnt(13)
	v_mfma_f32_16x16x32_bf16 v[92:95], v[152:155], v[160:163], v[92:95]
	v_mfma_f32_16x16x32_bf16 v[88:91], v[156:159], v[160:163], v[88:91]
	s_waitcnt lgkmcnt(11)
	v_mfma_f32_16x16x32_bf16 v[84:87], v[168:171], v[160:163], v[84:87]
	s_waitcnt lgkmcnt(10)
	v_mfma_f32_16x16x32_bf16 v[80:83], v[172:175], v[160:163], v[80:83]
	v_mfma_f32_16x16x32_bf16 v[76:79], v[152:155], v[164:167], v[76:79]
	v_mfma_f32_16x16x32_bf16 v[72:75], v[156:159], v[164:167], v[72:75]
	v_mfma_f32_16x16x32_bf16 v[60:63], v[168:171], v[164:167], v[60:63]
	v_mfma_f32_16x16x32_bf16 v[28:31], v[172:175], v[164:167], v[28:31]
	s_waitcnt lgkmcnt(9)
	v_mfma_f32_16x16x32_bf16 v[64:67], v[152:155], v[208:211], v[64:67]
	v_mfma_f32_16x16x32_bf16 v[36:39], v[156:159], v[208:211], v[36:39]
	v_mfma_f32_16x16x32_bf16 v[32:35], v[168:171], v[208:211], v[32:35]
	v_mfma_f32_16x16x32_bf16 v[16:19], v[172:175], v[208:211], v[16:19]
	s_waitcnt lgkmcnt(8)
	v_mfma_f32_16x16x32_bf16 v[12:15], v[152:155], v[212:215], v[12:15]
	v_mfma_f32_16x16x32_bf16 v[8:11], v[156:159], v[212:215], v[8:11]
	v_mfma_f32_16x16x32_bf16 v[4:7], v[168:171], v[212:215], v[4:7]
	v_mfma_f32_16x16x32_bf16 v[0:3], v[172:175], v[212:215], v[0:3]
	s_setprio 0
	s_waitcnt lgkmcnt(0)
	s_barrier
	s_add_i32 s4, s14, 0x80
	s_min_u32 s4, s4, 0x3c0
	s_lshl_b32 s4, s4, 1
	s_setprio 1
	v_mfma_f32_16x16x32_bf16 v[92:95], v[216:219], v[224:227], v[92:95]
	s_add_u32 m0, s15, 0x0
	v_lshl_add_u64 v[204:205], v[188:189], 0, s[4:5]
	global_load_lds_dwordx4 v[204:205], off
	v_mfma_f32_16x16x32_bf16 v[88:91], v[220:223], v[224:227], v[88:91]
	v_mfma_f32_16x16x32_bf16 v[84:87], v[232:235], v[224:227], v[84:87]
	s_add_u32 m0, s15, 0x1000
	v_lshl_add_u64 v[206:207], v[190:191], 0, s[4:5]
	global_load_lds_dwordx4 v[206:207], off
	v_mfma_f32_16x16x32_bf16 v[80:83], v[236:239], v[224:227], v[80:83]
	v_mfma_f32_16x16x32_bf16 v[76:79], v[216:219], v[228:231], v[76:79]
	s_add_u32 m0, s15, 0x2000
	v_lshl_add_u64 v[204:205], v[192:193], 0, s[4:5]
	global_load_lds_dwordx4 v[204:205], off
	v_mfma_f32_16x16x32_bf16 v[72:75], v[220:223], v[228:231], v[72:75]
	v_mfma_f32_16x16x32_bf16 v[60:63], v[232:235], v[228:231], v[60:63]
	s_add_u32 m0, s15, 0x3000
	v_lshl_add_u64 v[206:207], v[194:195], 0, s[4:5]
	global_load_lds_dwordx4 v[206:207], off
	v_mfma_f32_16x16x32_bf16 v[28:31], v[236:239], v[228:231], v[28:31]
	v_mfma_f32_16x16x32_bf16 v[64:67], v[216:219], v[240:243], v[64:67]
	s_add_u32 m0, s15, 0x4000
	v_lshl_add_u64 v[204:205], v[196:197], 0, s[4:5]
	global_load_lds_dwordx4 v[204:205], off
	v_mfma_f32_16x16x32_bf16 v[36:39], v[220:223], v[240:243], v[36:39]
	v_mfma_f32_16x16x32_bf16 v[32:35], v[232:235], v[240:243], v[32:35]
	s_add_u32 m0, s15, 0x5000
	v_lshl_add_u64 v[206:207], v[198:199], 0, s[4:5]
	global_load_lds_dwordx4 v[206:207], off
	v_mfma_f32_16x16x32_bf16 v[16:19], v[236:239], v[240:243], v[16:19]
	v_mfma_f32_16x16x32_bf16 v[12:15], v[216:219], v[244:247], v[12:15]
	s_add_u32 m0, s15, 0x6000
	v_lshl_add_u64 v[204:205], v[200:201], 0, s[4:5]
	global_load_lds_dwordx4 v[204:205], off
	v_mfma_f32_16x16x32_bf16 v[8:11], v[220:223], v[244:247], v[8:11]
	v_mfma_f32_16x16x32_bf16 v[4:7], v[232:235], v[244:247], v[4:7]
	s_add_u32 m0, s15, 0x7000
	v_lshl_add_u64 v[206:207], v[202:203], 0, s[4:5]
	global_load_lds_dwordx4 v[206:207], off
	v_mfma_f32_16x16x32_bf16 v[0:3], v[236:239], v[244:247], v[0:3]
	s_setprio 0
	s_waitcnt vmcnt(8)
	s_barrier
	ds_read_b128 v[152:155], v111 offset:49152
	ds_read_b128 v[156:159], v111 offset:51200
	ds_read_b128 v[160:163], v109 offset:32768
	ds_read_b128 v[164:167], v109 offset:34816
	ds_read_b128 v[168:171], v111 offset:53248
	ds_read_b128 v[172:175], v112 offset:49152
	ds_read_b128 v[208:211], v109 offset:36864
	ds_read_b128 v[212:215], v110 offset:32768
	ds_read_b128 v[216:219], v115 offset:49152
	ds_read_b128 v[220:223], v115 offset:51200
	ds_read_b128 v[224:227], v113 offset:32768
	ds_read_b128 v[228:231], v113 offset:34816
	ds_read_b128 v[232:235], v115 offset:53248
	ds_read_b128 v[236:239], v116 offset:49152
	ds_read_b128 v[240:243], v113 offset:36864
	ds_read_b128 v[244:247], v114 offset:32768
	s_setprio 1
	s_waitcnt lgkmcnt(13)
	v_mfma_f32_16x16x32_bf16 v[92:95], v[152:155], v[160:163], v[92:95]
	v_mfma_f32_16x16x32_bf16 v[88:91], v[156:159], v[160:163], v[88:91]
	s_waitcnt lgkmcnt(11)
	v_mfma_f32_16x16x32_bf16 v[84:87], v[168:171], v[160:163], v[84:87]
	s_waitcnt lgkmcnt(10)
	v_mfma_f32_16x16x32_bf16 v[80:83], v[172:175], v[160:163], v[80:83]
	v_mfma_f32_16x16x32_bf16 v[76:79], v[152:155], v[164:167], v[76:79]
	v_mfma_f32_16x16x32_bf16 v[72:75], v[156:159], v[164:167], v[72:75]
	v_mfma_f32_16x16x32_bf16 v[60:63], v[168:171], v[164:167], v[60:63]
	v_mfma_f32_16x16x32_bf16 v[28:31], v[172:175], v[164:167], v[28:31]
	s_waitcnt lgkmcnt(9)
	v_mfma_f32_16x16x32_bf16 v[64:67], v[152:155], v[208:211], v[64:67]
	v_mfma_f32_16x16x32_bf16 v[36:39], v[156:159], v[208:211], v[36:39]
	v_mfma_f32_16x16x32_bf16 v[32:35], v[168:171], v[208:211], v[32:35]
	v_mfma_f32_16x16x32_bf16 v[16:19], v[172:175], v[208:211], v[16:19]
	s_waitcnt lgkmcnt(8)
	v_mfma_f32_16x16x32_bf16 v[12:15], v[152:155], v[212:215], v[12:15]
	v_mfma_f32_16x16x32_bf16 v[8:11], v[156:159], v[212:215], v[8:11]
	v_mfma_f32_16x16x32_bf16 v[4:7], v[168:171], v[212:215], v[4:7]
	v_mfma_f32_16x16x32_bf16 v[0:3], v[172:175], v[212:215], v[0:3]
	s_setprio 0
	s_waitcnt lgkmcnt(0)
	s_barrier
	s_add_i32 s4, s14, 0xc0
	s_min_u32 s4, s4, 0x3c0
	s_lshl_b32 s4, s4, 1
	s_setprio 1
	v_mfma_f32_16x16x32_bf16 v[92:95], v[216:219], v[224:227], v[92:95]
	s_add_u32 m0, s15, 0x8000
	v_lshl_add_u64 v[204:205], v[188:189], 0, s[4:5]
	global_load_lds_dwordx4 v[204:205], off
	v_mfma_f32_16x16x32_bf16 v[88:91], v[220:223], v[224:227], v[88:91]
	v_mfma_f32_16x16x32_bf16 v[84:87], v[232:235], v[224:227], v[84:87]
	s_add_u32 m0, s15, 0x9000
	v_lshl_add_u64 v[206:207], v[190:191], 0, s[4:5]
	global_load_lds_dwordx4 v[206:207], off
	v_mfma_f32_16x16x32_bf16 v[80:83], v[236:239], v[224:227], v[80:83]
	v_mfma_f32_16x16x32_bf16 v[76:79], v[216:219], v[228:231], v[76:79]
	s_add_u32 m0, s15, 0xa000
	v_lshl_add_u64 v[204:205], v[192:193], 0, s[4:5]
	global_load_lds_dwordx4 v[204:205], off
	v_mfma_f32_16x16x32_bf16 v[72:75], v[220:223], v[228:231], v[72:75]
	v_mfma_f32_16x16x32_bf16 v[60:63], v[232:235], v[228:231], v[60:63]
	s_add_u32 m0, s15, 0xb000
	v_lshl_add_u64 v[206:207], v[194:195], 0, s[4:5]
	global_load_lds_dwordx4 v[206:207], off
	v_mfma_f32_16x16x32_bf16 v[28:31], v[236:239], v[228:231], v[28:31]
	v_mfma_f32_16x16x32_bf16 v[64:67], v[216:219], v[240:243], v[64:67]
	s_add_u32 m0, s15, 0xc000
	v_lshl_add_u64 v[204:205], v[196:197], 0, s[4:5]
	global_load_lds_dwordx4 v[204:205], off
	v_mfma_f32_16x16x32_bf16 v[36:39], v[220:223], v[240:243], v[36:39]
	v_mfma_f32_16x16x32_bf16 v[32:35], v[232:235], v[240:243], v[32:35]
	s_add_u32 m0, s15, 0xd000
	v_lshl_add_u64 v[206:207], v[198:199], 0, s[4:5]
	global_load_lds_dwordx4 v[206:207], off
	v_mfma_f32_16x16x32_bf16 v[16:19], v[236:239], v[240:243], v[16:19]
	v_mfma_f32_16x16x32_bf16 v[12:15], v[216:219], v[244:247], v[12:15]
	s_add_u32 m0, s15, 0xe000
	v_lshl_add_u64 v[204:205], v[200:201], 0, s[4:5]
	global_load_lds_dwordx4 v[204:205], off
	v_mfma_f32_16x16x32_bf16 v[8:11], v[220:223], v[244:247], v[8:11]
	v_mfma_f32_16x16x32_bf16 v[4:7], v[232:235], v[244:247], v[4:7]
	s_add_u32 m0, s15, 0xf000
	v_lshl_add_u64 v[206:207], v[202:203], 0, s[4:5]
	global_load_lds_dwordx4 v[206:207], off
	v_mfma_f32_16x16x32_bf16 v[0:3], v[236:239], v[244:247], v[0:3]
	s_setprio 0
	s_waitcnt vmcnt(8)
	s_barrier
	s_add_i32 s14, s14, 0x80
	s_add_i32 s13, s13, 2
	s_cmp_lt_u32 s13, 14
	s_cbranch_scc1 .Lglds2_26323
	ds_read_b128 v[152:155], v111 offset:16384
	ds_read_b128 v[156:159], v111 offset:18432
	ds_read_b128 v[160:163], v109
	ds_read_b128 v[164:167], v109 offset:2048
	ds_read_b128 v[168:171], v111 offset:20480
	ds_read_b128 v[172:175], v112 offset:16384
	ds_read_b128 v[208:211], v109 offset:4096
	ds_read_b128 v[212:215], v110
	ds_read_b128 v[216:219], v115 offset:16384
	ds_read_b128 v[220:223], v115 offset:18432
	ds_read_b128 v[224:227], v113
	ds_read_b128 v[228:231], v113 offset:2048
	ds_read_b128 v[232:235], v115 offset:20480
	ds_read_b128 v[236:239], v116 offset:16384
	ds_read_b128 v[240:243], v113 offset:4096
	ds_read_b128 v[244:247], v114
	s_setprio 1
	s_waitcnt lgkmcnt(13)
	v_mfma_f32_16x16x32_bf16 v[92:95], v[152:155], v[160:163], v[92:95]
	v_mfma_f32_16x16x32_bf16 v[88:91], v[156:159], v[160:163], v[88:91]
	s_waitcnt lgkmcnt(11)
	v_mfma_f32_16x16x32_bf16 v[84:87], v[168:171], v[160:163], v[84:87]
	s_waitcnt lgkmcnt(10)
	v_mfma_f32_16x16x32_bf16 v[80:83], v[172:175], v[160:163], v[80:83]
	v_mfma_f32_16x16x32_bf16 v[76:79], v[152:155], v[164:167], v[76:79]
	v_mfma_f32_16x16x32_bf16 v[72:75], v[156:159], v[164:167], v[72:75]
	v_mfma_f32_16x16x32_bf16 v[60:63], v[168:171], v[164:167], v[60:63]
	v_mfma_f32_16x16x32_bf16 v[28:31], v[172:175], v[164:167], v[28:31]
	s_waitcnt lgkmcnt(9)
	v_mfma_f32_16x16x32_bf16 v[64:67], v[152:155], v[208:211], v[64:67]
	v_mfma_f32_16x16x32_bf16 v[36:39], v[156:159], v[208:211], v[36:39]
	v_mfma_f32_16x16x32_bf16 v[32:35], v[168:171], v[208:211], v[32:35]
	v_mfma_f32_16x16x32_bf16 v[16:19], v[172:175], v[208:211], v[16:19]
	s_waitcnt lgkmcnt(8)
	v_mfma_f32_16x16x32_bf16 v[12:15], v[152:155], v[212:215], v[12:15]
	v_mfma_f32_16x16x32_bf16 v[8:11], v[156:159], v[212:215], v[8:11]
	v_mfma_f32_16x16x32_bf16 v[4:7], v[168:171], v[212:215], v[4:7]
	v_mfma_f32_16x16x32_bf16 v[0:3], v[172:175], v[212:215], v[0:3]
	s_setprio 0
	s_waitcnt lgkmcnt(0)
	s_setprio 1
	v_mfma_f32_16x16x32_bf16 v[92:95], v[216:219], v[224:227], v[92:95]
	v_mfma_f32_16x16x32_bf16 v[88:91], v[220:223], v[224:227], v[88:91]
	v_mfma_f32_16x16x32_bf16 v[84:87], v[232:235], v[224:227], v[84:87]
	v_mfma_f32_16x16x32_bf16 v[80:83], v[236:239], v[224:227], v[80:83]
	v_mfma_f32_16x16x32_bf16 v[76:79], v[216:219], v[228:231], v[76:79]
	v_mfma_f32_16x16x32_bf16 v[72:75], v[220:223], v[228:231], v[72:75]
	v_mfma_f32_16x16x32_bf16 v[60:63], v[232:235], v[228:231], v[60:63]
	v_mfma_f32_16x16x32_bf16 v[28:31], v[236:239], v[228:231], v[28:31]
	v_mfma_f32_16x16x32_bf16 v[64:67], v[216:219], v[240:243], v[64:67]
	v_mfma_f32_16x16x32_bf16 v[36:39], v[220:223], v[240:243], v[36:39]
	v_mfma_f32_16x16x32_bf16 v[32:35], v[232:235], v[240:243], v[32:35]
	v_mfma_f32_16x16x32_bf16 v[16:19], v[236:239], v[240:243], v[16:19]
	v_mfma_f32_16x16x32_bf16 v[12:15], v[216:219], v[244:247], v[12:15]
	v_mfma_f32_16x16x32_bf16 v[8:11], v[220:223], v[244:247], v[8:11]
	v_mfma_f32_16x16x32_bf16 v[4:7], v[232:235], v[244:247], v[4:7]
	v_mfma_f32_16x16x32_bf16 v[0:3], v[236:239], v[244:247], v[0:3]
	s_setprio 0
	s_waitcnt vmcnt(0)
	s_barrier
	ds_read_b128 v[152:155], v111 offset:49152
	ds_read_b128 v[156:159], v111 offset:51200
	ds_read_b128 v[160:163], v109 offset:32768
	ds_read_b128 v[164:167], v109 offset:34816
	ds_read_b128 v[168:171], v111 offset:53248
	ds_read_b128 v[172:175], v112 offset:49152
	ds_read_b128 v[208:211], v109 offset:36864
	ds_read_b128 v[212:215], v110 offset:32768
	ds_read_b128 v[216:219], v115 offset:49152
	ds_read_b128 v[220:223], v115 offset:51200
	ds_read_b128 v[224:227], v113 offset:32768
	ds_read_b128 v[228:231], v113 offset:34816
	ds_read_b128 v[232:235], v115 offset:53248
	ds_read_b128 v[236:239], v116 offset:49152
	ds_read_b128 v[240:243], v113 offset:36864
	ds_read_b128 v[244:247], v114 offset:32768
	s_setprio 1
	s_waitcnt lgkmcnt(13)
	v_mfma_f32_16x16x32_bf16 v[92:95], v[152:155], v[160:163], v[92:95]
	v_mfma_f32_16x16x32_bf16 v[88:91], v[156:159], v[160:163], v[88:91]
	s_waitcnt lgkmcnt(11)
	v_mfma_f32_16x16x32_bf16 v[84:87], v[168:171], v[160:163], v[84:87]
	s_waitcnt lgkmcnt(10)
	v_mfma_f32_16x16x32_bf16 v[80:83], v[172:175], v[160:163], v[80:83]
	v_mfma_f32_16x16x32_bf16 v[76:79], v[152:155], v[164:167], v[76:79]
	v_mfma_f32_16x16x32_bf16 v[72:75], v[156:159], v[164:167], v[72:75]
	v_mfma_f32_16x16x32_bf16 v[60:63], v[168:171], v[164:167], v[60:63]
	v_mfma_f32_16x16x32_bf16 v[28:31], v[172:175], v[164:167], v[28:31]
	s_waitcnt lgkmcnt(9)
	v_mfma_f32_16x16x32_bf16 v[64:67], v[152:155], v[208:211], v[64:67]
	v_mfma_f32_16x16x32_bf16 v[36:39], v[156:159], v[208:211], v[36:39]
	v_mfma_f32_16x16x32_bf16 v[32:35], v[168:171], v[208:211], v[32:35]
	v_mfma_f32_16x16x32_bf16 v[16:19], v[172:175], v[208:211], v[16:19]
	s_waitcnt lgkmcnt(8)
	v_mfma_f32_16x16x32_bf16 v[12:15], v[152:155], v[212:215], v[12:15]
	v_mfma_f32_16x16x32_bf16 v[8:11], v[156:159], v[212:215], v[8:11]
	v_mfma_f32_16x16x32_bf16 v[4:7], v[168:171], v[212:215], v[4:7]
	v_mfma_f32_16x16x32_bf16 v[0:3], v[172:175], v[212:215], v[0:3]
	s_setprio 0
	s_waitcnt lgkmcnt(0)
	s_barrier
	s_setprio 1
	v_mfma_f32_16x16x32_bf16 v[92:95], v[216:219], v[224:227], v[92:95]
	v_mfma_f32_16x16x32_bf16 v[88:91], v[220:223], v[224:227], v[88:91]
	v_mfma_f32_16x16x32_bf16 v[84:87], v[232:235], v[224:227], v[84:87]
	v_mfma_f32_16x16x32_bf16 v[80:83], v[236:239], v[224:227], v[80:83]
	v_mfma_f32_16x16x32_bf16 v[76:79], v[216:219], v[228:231], v[76:79]
	v_mfma_f32_16x16x32_bf16 v[72:75], v[220:223], v[228:231], v[72:75]
	v_mfma_f32_16x16x32_bf16 v[60:63], v[232:235], v[228:231], v[60:63]
	v_mfma_f32_16x16x32_bf16 v[28:31], v[236:239], v[228:231], v[28:31]
	v_mfma_f32_16x16x32_bf16 v[64:67], v[216:219], v[240:243], v[64:67]
	v_mfma_f32_16x16x32_bf16 v[36:39], v[220:223], v[240:243], v[36:39]
	v_mfma_f32_16x16x32_bf16 v[32:35], v[232:235], v[240:243], v[32:35]
	v_mfma_f32_16x16x32_bf16 v[16:19], v[236:239], v[240:243], v[16:19]
	v_mfma_f32_16x16x32_bf16 v[12:15], v[216:219], v[244:247], v[12:15]
	v_mfma_f32_16x16x32_bf16 v[8:11], v[220:223], v[244:247], v[8:11]
	v_mfma_f32_16x16x32_bf16 v[4:7], v[232:235], v[244:247], v[4:7]
	v_mfma_f32_16x16x32_bf16 v[0:3], v[236:239], v[244:247], v[0:3]
	s_setprio 0
	s_waitcnt vmcnt(0)
	s_waitcnt vmcnt(0)
	v_or_b32_e32 v170, s12, v118
	v_add_lshl_u32 v96, v117, s11, 10
	v_readlane_b32 s12, v254, 24
	v_readlane_b32 s16, v254, 28
	v_readlane_b32 s17, v254, 29
	v_readlane_b32 s13, v254, 25
	v_readlane_b32 s14, v254, 26
	v_readlane_b32 s15, v254, 27
	v_readlane_b32 s18, v254, 30
	v_readlane_b32 s19, v254, 31
	v_readlane_b32 s20, v254, 32
	v_readlane_b32 s21, v254, 33
	v_readlane_b32 s22, v254, 34
	v_readlane_b32 s23, v254, 35
	v_readlane_b32 s24, v254, 36
	v_readlane_b32 s25, v254, 37
	v_readlane_b32 s26, v254, 38
	v_readlane_b32 s27, v254, 39
	v_lshlrev_b32_e32 v168, 2, v170
	v_mov_b32_e32 v169, v97
	v_lshlrev_b64 v[174:175], 2, v[96:97]
	v_lshl_add_u64 v[152:153], s[16:17], 0, v[174:175]
	v_lshl_add_u64 v[160:161], s[82:83], 0, v[174:175]
	v_lshl_add_u64 v[152:153], v[152:153], 0, v[168:169]
	v_lshl_add_u64 v[160:161], v[160:161], 0, v[168:169]
	global_load_dwordx4 v[120:123], v[152:153], off
	global_load_dwordx4 v[124:127], v[152:153], off offset:64
	global_load_dwordx4 v[128:131], v[152:153], off offset:128
	global_load_dwordx4 v[132:135], v[152:153], off offset:192
	v_or_b32_e32 v172, 0x4000, v96
	v_mov_b32_e32 v173, v97
	v_lshlrev_b64 v[174:175], 2, v[172:173]
	v_lshl_add_u64 v[154:155], s[16:17], 0, v[174:175]
	v_lshl_add_u64 v[162:163], s[82:83], 0, v[174:175]
	v_lshl_add_u64 v[154:155], v[154:155], 0, v[168:169]
	v_lshl_add_u64 v[162:163], v[162:163], 0, v[168:169]
	global_load_dwordx4 v[136:139], v[154:155], off
	global_load_dwordx4 v[140:143], v[154:155], off offset:64
	global_load_dwordx4 v[144:147], v[154:155], off offset:128
	global_load_dwordx4 v[148:151], v[154:155], off offset:192
	v_or_b32_e32 v172, 0x8000, v96
	v_mov_b32_e32 v173, v97
	v_lshlrev_b64 v[174:175], 2, v[172:173]
	v_lshl_add_u64 v[156:157], s[16:17], 0, v[174:175]
	v_lshl_add_u64 v[164:165], s[82:83], 0, v[174:175]
	v_lshl_add_u64 v[156:157], v[156:157], 0, v[168:169]
	v_lshl_add_u64 v[164:165], v[164:165], 0, v[168:169]
	global_load_dwordx4 v[20:23], v[156:157], off
	global_load_dwordx4 v[24:27], v[156:157], off offset:64
	global_load_dwordx4 v[40:43], v[156:157], off offset:128
	global_load_dwordx4 v[44:47], v[156:157], off offset:192
	v_or_b32_e32 v172, 0xc000, v96
	v_mov_b32_e32 v173, v97
	v_lshlrev_b64 v[174:175], 2, v[172:173]
	v_lshl_add_u64 v[158:159], s[16:17], 0, v[174:175]
	v_lshl_add_u64 v[166:167], s[82:83], 0, v[174:175]
	v_lshl_add_u64 v[158:159], v[158:159], 0, v[168:169]
	v_lshl_add_u64 v[166:167], v[166:167], 0, v[168:169]
	global_load_dwordx4 v[48:51], v[158:159], off
	global_load_dwordx4 v[52:55], v[158:159], off offset:64
	global_load_dwordx4 v[56:59], v[158:159], off offset:128
	global_load_dwordx4 v[68:71], v[158:159], off offset:192
	s_waitcnt vmcnt(15)
	v_pk_fma_f32 v[120:121], v[120:121], s[6:7], v[92:93] op_sel_hi:[1,0,1]
	v_pk_fma_f32 v[122:123], v[122:123], s[6:7], v[94:95] op_sel_hi:[1,0,1]
	s_waitcnt vmcnt(14)
	v_pk_fma_f32 v[124:125], v[124:125], s[6:7], v[88:89] op_sel_hi:[1,0,1]
	v_pk_fma_f32 v[126:127], v[126:127], s[6:7], v[90:91] op_sel_hi:[1,0,1]
	s_waitcnt vmcnt(13)
	v_pk_fma_f32 v[128:129], v[128:129], s[6:7], v[84:85] op_sel_hi:[1,0,1]
	v_pk_fma_f32 v[130:131], v[130:131], s[6:7], v[86:87] op_sel_hi:[1,0,1]
	s_waitcnt vmcnt(12)
	v_pk_fma_f32 v[132:133], v[132:133], s[6:7], v[80:81] op_sel_hi:[1,0,1]
	v_pk_fma_f32 v[134:135], v[134:135], s[6:7], v[82:83] op_sel_hi:[1,0,1]
	s_waitcnt vmcnt(11)
	v_pk_fma_f32 v[136:137], v[136:137], s[6:7], v[76:77] op_sel_hi:[1,0,1]
	v_pk_fma_f32 v[138:139], v[138:139], s[6:7], v[78:79] op_sel_hi:[1,0,1]
	s_waitcnt vmcnt(10)
	v_pk_fma_f32 v[140:141], v[140:141], s[6:7], v[72:73] op_sel_hi:[1,0,1]
	v_pk_fma_f32 v[142:143], v[142:143], s[6:7], v[74:75] op_sel_hi:[1,0,1]
	s_waitcnt vmcnt(9)
	v_pk_fma_f32 v[144:145], v[144:145], s[6:7], v[60:61] op_sel_hi:[1,0,1]
	v_pk_fma_f32 v[146:147], v[146:147], s[6:7], v[62:63] op_sel_hi:[1,0,1]
	s_waitcnt vmcnt(8)
	v_pk_fma_f32 v[148:149], v[148:149], s[6:7], v[28:29] op_sel_hi:[1,0,1]
	v_pk_fma_f32 v[150:151], v[150:151], s[6:7], v[30:31] op_sel_hi:[1,0,1]
	s_waitcnt vmcnt(7)
	v_pk_fma_f32 v[20:21], v[20:21], s[6:7], v[64:65] op_sel_hi:[1,0,1]
	v_pk_fma_f32 v[22:23], v[22:23], s[6:7], v[66:67] op_sel_hi:[1,0,1]
	s_waitcnt vmcnt(6)
	v_pk_fma_f32 v[24:25], v[24:25], s[6:7], v[36:37] op_sel_hi:[1,0,1]
	v_pk_fma_f32 v[26:27], v[26:27], s[6:7], v[38:39] op_sel_hi:[1,0,1]
	s_waitcnt vmcnt(5)
	v_pk_fma_f32 v[40:41], v[40:41], s[6:7], v[32:33] op_sel_hi:[1,0,1]
	v_pk_fma_f32 v[42:43], v[42:43], s[6:7], v[34:35] op_sel_hi:[1,0,1]
	s_waitcnt vmcnt(4)
	v_pk_fma_f32 v[44:45], v[44:45], s[6:7], v[16:17] op_sel_hi:[1,0,1]
	v_pk_fma_f32 v[46:47], v[46:47], s[6:7], v[18:19] op_sel_hi:[1,0,1]
	s_waitcnt vmcnt(3)
	v_pk_fma_f32 v[48:49], v[48:49], s[6:7], v[12:13] op_sel_hi:[1,0,1]
	v_pk_fma_f32 v[50:51], v[50:51], s[6:7], v[14:15] op_sel_hi:[1,0,1]
	s_waitcnt vmcnt(2)
	v_pk_fma_f32 v[52:53], v[52:53], s[6:7], v[8:9] op_sel_hi:[1,0,1]
	v_pk_fma_f32 v[54:55], v[54:55], s[6:7], v[10:11] op_sel_hi:[1,0,1]
	s_waitcnt vmcnt(1)
	v_pk_fma_f32 v[56:57], v[56:57], s[6:7], v[4:5] op_sel_hi:[1,0,1]
	v_pk_fma_f32 v[58:59], v[58:59], s[6:7], v[6:7] op_sel_hi:[1,0,1]
	s_waitcnt vmcnt(0)
	v_pk_fma_f32 v[68:69], v[68:69], s[6:7], v[0:1] op_sel_hi:[1,0,1]
	v_pk_fma_f32 v[70:71], v[70:71], s[6:7], v[2:3] op_sel_hi:[1,0,1]
	global_store_dwordx4 v[160:161], v[120:123], off
	global_store_dwordx4 v[160:161], v[124:127], off offset:64
	global_store_dwordx4 v[160:161], v[128:131], off offset:128
	global_store_dwordx4 v[160:161], v[132:135], off offset:192
	global_store_dwordx4 v[162:163], v[136:139], off
	global_store_dwordx4 v[162:163], v[140:143], off offset:64
	global_store_dwordx4 v[162:163], v[144:147], off offset:128
	global_store_dwordx4 v[162:163], v[148:151], off offset:192
	global_store_dwordx4 v[164:165], v[20:23], off
	global_store_dwordx4 v[164:165], v[24:27], off offset:64
	global_store_dwordx4 v[164:165], v[40:43], off offset:128
	global_store_dwordx4 v[164:165], v[44:47], off offset:192
	global_store_dwordx4 v[166:167], v[48:51], off
	global_store_dwordx4 v[166:167], v[52:55], off offset:64
	global_store_dwordx4 v[166:167], v[56:59], off offset:128
	global_store_dwordx4 v[166:167], v[68:71], off offset:192
	s_add_i32 s7, s7, s3
	s_cmpk_lt_u32 s7, 0x100
	s_cbranch_scc1 .LBB0_798

.LBB0_889:
	s_lshr_b32 s6, s8, 1
	s_and_b32 s6, s6, 0xf8
	s_or_b32 s6, s6, s2
	s_lshl_b32 s12, s6, 7
	s_lshl_b32 s6, s8, 7
	v_or_b32_e32 v0, s12, v107
	s_and_b32 s13, s6, 0x780
	v_lshlrev_b32_e32 v96, 10, v0
	v_lshl_add_u64 v[102:103], v[98:99], 0, v[96:97]
	v_or_b32_e32 v0, s13, v107
	v_lshlrev_b32_e32 v96, 10, v0
	v_lshl_add_u64 v[104:105], v[100:101], 0, v[96:97]
	v_and_b32_e32 v181, 7, v106
	v_bfe_u32 v180, v106, 3, 3
	v_xor_b32_e32 v180, v181, v180
	v_sub_u32_e32 v180, v180, v181
	v_lshlrev_b32_e32 v180, 4, v180
	v_ashrrev_i32_e32 v181, 31, v180
	v_lshrrev_b32_e32 v186, 6, v106
	v_mov_b32_e32 v187, 0x110
	v_lshl_add_u32 v186, v186, 10, v187
	v_lshl_add_u64 v[188:189], v[102:103], 0, v[180:181]
	v_lshl_add_u64 v[196:197], v[104:105], 0, v[180:181]
	v_readfirstlane_b32 s16, v186
	v_add_co_u32_e32 v190, vcc, s9, v188
	v_addc_co_u32_e32 v191, vcc, 0, v189, vcc
	v_add_co_u32_e32 v192, vcc, s10, v188
	v_addc_co_u32_e32 v193, vcc, 0, v189, vcc
	v_add_co_u32_e32 v194, vcc, s11, v188
	v_addc_co_u32_e32 v195, vcc, 0, v189, vcc
	v_add_co_u32_e32 v198, vcc, s9, v196
	v_addc_co_u32_e32 v199, vcc, 0, v197, vcc
	v_add_co_u32_e32 v200, vcc, s10, v196
	v_addc_co_u32_e32 v201, vcc, 0, v197, vcc
	v_add_co_u32_e32 v202, vcc, s11, v196
	v_addc_co_u32_e32 v203, vcc, 0, v197, vcc
	v_mov_b32_e32 v28, 0
	v_mov_b32_e32 v29, v97
	v_mov_b32_e32 v30, v97
	v_mov_b32_e32 v31, v97
	v_mov_b32_e32 v36, 0
	v_mov_b32_e32 v37, v97
	v_mov_b32_e32 v38, v97
	v_mov_b32_e32 v39, v97
	v_mov_b32_e32 v40, 0
	v_mov_b32_e32 v41, v97
	v_mov_b32_e32 v42, v97
	v_mov_b32_e32 v43, v97
	v_mov_b32_e32 v60, 0
	v_mov_b32_e32 v61, v97
	v_mov_b32_e32 v62, v97
	v_mov_b32_e32 v63, v97
	v_mov_b32_e32 v80, 0
	v_mov_b32_e32 v81, v97
	v_mov_b32_e32 v82, v97
	v_mov_b32_e32 v83, v97
	v_mov_b32_e32 v84, 0
	v_mov_b32_e32 v85, v97
	v_mov_b32_e32 v86, v97
	v_mov_b32_e32 v87, v97
	v_mov_b32_e32 v88, 0
	v_mov_b32_e32 v89, v97
	v_mov_b32_e32 v90, v97
	v_mov_b32_e32 v91, v97
	v_mov_b32_e32 v92, 0
	v_mov_b32_e32 v93, v97
	v_mov_b32_e32 v94, v97
	v_mov_b32_e32 v95, v97
	v_mov_b32_e32 v32, 0
	v_mov_b32_e32 v33, v97
	v_mov_b32_e32 v34, v97
	v_mov_b32_e32 v35, v97
	v_mov_b32_e32 v24, 0
	v_mov_b32_e32 v25, v97
	v_mov_b32_e32 v26, v97
	v_mov_b32_e32 v27, v97
	v_mov_b32_e32 v20, 0
	v_mov_b32_e32 v21, v97
	v_mov_b32_e32 v22, v97
	v_mov_b32_e32 v23, v97
	v_mov_b32_e32 v16, 0
	v_mov_b32_e32 v17, v97
	v_mov_b32_e32 v18, v97
	v_mov_b32_e32 v19, v97
	v_mov_b32_e32 v12, 0
	v_mov_b32_e32 v13, v97
	v_mov_b32_e32 v14, v97
	v_mov_b32_e32 v15, v97
	v_mov_b32_e32 v8, 0
	v_mov_b32_e32 v9, v97
	v_mov_b32_e32 v10, v97
	v_mov_b32_e32 v11, v97
	v_mov_b32_e32 v4, 0
	v_mov_b32_e32 v5, v97
	v_mov_b32_e32 v6, v97
	v_mov_b32_e32 v7, v97
	v_mov_b32_e32 v0, 0
	v_mov_b32_e32 v1, v97
	v_mov_b32_e32 v2, v97
	v_mov_b32_e32 v3, v97
	s_add_u32 m0, s16, 0x0
	s_nop 0
	global_load_lds_dwordx4 v[188:189], off
	s_add_u32 m0, s16, 0x1000
	s_nop 0
	global_load_lds_dwordx4 v[190:191], off
	s_add_u32 m0, s16, 0x2000
	s_nop 0
	global_load_lds_dwordx4 v[192:193], off
	s_add_u32 m0, s16, 0x3000
	s_nop 0
	global_load_lds_dwordx4 v[194:195], off
	s_add_u32 m0, s16, 0x4000
	s_nop 0
	global_load_lds_dwordx4 v[196:197], off
	s_add_u32 m0, s16, 0x5000
	s_nop 0
	global_load_lds_dwordx4 v[198:199], off
	s_add_u32 m0, s16, 0x6000
	s_nop 0
	global_load_lds_dwordx4 v[200:201], off
	s_add_u32 m0, s16, 0x7000
	s_nop 0
	global_load_lds_dwordx4 v[202:203], off
	s_mov_b32 s6, 0x80
	s_add_u32 m0, s16, 0x8000
	v_lshl_add_u64 v[204:205], v[188:189], 0, s[6:7]
	global_load_lds_dwordx4 v[204:205], off
	s_add_u32 m0, s16, 0x9000
	v_lshl_add_u64 v[206:207], v[190:191], 0, s[6:7]
	global_load_lds_dwordx4 v[206:207], off
	s_add_u32 m0, s16, 0xa000
	v_lshl_add_u64 v[204:205], v[192:193], 0, s[6:7]
	global_load_lds_dwordx4 v[204:205], off
	s_add_u32 m0, s16, 0xb000
	v_lshl_add_u64 v[206:207], v[194:195], 0, s[6:7]
	global_load_lds_dwordx4 v[206:207], off
	s_add_u32 m0, s16, 0xc000
	v_lshl_add_u64 v[204:205], v[196:197], 0, s[6:7]
	global_load_lds_dwordx4 v[204:205], off
	s_add_u32 m0, s16, 0xd000
	v_lshl_add_u64 v[206:207], v[198:199], 0, s[6:7]
	global_load_lds_dwordx4 v[206:207], off
	s_add_u32 m0, s16, 0xe000
	v_lshl_add_u64 v[204:205], v[200:201], 0, s[6:7]
	global_load_lds_dwordx4 v[204:205], off
	s_add_u32 m0, s16, 0xf000
	v_lshl_add_u64 v[206:207], v[202:203], 0, s[6:7]
	global_load_lds_dwordx4 v[206:207], off
	s_mov_b32 s15, 0
	s_mov_b32 s14, 0
	s_waitcnt vmcnt(8)
	s_barrier
.Lglds2_28042:
	ds_read_b128 v[152:155], v111 offset:16384
	ds_read_b128 v[156:159], v111 offset:18432
	ds_read_b128 v[160:163], v109
	ds_read_b128 v[164:167], v109 offset:2048
	ds_read_b128 v[168:171], v111 offset:20480
	ds_read_b128 v[172:175], v112 offset:16384
	ds_read_b128 v[208:211], v109 offset:4096
	ds_read_b128 v[212:215], v110
	ds_read_b128 v[216:219], v115 offset:16384
	ds_read_b128 v[220:223], v115 offset:18432
	ds_read_b128 v[224:227], v113
	ds_read_b128 v[228:231], v113 offset:2048
	ds_read_b128 v[232:235], v115 offset:20480
	ds_read_b128 v[236:239], v116 offset:16384
	ds_read_b128 v[240:243], v113 offset:4096
	ds_read_b128 v[244:247], v114
	s_setprio 1
	s_waitcnt lgkmcnt(13)
	v_mfma_i32_16x16x64_i8 v[92:95], v[152:155], v[160:163], v[92:95]
	v_mfma_i32_16x16x64_i8 v[88:91], v[156:159], v[160:163], v[88:91]
	s_waitcnt lgkmcnt(11)
	v_mfma_i32_16x16x64_i8 v[84:87], v[168:171], v[160:163], v[84:87]
	s_waitcnt lgkmcnt(10)
	v_mfma_i32_16x16x64_i8 v[80:83], v[172:175], v[160:163], v[80:83]
	v_mfma_i32_16x16x64_i8 v[60:63], v[152:155], v[164:167], v[60:63]
	v_mfma_i32_16x16x64_i8 v[40:43], v[156:159], v[164:167], v[40:43]
	v_mfma_i32_16x16x64_i8 v[36:39], v[168:171], v[164:167], v[36:39]
	v_mfma_i32_16x16x64_i8 v[28:31], v[172:175], v[164:167], v[28:31]
	s_waitcnt lgkmcnt(9)
	v_mfma_i32_16x16x64_i8 v[32:35], v[152:155], v[208:211], v[32:35]
	v_mfma_i32_16x16x64_i8 v[24:27], v[156:159], v[208:211], v[24:27]
	v_mfma_i32_16x16x64_i8 v[20:23], v[168:171], v[208:211], v[20:23]
	v_mfma_i32_16x16x64_i8 v[16:19], v[172:175], v[208:211], v[16:19]
	s_waitcnt lgkmcnt(8)
	v_mfma_i32_16x16x64_i8 v[12:15], v[152:155], v[212:215], v[12:15]
	v_mfma_i32_16x16x64_i8 v[8:11], v[156:159], v[212:215], v[8:11]
	v_mfma_i32_16x16x64_i8 v[4:7], v[168:171], v[212:215], v[4:7]
	v_mfma_i32_16x16x64_i8 v[0:3], v[172:175], v[212:215], v[0:3]
	s_setprio 0
	s_waitcnt lgkmcnt(0)
	s_barrier
	s_add_i32 s6, s15, 0x80
	s_min_u32 s6, s6, 0x1c0
	s_lshl_b32 s6, s6, 1
	s_setprio 1
	v_mfma_i32_16x16x64_i8 v[92:95], v[216:219], v[224:227], v[92:95]
	s_add_u32 m0, s16, 0x0
	v_lshl_add_u64 v[204:205], v[188:189], 0, s[6:7]
	global_load_lds_dwordx4 v[204:205], off
	v_mfma_i32_16x16x64_i8 v[88:91], v[220:223], v[224:227], v[88:91]
	v_mfma_i32_16x16x64_i8 v[84:87], v[232:235], v[224:227], v[84:87]
	s_add_u32 m0, s16, 0x1000
	v_lshl_add_u64 v[206:207], v[190:191], 0, s[6:7]
	global_load_lds_dwordx4 v[206:207], off
	v_mfma_i32_16x16x64_i8 v[80:83], v[236:239], v[224:227], v[80:83]
	v_mfma_i32_16x16x64_i8 v[60:63], v[216:219], v[228:231], v[60:63]
	s_add_u32 m0, s16, 0x2000
	v_lshl_add_u64 v[204:205], v[192:193], 0, s[6:7]
	global_load_lds_dwordx4 v[204:205], off
	v_mfma_i32_16x16x64_i8 v[40:43], v[220:223], v[228:231], v[40:43]
	v_mfma_i32_16x16x64_i8 v[36:39], v[232:235], v[228:231], v[36:39]
	s_add_u32 m0, s16, 0x3000
	v_lshl_add_u64 v[206:207], v[194:195], 0, s[6:7]
	global_load_lds_dwordx4 v[206:207], off
	v_mfma_i32_16x16x64_i8 v[28:31], v[236:239], v[228:231], v[28:31]
	v_mfma_i32_16x16x64_i8 v[32:35], v[216:219], v[240:243], v[32:35]
	s_add_u32 m0, s16, 0x4000
	v_lshl_add_u64 v[204:205], v[196:197], 0, s[6:7]
	global_load_lds_dwordx4 v[204:205], off
	v_mfma_i32_16x16x64_i8 v[24:27], v[220:223], v[240:243], v[24:27]
	v_mfma_i32_16x16x64_i8 v[20:23], v[232:235], v[240:243], v[20:23]
	s_add_u32 m0, s16, 0x5000
	v_lshl_add_u64 v[206:207], v[198:199], 0, s[6:7]
	global_load_lds_dwordx4 v[206:207], off
	v_mfma_i32_16x16x64_i8 v[16:19], v[236:239], v[240:243], v[16:19]
	v_mfma_i32_16x16x64_i8 v[12:15], v[216:219], v[244:247], v[12:15]
	s_add_u32 m0, s16, 0x6000
	v_lshl_add_u64 v[204:205], v[200:201], 0, s[6:7]
	global_load_lds_dwordx4 v[204:205], off
	v_mfma_i32_16x16x64_i8 v[8:11], v[220:223], v[244:247], v[8:11]
	v_mfma_i32_16x16x64_i8 v[4:7], v[232:235], v[244:247], v[4:7]
	s_add_u32 m0, s16, 0x7000
	v_lshl_add_u64 v[206:207], v[202:203], 0, s[6:7]
	global_load_lds_dwordx4 v[206:207], off
	v_mfma_i32_16x16x64_i8 v[0:3], v[236:239], v[244:247], v[0:3]
	s_setprio 0
	s_waitcnt vmcnt(8)
	s_barrier
	ds_read_b128 v[152:155], v111 offset:49152
	ds_read_b128 v[156:159], v111 offset:51200
	ds_read_b128 v[160:163], v109 offset:32768
	ds_read_b128 v[164:167], v109 offset:34816
	ds_read_b128 v[168:171], v111 offset:53248
	ds_read_b128 v[172:175], v112 offset:49152
	ds_read_b128 v[208:211], v109 offset:36864
	ds_read_b128 v[212:215], v110 offset:32768
	ds_read_b128 v[216:219], v115 offset:49152
	ds_read_b128 v[220:223], v115 offset:51200
	ds_read_b128 v[224:227], v113 offset:32768
	ds_read_b128 v[228:231], v113 offset:34816
	ds_read_b128 v[232:235], v115 offset:53248
	ds_read_b128 v[236:239], v116 offset:49152
	ds_read_b128 v[240:243], v113 offset:36864
	ds_read_b128 v[244:247], v114 offset:32768
	s_setprio 1
	s_waitcnt lgkmcnt(13)
	v_mfma_i32_16x16x64_i8 v[92:95], v[152:155], v[160:163], v[92:95]
	v_mfma_i32_16x16x64_i8 v[88:91], v[156:159], v[160:163], v[88:91]
	s_waitcnt lgkmcnt(11)
	v_mfma_i32_16x16x64_i8 v[84:87], v[168:171], v[160:163], v[84:87]
	s_waitcnt lgkmcnt(10)
	v_mfma_i32_16x16x64_i8 v[80:83], v[172:175], v[160:163], v[80:83]
	v_mfma_i32_16x16x64_i8 v[60:63], v[152:155], v[164:167], v[60:63]
	v_mfma_i32_16x16x64_i8 v[40:43], v[156:159], v[164:167], v[40:43]
	v_mfma_i32_16x16x64_i8 v[36:39], v[168:171], v[164:167], v[36:39]
	v_mfma_i32_16x16x64_i8 v[28:31], v[172:175], v[164:167], v[28:31]
	s_waitcnt lgkmcnt(9)
	v_mfma_i32_16x16x64_i8 v[32:35], v[152:155], v[208:211], v[32:35]
	v_mfma_i32_16x16x64_i8 v[24:27], v[156:159], v[208:211], v[24:27]
	v_mfma_i32_16x16x64_i8 v[20:23], v[168:171], v[208:211], v[20:23]
	v_mfma_i32_16x16x64_i8 v[16:19], v[172:175], v[208:211], v[16:19]
	s_waitcnt lgkmcnt(8)
	v_mfma_i32_16x16x64_i8 v[12:15], v[152:155], v[212:215], v[12:15]
	v_mfma_i32_16x16x64_i8 v[8:11], v[156:159], v[212:215], v[8:11]
	v_mfma_i32_16x16x64_i8 v[4:7], v[168:171], v[212:215], v[4:7]
	v_mfma_i32_16x16x64_i8 v[0:3], v[172:175], v[212:215], v[0:3]
	s_setprio 0
	s_waitcnt lgkmcnt(0)
	s_barrier
	s_add_i32 s6, s15, 0xc0
	s_min_u32 s6, s6, 0x1c0
	s_lshl_b32 s6, s6, 1
	s_setprio 1
	v_mfma_i32_16x16x64_i8 v[92:95], v[216:219], v[224:227], v[92:95]
	s_add_u32 m0, s16, 0x8000
	v_lshl_add_u64 v[204:205], v[188:189], 0, s[6:7]
	global_load_lds_dwordx4 v[204:205], off
	v_mfma_i32_16x16x64_i8 v[88:91], v[220:223], v[224:227], v[88:91]
	v_mfma_i32_16x16x64_i8 v[84:87], v[232:235], v[224:227], v[84:87]
	s_add_u32 m0, s16, 0x9000
	v_lshl_add_u64 v[206:207], v[190:191], 0, s[6:7]
	global_load_lds_dwordx4 v[206:207], off
	v_mfma_i32_16x16x64_i8 v[80:83], v[236:239], v[224:227], v[80:83]
	v_mfma_i32_16x16x64_i8 v[60:63], v[216:219], v[228:231], v[60:63]
	s_add_u32 m0, s16, 0xa000
	v_lshl_add_u64 v[204:205], v[192:193], 0, s[6:7]
	global_load_lds_dwordx4 v[204:205], off
	v_mfma_i32_16x16x64_i8 v[40:43], v[220:223], v[228:231], v[40:43]
	v_mfma_i32_16x16x64_i8 v[36:39], v[232:235], v[228:231], v[36:39]
	s_add_u32 m0, s16, 0xb000
	v_lshl_add_u64 v[206:207], v[194:195], 0, s[6:7]
	global_load_lds_dwordx4 v[206:207], off
	v_mfma_i32_16x16x64_i8 v[28:31], v[236:239], v[228:231], v[28:31]
	v_mfma_i32_16x16x64_i8 v[32:35], v[216:219], v[240:243], v[32:35]
	s_add_u32 m0, s16, 0xc000
	v_lshl_add_u64 v[204:205], v[196:197], 0, s[6:7]
	global_load_lds_dwordx4 v[204:205], off
	v_mfma_i32_16x16x64_i8 v[24:27], v[220:223], v[240:243], v[24:27]
	v_mfma_i32_16x16x64_i8 v[20:23], v[232:235], v[240:243], v[20:23]
	s_add_u32 m0, s16, 0xd000
	v_lshl_add_u64 v[206:207], v[198:199], 0, s[6:7]
	global_load_lds_dwordx4 v[206:207], off
	v_mfma_i32_16x16x64_i8 v[16:19], v[236:239], v[240:243], v[16:19]
	v_mfma_i32_16x16x64_i8 v[12:15], v[216:219], v[244:247], v[12:15]
	s_add_u32 m0, s16, 0xe000
	v_lshl_add_u64 v[204:205], v[200:201], 0, s[6:7]
	global_load_lds_dwordx4 v[204:205], off
	v_mfma_i32_16x16x64_i8 v[8:11], v[220:223], v[244:247], v[8:11]
	v_mfma_i32_16x16x64_i8 v[4:7], v[232:235], v[244:247], v[4:7]
	s_add_u32 m0, s16, 0xf000
	v_lshl_add_u64 v[206:207], v[202:203], 0, s[6:7]
	global_load_lds_dwordx4 v[206:207], off
	v_mfma_i32_16x16x64_i8 v[0:3], v[236:239], v[244:247], v[0:3]
	s_setprio 0
	s_waitcnt vmcnt(8)
	s_barrier
	s_add_i32 s15, s15, 0x80
	s_add_i32 s14, s14, 2
	s_cmp_lt_u32 s14, 6
	s_cbranch_scc1 .Lglds2_28042
	ds_read_b128 v[152:155], v111 offset:16384
	ds_read_b128 v[156:159], v111 offset:18432
	ds_read_b128 v[160:163], v109
	ds_read_b128 v[164:167], v109 offset:2048
	ds_read_b128 v[168:171], v111 offset:20480
	ds_read_b128 v[172:175], v112 offset:16384
	ds_read_b128 v[208:211], v109 offset:4096
	ds_read_b128 v[212:215], v110
	ds_read_b128 v[216:219], v115 offset:16384
	ds_read_b128 v[220:223], v115 offset:18432
	ds_read_b128 v[224:227], v113
	ds_read_b128 v[228:231], v113 offset:2048
	ds_read_b128 v[232:235], v115 offset:20480
	ds_read_b128 v[236:239], v116 offset:16384
	ds_read_b128 v[240:243], v113 offset:4096
	ds_read_b128 v[244:247], v114
	s_setprio 1
	s_waitcnt lgkmcnt(13)
	v_mfma_i32_16x16x64_i8 v[92:95], v[152:155], v[160:163], v[92:95]
	v_mfma_i32_16x16x64_i8 v[88:91], v[156:159], v[160:163], v[88:91]
	s_waitcnt lgkmcnt(11)
	v_mfma_i32_16x16x64_i8 v[84:87], v[168:171], v[160:163], v[84:87]
	s_waitcnt lgkmcnt(10)
	v_mfma_i32_16x16x64_i8 v[80:83], v[172:175], v[160:163], v[80:83]
	v_mfma_i32_16x16x64_i8 v[60:63], v[152:155], v[164:167], v[60:63]
	v_mfma_i32_16x16x64_i8 v[40:43], v[156:159], v[164:167], v[40:43]
	v_mfma_i32_16x16x64_i8 v[36:39], v[168:171], v[164:167], v[36:39]
	v_mfma_i32_16x16x64_i8 v[28:31], v[172:175], v[164:167], v[28:31]
	s_waitcnt lgkmcnt(9)
	v_mfma_i32_16x16x64_i8 v[32:35], v[152:155], v[208:211], v[32:35]
	v_mfma_i32_16x16x64_i8 v[24:27], v[156:159], v[208:211], v[24:27]
	v_mfma_i32_16x16x64_i8 v[20:23], v[168:171], v[208:211], v[20:23]
	v_mfma_i32_16x16x64_i8 v[16:19], v[172:175], v[208:211], v[16:19]
	s_waitcnt lgkmcnt(8)
	v_mfma_i32_16x16x64_i8 v[12:15], v[152:155], v[212:215], v[12:15]
	v_mfma_i32_16x16x64_i8 v[8:11], v[156:159], v[212:215], v[8:11]
	v_mfma_i32_16x16x64_i8 v[4:7], v[168:171], v[212:215], v[4:7]
	v_mfma_i32_16x16x64_i8 v[0:3], v[172:175], v[212:215], v[0:3]
	s_setprio 0
	s_waitcnt lgkmcnt(0)
	s_setprio 1
	v_mfma_i32_16x16x64_i8 v[92:95], v[216:219], v[224:227], v[92:95]
	v_mfma_i32_16x16x64_i8 v[88:91], v[220:223], v[224:227], v[88:91]
	v_mfma_i32_16x16x64_i8 v[84:87], v[232:235], v[224:227], v[84:87]
	v_mfma_i32_16x16x64_i8 v[80:83], v[236:239], v[224:227], v[80:83]
	v_mfma_i32_16x16x64_i8 v[60:63], v[216:219], v[228:231], v[60:63]
	v_mfma_i32_16x16x64_i8 v[40:43], v[220:223], v[228:231], v[40:43]
	v_mfma_i32_16x16x64_i8 v[36:39], v[232:235], v[228:231], v[36:39]
	v_mfma_i32_16x16x64_i8 v[28:31], v[236:239], v[228:231], v[28:31]
	v_mfma_i32_16x16x64_i8 v[32:35], v[216:219], v[240:243], v[32:35]
	v_mfma_i32_16x16x64_i8 v[24:27], v[220:223], v[240:243], v[24:27]
	v_mfma_i32_16x16x64_i8 v[20:23], v[232:235], v[240:243], v[20:23]
	v_mfma_i32_16x16x64_i8 v[16:19], v[236:239], v[240:243], v[16:19]
	v_mfma_i32_16x16x64_i8 v[12:15], v[216:219], v[244:247], v[12:15]
	v_mfma_i32_16x16x64_i8 v[8:11], v[220:223], v[244:247], v[8:11]
	v_mfma_i32_16x16x64_i8 v[4:7], v[232:235], v[244:247], v[4:7]
	v_mfma_i32_16x16x64_i8 v[0:3], v[236:239], v[244:247], v[0:3]
	s_setprio 0
	s_waitcnt vmcnt(0)
	s_barrier
	ds_read_b128 v[152:155], v111 offset:49152
	ds_read_b128 v[156:159], v111 offset:51200
	ds_read_b128 v[160:163], v109 offset:32768
	ds_read_b128 v[164:167], v109 offset:34816
	ds_read_b128 v[168:171], v111 offset:53248
	ds_read_b128 v[172:175], v112 offset:49152
	ds_read_b128 v[208:211], v109 offset:36864
	ds_read_b128 v[212:215], v110 offset:32768
	ds_read_b128 v[216:219], v115 offset:49152
	ds_read_b128 v[220:223], v115 offset:51200
	ds_read_b128 v[224:227], v113 offset:32768
	ds_read_b128 v[228:231], v113 offset:34816
	ds_read_b128 v[232:235], v115 offset:53248
	ds_read_b128 v[236:239], v116 offset:49152
	ds_read_b128 v[240:243], v113 offset:36864
	ds_read_b128 v[244:247], v114 offset:32768
	s_setprio 1
	s_waitcnt lgkmcnt(13)
	v_mfma_i32_16x16x64_i8 v[92:95], v[152:155], v[160:163], v[92:95]
	v_mfma_i32_16x16x64_i8 v[88:91], v[156:159], v[160:163], v[88:91]
	s_waitcnt lgkmcnt(11)
	v_mfma_i32_16x16x64_i8 v[84:87], v[168:171], v[160:163], v[84:87]
	s_waitcnt lgkmcnt(10)
	v_mfma_i32_16x16x64_i8 v[80:83], v[172:175], v[160:163], v[80:83]
	v_mfma_i32_16x16x64_i8 v[60:63], v[152:155], v[164:167], v[60:63]
	v_mfma_i32_16x16x64_i8 v[40:43], v[156:159], v[164:167], v[40:43]
	v_mfma_i32_16x16x64_i8 v[36:39], v[168:171], v[164:167], v[36:39]
	v_mfma_i32_16x16x64_i8 v[28:31], v[172:175], v[164:167], v[28:31]
	s_waitcnt lgkmcnt(9)
	v_mfma_i32_16x16x64_i8 v[32:35], v[152:155], v[208:211], v[32:35]
	v_mfma_i32_16x16x64_i8 v[24:27], v[156:159], v[208:211], v[24:27]
	v_mfma_i32_16x16x64_i8 v[20:23], v[168:171], v[208:211], v[20:23]
	v_mfma_i32_16x16x64_i8 v[16:19], v[172:175], v[208:211], v[16:19]
	s_waitcnt lgkmcnt(8)
	v_mfma_i32_16x16x64_i8 v[12:15], v[152:155], v[212:215], v[12:15]
	v_mfma_i32_16x16x64_i8 v[8:11], v[156:159], v[212:215], v[8:11]
	v_mfma_i32_16x16x64_i8 v[4:7], v[168:171], v[212:215], v[4:7]
	v_mfma_i32_16x16x64_i8 v[0:3], v[172:175], v[212:215], v[0:3]
	s_setprio 0
	s_waitcnt lgkmcnt(0)
	s_barrier
	s_setprio 1
	v_mfma_i32_16x16x64_i8 v[92:95], v[216:219], v[224:227], v[92:95]
	v_mfma_i32_16x16x64_i8 v[88:91], v[220:223], v[224:227], v[88:91]
	v_mfma_i32_16x16x64_i8 v[84:87], v[232:235], v[224:227], v[84:87]
	v_mfma_i32_16x16x64_i8 v[80:83], v[236:239], v[224:227], v[80:83]
	v_mfma_i32_16x16x64_i8 v[60:63], v[216:219], v[228:231], v[60:63]
	v_mfma_i32_16x16x64_i8 v[40:43], v[220:223], v[228:231], v[40:43]
	v_mfma_i32_16x16x64_i8 v[36:39], v[232:235], v[228:231], v[36:39]
	v_mfma_i32_16x16x64_i8 v[28:31], v[236:239], v[228:231], v[28:31]
	v_mfma_i32_16x16x64_i8 v[32:35], v[216:219], v[240:243], v[32:35]
	v_mfma_i32_16x16x64_i8 v[24:27], v[220:223], v[240:243], v[24:27]
	v_mfma_i32_16x16x64_i8 v[20:23], v[232:235], v[240:243], v[20:23]
	v_mfma_i32_16x16x64_i8 v[16:19], v[236:239], v[240:243], v[16:19]
	v_mfma_i32_16x16x64_i8 v[12:15], v[216:219], v[244:247], v[12:15]
	v_mfma_i32_16x16x64_i8 v[8:11], v[220:223], v[244:247], v[8:11]
	v_mfma_i32_16x16x64_i8 v[4:7], v[232:235], v[244:247], v[4:7]
	v_mfma_i32_16x16x64_i8 v[0:3], v[236:239], v[244:247], v[0:3]
	s_setprio 0
	s_waitcnt vmcnt(0)
	v_cvt_f32_i32_e32 v92, v92
	v_cvt_f32_i32_e32 v93, v93
	v_cvt_f32_i32_e32 v94, v94
	v_cvt_f32_i32_e32 v95, v95
	v_cvt_f32_i32_e32 v88, v88
	v_cvt_f32_i32_e32 v89, v89
	v_cvt_f32_i32_e32 v90, v90
	v_cvt_f32_i32_e32 v91, v91
	v_cvt_f32_i32_e32 v84, v84
	v_cvt_f32_i32_e32 v85, v85
	v_cvt_f32_i32_e32 v86, v86
	v_cvt_f32_i32_e32 v87, v87
	v_cvt_f32_i32_e32 v80, v80
	v_cvt_f32_i32_e32 v81, v81
	v_cvt_f32_i32_e32 v82, v82
	v_cvt_f32_i32_e32 v83, v83
	v_cvt_f32_i32_e32 v60, v60
	v_cvt_f32_i32_e32 v61, v61
	v_cvt_f32_i32_e32 v62, v62
	v_cvt_f32_i32_e32 v63, v63
	v_cvt_f32_i32_e32 v40, v40
	v_cvt_f32_i32_e32 v41, v41
	v_cvt_f32_i32_e32 v42, v42
	v_cvt_f32_i32_e32 v43, v43
	v_cvt_f32_i32_e32 v36, v36
	v_cvt_f32_i32_e32 v37, v37
	v_cvt_f32_i32_e32 v38, v38
	v_cvt_f32_i32_e32 v39, v39
	v_cvt_f32_i32_e32 v28, v28
	v_cvt_f32_i32_e32 v29, v29
	v_cvt_f32_i32_e32 v30, v30
	v_cvt_f32_i32_e32 v31, v31
	v_cvt_f32_i32_e32 v32, v32
	v_cvt_f32_i32_e32 v33, v33
	v_cvt_f32_i32_e32 v34, v34
	v_cvt_f32_i32_e32 v35, v35
	v_cvt_f32_i32_e32 v24, v24
	v_cvt_f32_i32_e32 v25, v25
	v_cvt_f32_i32_e32 v26, v26
	v_cvt_f32_i32_e32 v27, v27
	v_cvt_f32_i32_e32 v20, v20
	v_cvt_f32_i32_e32 v21, v21
	v_cvt_f32_i32_e32 v22, v22
	v_cvt_f32_i32_e32 v23, v23
	v_cvt_f32_i32_e32 v16, v16
	v_cvt_f32_i32_e32 v17, v17
	v_cvt_f32_i32_e32 v18, v18
	v_cvt_f32_i32_e32 v19, v19
	v_cvt_f32_i32_e32 v12, v12
	v_cvt_f32_i32_e32 v13, v13
	v_cvt_f32_i32_e32 v14, v14
	v_cvt_f32_i32_e32 v15, v15
	v_cvt_f32_i32_e32 v8, v8
	v_cvt_f32_i32_e32 v9, v9
	v_cvt_f32_i32_e32 v10, v10
	v_cvt_f32_i32_e32 v11, v11
	v_cvt_f32_i32_e32 v4, v4
	v_cvt_f32_i32_e32 v5, v5
	v_cvt_f32_i32_e32 v6, v6
	v_cvt_f32_i32_e32 v7, v7
	v_cvt_f32_i32_e32 v0, v0
	v_cvt_f32_i32_e32 v1, v1
	v_cvt_f32_i32_e32 v2, v2
	v_cvt_f32_i32_e32 v3, v3
	s_waitcnt vmcnt(0)
	v_add_u32_e32 v96, s12, v117
	v_or_b32_e32 v146, s13, v118
	v_lshl_add_u64 v[144:145], v[96:97], 2, s[68:69]
	v_lshlrev_b32_e32 v148, 2, v146
	global_load_dword v136, v[144:145], off
	global_load_dword v138, v[144:145], off offset:64
	global_load_dword v140, v[144:145], off offset:128
	global_load_dword v142, v[144:145], off offset:192
	global_load_dwordx4 v[120:123], v148, s[0:1]
	global_load_dwordx4 v[124:127], v148, s[0:1] offset:64
	global_load_dwordx4 v[128:131], v148, s[0:1] offset:128
	global_load_dwordx4 v[132:135], v148, s[0:1] offset:192
	v_lshlrev_b32_e32 v146, 1, v146
	v_mov_b32_e32 v147, v97
	v_lshlrev_b64 v[44:45], 12, v[96:97]
	v_lshl_add_u64 v[44:45], s[64:65], 0, v[44:45]
	v_lshl_add_u64 v[44:45], v[44:45], 0, v[146:147]
	v_or_b32_e32 v52, 16, v96
	v_mov_b32_e32 v53, v97
	v_lshlrev_b64 v[46:47], 12, v[52:53]
	v_lshl_add_u64 v[46:47], s[64:65], 0, v[46:47]
	v_lshl_add_u64 v[46:47], v[46:47], 0, v[146:147]
	v_or_b32_e32 v52, 32, v96
	v_mov_b32_e32 v53, v97
	v_lshlrev_b64 v[48:49], 12, v[52:53]
	v_lshl_add_u64 v[48:49], s[64:65], 0, v[48:49]
	v_lshl_add_u64 v[48:49], v[48:49], 0, v[146:147]
	v_or_b32_e32 v52, 48, v96
	v_mov_b32_e32 v53, v97
	v_lshlrev_b64 v[50:51], 12, v[52:53]
	v_lshl_add_u64 v[50:51], s[64:65], 0, v[50:51]
	v_lshl_add_u64 v[50:51], v[50:51], 0, v[146:147]
	s_waitcnt vmcnt(0)
	v_pk_mul_f32 v[92:93], v[136:137], v[92:93] op_sel_hi:[0,1]
	v_pk_mul_f32 v[94:95], v[136:137], v[94:95] op_sel_hi:[0,1]
	v_pk_mul_f32 v[92:93], v[120:121], v[92:93]
	v_pk_mul_f32 v[94:95], v[94:95], v[122:123]
	v_cvt_pk_bf16_f32 v92, v92, v93
	v_cvt_pk_bf16_f32 v93, v94, v95
	global_store_dwordx2 v[44:45], v[92:93], off
	v_pk_mul_f32 v[88:89], v[136:137], v[88:89] op_sel_hi:[0,1]
	v_pk_mul_f32 v[90:91], v[136:137], v[90:91] op_sel_hi:[0,1]
	v_pk_mul_f32 v[88:89], v[124:125], v[88:89]
	v_pk_mul_f32 v[90:91], v[90:91], v[126:127]
	v_cvt_pk_bf16_f32 v88, v88, v89
	v_cvt_pk_bf16_f32 v89, v90, v91
	global_store_dwordx2 v[44:45], v[88:89], off offset:32
	v_pk_mul_f32 v[84:85], v[136:137], v[84:85] op_sel_hi:[0,1]
	v_pk_mul_f32 v[86:87], v[136:137], v[86:87] op_sel_hi:[0,1]
	v_pk_mul_f32 v[84:85], v[128:129], v[84:85]
	v_pk_mul_f32 v[86:87], v[86:87], v[130:131]
	v_cvt_pk_bf16_f32 v84, v84, v85
	v_cvt_pk_bf16_f32 v85, v86, v87
	global_store_dwordx2 v[44:45], v[84:85], off offset:64
	v_pk_mul_f32 v[80:81], v[136:137], v[80:81] op_sel_hi:[0,1]
	v_pk_mul_f32 v[82:83], v[136:137], v[82:83] op_sel_hi:[0,1]
	v_pk_mul_f32 v[80:81], v[132:133], v[80:81]
	v_pk_mul_f32 v[82:83], v[82:83], v[134:135]
	v_cvt_pk_bf16_f32 v80, v80, v81
	v_cvt_pk_bf16_f32 v81, v82, v83
	global_store_dwordx2 v[44:45], v[80:81], off offset:96
	v_pk_mul_f32 v[60:61], v[138:139], v[60:61] op_sel_hi:[0,1]
	v_pk_mul_f32 v[62:63], v[138:139], v[62:63] op_sel_hi:[0,1]
	v_pk_mul_f32 v[60:61], v[120:121], v[60:61]
	v_pk_mul_f32 v[62:63], v[62:63], v[122:123]
	v_cvt_pk_bf16_f32 v60, v60, v61
	v_cvt_pk_bf16_f32 v61, v62, v63
	global_store_dwordx2 v[46:47], v[60:61], off
	v_pk_mul_f32 v[40:41], v[138:139], v[40:41] op_sel_hi:[0,1]
	v_pk_mul_f32 v[42:43], v[138:139], v[42:43] op_sel_hi:[0,1]
	v_pk_mul_f32 v[40:41], v[124:125], v[40:41]
	v_pk_mul_f32 v[42:43], v[42:43], v[126:127]
	v_cvt_pk_bf16_f32 v40, v40, v41
	v_cvt_pk_bf16_f32 v41, v42, v43
	global_store_dwordx2 v[46:47], v[40:41], off offset:32
	v_pk_mul_f32 v[36:37], v[138:139], v[36:37] op_sel_hi:[0,1]
	v_pk_mul_f32 v[38:39], v[138:139], v[38:39] op_sel_hi:[0,1]
	v_pk_mul_f32 v[36:37], v[128:129], v[36:37]
	v_pk_mul_f32 v[38:39], v[38:39], v[130:131]
	v_cvt_pk_bf16_f32 v36, v36, v37
	v_cvt_pk_bf16_f32 v37, v38, v39
	global_store_dwordx2 v[46:47], v[36:37], off offset:64
	v_pk_mul_f32 v[28:29], v[138:139], v[28:29] op_sel_hi:[0,1]
	v_pk_mul_f32 v[30:31], v[138:139], v[30:31] op_sel_hi:[0,1]
	v_pk_mul_f32 v[28:29], v[132:133], v[28:29]
	v_pk_mul_f32 v[30:31], v[30:31], v[134:135]
	v_cvt_pk_bf16_f32 v28, v28, v29
	v_cvt_pk_bf16_f32 v29, v30, v31
	global_store_dwordx2 v[46:47], v[28:29], off offset:96
	v_pk_mul_f32 v[32:33], v[140:141], v[32:33] op_sel_hi:[0,1]
	v_pk_mul_f32 v[34:35], v[140:141], v[34:35] op_sel_hi:[0,1]
	v_pk_mul_f32 v[32:33], v[120:121], v[32:33]
	v_pk_mul_f32 v[34:35], v[34:35], v[122:123]
	v_cvt_pk_bf16_f32 v32, v32, v33
	v_cvt_pk_bf16_f32 v33, v34, v35
	global_store_dwordx2 v[48:49], v[32:33], off
	v_pk_mul_f32 v[24:25], v[140:141], v[24:25] op_sel_hi:[0,1]
	v_pk_mul_f32 v[26:27], v[140:141], v[26:27] op_sel_hi:[0,1]
	v_pk_mul_f32 v[24:25], v[124:125], v[24:25]
	v_pk_mul_f32 v[26:27], v[26:27], v[126:127]
	v_cvt_pk_bf16_f32 v24, v24, v25
	v_cvt_pk_bf16_f32 v25, v26, v27
	global_store_dwordx2 v[48:49], v[24:25], off offset:32
	v_pk_mul_f32 v[20:21], v[140:141], v[20:21] op_sel_hi:[0,1]
	v_pk_mul_f32 v[22:23], v[140:141], v[22:23] op_sel_hi:[0,1]
	v_pk_mul_f32 v[20:21], v[128:129], v[20:21]
	v_pk_mul_f32 v[22:23], v[22:23], v[130:131]
	v_cvt_pk_bf16_f32 v20, v20, v21
	v_cvt_pk_bf16_f32 v21, v22, v23
	global_store_dwordx2 v[48:49], v[20:21], off offset:64
	v_pk_mul_f32 v[16:17], v[140:141], v[16:17] op_sel_hi:[0,1]
	v_pk_mul_f32 v[18:19], v[140:141], v[18:19] op_sel_hi:[0,1]
	v_pk_mul_f32 v[16:17], v[132:133], v[16:17]
	v_pk_mul_f32 v[18:19], v[18:19], v[134:135]
	v_cvt_pk_bf16_f32 v16, v16, v17
	v_cvt_pk_bf16_f32 v17, v18, v19
	global_store_dwordx2 v[48:49], v[16:17], off offset:96
	v_pk_mul_f32 v[12:13], v[142:143], v[12:13] op_sel_hi:[0,1]
	v_pk_mul_f32 v[14:15], v[142:143], v[14:15] op_sel_hi:[0,1]
	v_pk_mul_f32 v[12:13], v[120:121], v[12:13]
	v_pk_mul_f32 v[14:15], v[14:15], v[122:123]
	v_cvt_pk_bf16_f32 v12, v12, v13
	v_cvt_pk_bf16_f32 v13, v14, v15
	global_store_dwordx2 v[50:51], v[12:13], off
	v_pk_mul_f32 v[8:9], v[142:143], v[8:9] op_sel_hi:[0,1]
	v_pk_mul_f32 v[10:11], v[142:143], v[10:11] op_sel_hi:[0,1]
	v_pk_mul_f32 v[8:9], v[124:125], v[8:9]
	v_pk_mul_f32 v[10:11], v[10:11], v[126:127]
	v_cvt_pk_bf16_f32 v8, v8, v9
	v_cvt_pk_bf16_f32 v9, v10, v11
	global_store_dwordx2 v[50:51], v[8:9], off offset:32
	v_pk_mul_f32 v[4:5], v[142:143], v[4:5] op_sel_hi:[0,1]
	v_pk_mul_f32 v[6:7], v[142:143], v[6:7] op_sel_hi:[0,1]
	v_pk_mul_f32 v[4:5], v[128:129], v[4:5]
	v_pk_mul_f32 v[6:7], v[6:7], v[130:131]
	v_cvt_pk_bf16_f32 v4, v4, v5
	v_cvt_pk_bf16_f32 v5, v6, v7
	global_store_dwordx2 v[50:51], v[4:5], off offset:64
	v_pk_mul_f32 v[0:1], v[142:143], v[0:1] op_sel_hi:[0,1]
	v_pk_mul_f32 v[2:3], v[142:143], v[2:3] op_sel_hi:[0,1]
	v_pk_mul_f32 v[0:1], v[132:133], v[0:1]
	v_pk_mul_f32 v[2:3], v[2:3], v[134:135]
	v_cvt_pk_bf16_f32 v0, v0, v1
	v_cvt_pk_bf16_f32 v1, v2, v3
	global_store_dwordx2 v[50:51], v[0:1], off offset:96
	s_add_i32 s8, s8, s3
	s_cmpk_lt_u32 s8, 0x200
	s_cbranch_scc1 .LBB0_889
